# diff attention tile loop rewritten on v_mfma_f32_16x16x32_bf16 (both even layers), same bf16 operands and f32 accumulation
# speedup vs baseline: 1.0125x; 1.0019x over previous
.LBB0_783:
	v_readlane_b32 s3, v251, 25
	s_ashr_i32 s0, s3, 7
	s_ashr_i32 s1, s0, 31
	s_lshl_b64 s[8:9], s[0:1], 14
	v_writelane_b32 v251, s8, 32
	s_lshl_b32 s1, s3, 8
	s_and_b32 s1, s1, 0x1f00
	v_writelane_b32 v251, s9, 33
	s_bfe_u32 s2, s3, 0x20005
	v_writelane_b32 v251, s1, 34
	s_xor_b32 s1, s1, 0x3f00
	v_writelane_b32 v251, s1, 36
	s_lshl_b32 s1, s2, 8
	s_mul_i32 s4, s0, 0xc000000
	s_mul_hi_i32 s3, s0, 0xc000000
	s_add_u32 s0, s48, s4
	v_writelane_b32 v251, s1, 38
	s_addc_u32 s1, s49, s3
	s_add_u32 s40, s0, 0x2000
	s_addc_u32 s41, s1, 0
	s_lshl_b32 s8, s2, 9
	s_mov_b32 s9, s5
	v_writelane_b32 v251, s8, 40
	s_add_u32 s0, s0, s8
	s_addc_u32 s1, s1, 0
	v_writelane_b32 v251, s9, 41
	s_add_u32 s8, s0, 0x2800
	v_readlane_b32 s0, v251, 8
	s_addc_u32 s9, s1, 0
	v_mbcnt_lo_u32_b32 v0, -1, 0
	v_mbcnt_hi_u32_b32 v0, -1, v0
	s_lshl_b32 s2, s2, 10
	v_add_u32_e32 v208, s0, v0
	s_mov_b64 s[0:1], s[68:69]
	s_load_dwordx2 s[0:1], s[0:1], 0x88
	v_and_b32_e32 v2, 63, v0
	v_lshlrev_b32_e32 v5, 4, v0
	s_waitcnt lgkmcnt(0)
	v_lshlrev_b32_e32 v4, 3, v2
	v_and_b32_e32 v6, 0xc0, v5
	s_add_u32 s0, s0, s2
	v_lshlrev_b32_e32 v7, 1, v0
	s_addc_u32 s1, s1, 0
	v_and_or_b32 v6, v4, 24, v6
	v_and_b32_e32 v7, 32, v7
	v_and_b32_e32 v4, 0x100, v4
	v_bfe_u32 v212, v0, 4, 2
	s_add_u32 s42, s0, 0x37e00000
	v_bfe_u32 v1, v0, 5, 1
	v_or3_b32 v4, v6, v7, v4
	v_bitop3_b32 v7, v212, v0, 15 bitop3:0x78
	s_addc_u32 s43, s1, 0
	v_lshlrev_b32_e32 v210, 2, v1
	v_lshlrev_b32_e32 v213, 4, v7
	v_lshlrev_b32_e32 v7, 4, v1
	v_lshrrev_b32_e32 v1, 1, v0
	v_and_b32_e32 v209, 31, v0
	v_and_b32_e32 v215, 8, v1
	v_lshlrev_b32_e32 v1, 3, v0
	s_cmp_lg_u32 0, -1
	v_mul_u32_u24_e32 v3, 0x3000, v209
	v_and_b32_e32 v1, 24, v1
	s_cselect_b32 s2, 0, 0
	s_movk_i32 s0, 0x70
	v_and_b32_e32 v6, 15, v0
	v_or_b32_e32 v194, v7, v3
	v_bfe_u32 v214, v0, 2, 3
	v_and_or_b32 v216, v0, 32, v1
	v_add_u32_e32 v217, s2, v4
	v_lshlrev_b32_e32 v0, 8, v209
	v_and_b32_e32 v3, 0x70, v5
	s_add_i32 s1, s2, 0x10000
	v_bitop3_b32 v5, v7, v5, s0 bitop3:0x78
	s_movk_i32 s0, 0x60
	s_add_i32 s2, s2, 0x14000
	v_add_u32_e32 v4, s1, v0
	v_bitop3_b32 v8, v7, v3, 32 bitop3:0x36
	v_bitop3_b32 v9, v7, v3, 64 bitop3:0x36
	v_bitop3_b32 v3, v7, v3, s0 bitop3:0x36
	v_add_u32_e32 v0, s2, v0
	v_add_u32_e32 v222, v5, v0
	v_add_u32_e32 v223, v8, v0
	v_add_u32_e32 v224, v9, v0
	v_add_u32_e32 v225, v3, v0
	v_mul_u32_u24_e32 v0, 0x3000, v212
	s_movk_i32 s44, 0x3000
	v_mov_b32_e32 v1, 0
	v_cmp_gt_u32_e64 s[0:1], 32, v2
	s_add_u32 s6, s6, s4
	v_mov_b32_e32 v2, 0xc000
	v_or_b32_e32 v227, v0, v213
	v_bitop3_b32 v0, v212, v6, 4 bitop3:0x36
	v_sub_u32_e32 v211, v209, v210
	v_mov_b32_e32 v195, v1
	v_add_u32_e32 v218, v5, v4
	v_add_u32_e32 v219, v8, v4
	v_add_u32_e32 v220, v9, v4
	v_add_u32_e32 v221, v3, v4
	v_writelane_b32 v251, s4, 42
	s_addc_u32 s7, s7, s3
	v_mad_u32_u24 v226, v212, s44, v2
	v_lshlrev_b32_e32 v228, 4, v0
	v_mov_b32_e32 v229, 0x7ffffff3
	s_movk_i32 s45, 0x1800
	s_mov_b64 s[10:11], 0x1fec2000
	s_mov_b64 s[12:13], 0x1fec2800
	s_mov_b64 s[14:15], 0x1fec2880
	s_mov_b64 s[16:17], 0x1fec2900
	s_mov_b64 s[18:19], 0x1fec2980
	s_brev_b32 s46, -3
	s_mov_b32 s47, 0x41000000
	s_mov_b64 s[20:21], 0x1ff82000
	s_mov_b64 s[22:23], 0x1ff82800
	s_mov_b64 s[24:25], 0x1ff82880
	s_mov_b64 s[26:27], 0x1ff82900
	s_mov_b64 s[28:29], 0x1ff82980
	s_mov_b32 s50, 0x7fffe000
	v_mov_b32_e32 v230, 0xff800000
	s_mov_b32 s51, 0
	s_waitcnt vmcnt(63) expcnt(7) lgkmcnt(15)
	v_mbcnt_lo_u32_b32 v238, -1, 0
	v_mbcnt_hi_u32_b32 v238, -1, v238
	v_and_b32_e32 v239, 15, v238
	v_lshrrev_b32_e32 v240, 4, v238
	v_and_b32_e32 v241, 3, v238
	v_bfe_u32 v242, v238, 2, 2
	v_lshrrev_b32_e32 v243, 1, v240
	v_lshlrev_b32_e32 v217, 12, v243
	v_and_b32_e32 v243, 1, v240
	v_lshl_or_b32 v217, v243, 7, v217
	v_lshl_or_b32 v217, v242, 5, v217
	v_lshl_or_b32 v217, v241, 3, v217
	v_xor_b32_e32 v243, v240, v241
	v_lshlrev_b32_e32 v218, 8, v239
	v_lshl_or_b32 v218, v243, 4, v218
	v_bfe_u32 v243, v238, 2, 1
	v_lshl_or_b32 v218, v243, 6, v218
	v_or_b32_e32 v218, 0x10000, v218
	v_xor_b32_e32 v219, 64, v218
	v_bfe_u32 v243, v238, 1, 3
	v_mul_u32_u24_e32 v220, 0x3000, v243
	v_lshl_or_b32 v220, v240, 5, v220
	v_and_b32_e32 v243, 1, v238
	v_lshl_or_b32 v220, v243, 4, v220
	v_lshlrev_b32_e32 v243, 2, v240
	v_sub_u32_e32 v221, v239, v243
	v_mul_u32_u24_e32 v194, 0x3000, v239
	v_lshl_or_b32 v194, v240, 4, v194
	v_add_u32_e32 v194, 0x1800, v194
	v_mov_b32_e32 v195, 0
	v_xor_b32_e32 v224, 16, v238
	v_lshlrev_b32_e32 v224, 2, v224
	v_cmp_gt_u32_e64 s[0:1], 16, v238
	s_barrier
	v_writelane_b32 v251, s3, 43
	s_branch .LBB0_785

.LBB0_785:
	s_lshr_b32 s52, s51, 1
	s_lshl_b32 s2, s52, 7
	v_readlane_b32 s3, v251, 38
	s_add_i32 s4, s3, s2
	s_lshl_b64 s[34:35], s[4:5], 1
	s_bitcmp0_b32 s51, 0
	v_readlane_b32 s2, v251, 34
	v_readlane_b32 s3, v251, 36
	s_cselect_b32 s3, s3, s2
	v_readlane_b32 s60, v251, 32
	v_readlane_b32 s61, v251, 33
	s_or_b32 s2, s60, s3
	s_mul_i32 s30, s61, 0x3000
	s_mul_hi_u32 s4, s2, 0x3000
	v_writelane_b32 v251, s30, 44
	s_add_i32 s4, s4, s30
	s_mul_i32 s30, s2, 0x3000
	s_add_u32 s30, s48, s30
	s_addc_u32 s4, s49, s4
	s_add_u32 s38, s30, s34
	s_addc_u32 s39, s4, s35
	s_add_u32 s36, s40, s34
	v_readfirstlane_b32 s4, v208
	s_addc_u32 s37, s41, s35
	s_ashr_i32 s56, s4, 6
	s_and_b32 s4, s4, 0x3fffffc0
	s_lshl_b32 s4, s4, 2
	s_lshl_b32 s31, s56, 3
	s_lshl_b32 s30, s56, 5
	s_add_i32 s4, s4, 0
	v_or_b32_e32 v0, s31, v212
	v_bitop3_b32 v7, s31, v229, v214 bitop3:0xc8
	s_lshl_b32 s31, s56, 2
	s_add_i32 s57, s4, 0x18000
	s_add_i32 s4, s30, s3
	s_and_b32 s58, s31, 4
	s_lshl_b32 s53, s56, 11
	s_lshl_b32 s54, s56, 12
	s_ashr_i32 s31, s30, 31
	s_mul_i32 s55, s56, 0x60000
	s_mul_hi_i32 s59, s30, 0x3000
	s_add_u32 s38, s38, s55
	v_or3_b32 v2, v215, v7, s58
	s_addc_u32 s39, s39, s59
	s_lshr_b32 s3, s3, 6
	v_mul_lo_u32 v2, v2, s45
	s_or_b32 s55, s3, 3
	v_or_b32_e32 v8, v2, v216
	v_lshl_add_u64 v[2:3], s[38:39], 0, v[194:195]
	s_mov_b64 s[38:39], 0x30000
	s_cmp_lg_u32 0, -1
	v_lshl_add_u64 v[4:5], v[2:3], 0, s[38:39]
	s_movk_i32 s38, 0x1000
	s_cselect_b32 s3, 0, 0
	v_mul_lo_u32 v0, v0, s44
	s_add_i32 s38, s3, s53
	v_or_b32_e32 v6, v0, v213
	v_or_b32_e32 v0, v0, v228
	global_load_dwordx4 v[162:165], v[2:3], off
	global_load_dwordx4 v[166:169], v[2:3], off offset:64
	global_load_dwordx4 v[170:173], v[2:3], off offset:128
	global_load_dwordx4 v[174:177], v[2:3], off offset:192
	global_load_dwordx4 v[178:181], v[4:5], off
	global_load_dwordx4 v[182:185], v[4:5], off offset:64
	global_load_dwordx4 v[186:189], v[4:5], off offset:128
	global_load_dwordx4 v[190:193], v[4:5], off offset:192
	s_add_i32 m0, s38, 0x10000
	v_add_u32_e32 v0, 0xc000, v0
	global_load_lds_dwordx4 v6, s[36:37]
	s_add_i32 m0, s38, 0x10400
	s_add_i32 s3, s54, s3
	global_load_lds_dwordx4 v0, s[36:37]
	s_mul_i32 s73, s56, 0x18000
	v_add_u32_e32 v0, s73, v220
	v_lshl_add_u64 v[2:3], s[8:9], 0, v[0:1]
	s_mov_b32 m0, s3
	s_mov_b64 s[36:37], 0x80
	global_load_lds_dwordx4 v0, s[8:9]
	v_lshl_add_u64 v[4:5], v[2:3], 0, s[36:37]
	s_add_i32 m0, s3, 0x400
	s_mov_b64 s[36:37], 0x100
	global_load_lds_dwordx4 v[4:5], off
	v_lshl_add_u64 v[4:5], v[2:3], 0, s[36:37]
	s_add_i32 m0, s3, 0x800
	s_mov_b64 s[36:37], 0x180
	global_load_lds_dwordx4 v[4:5], off
	v_lshl_add_u64 v[2:3], v[2:3], 0, s[36:37]
	s_add_i32 m0, s3, 0xc00
	v_add3_u32 v0, v215, v7, s58
	global_load_lds_dwordx4 v[2:3], off
	v_mul_lo_u32 v0, v0, s45
	v_or_b32_e32 v0, v216, v0
	v_readlane_b32 s36, v251, 40
	v_lshlrev_b32_e32 v0, 1, v0
	v_readlane_b32 s37, v251, 41
	s_mul_i32 s56, s56, 0x18000
	v_mov_b32_e32 v14, v1
	v_add_u32_e32 v0, s56, v220
	v_lshl_add_u64 v[196:197], s[36:37], 0, v[0:1]
	v_add3_u32 v0, v226, s56, v228
	v_lshl_add_u64 v[198:199], s[34:35], 0, v[0:1]
	v_add_u32_e32 v0, s56, v227
	v_mov_b32_e32 v15, v1
	s_waitcnt vmcnt(0)
	v_lshl_add_u64 v[200:201], s[34:35], 0, v[0:1]
	v_mov_b32_e32 v0, v1
	v_mov_b32_e32 v2, v1
	v_mov_b32_e32 v3, v1
	v_mov_b32_e32 v4, v1
	v_mov_b32_e32 v5, v1
	v_mov_b32_e32 v6, v1
	v_mov_b32_e32 v7, v1
	v_mov_b32_e32 v8, v1
	v_mov_b32_e32 v9, v1
	v_mov_b32_e32 v10, v1
	v_mov_b32_e32 v11, v1
	v_mov_b32_e32 v12, v1
	v_mov_b32_e32 v13, v1
	s_waitcnt vmcnt(0)
	v_mov_b64_e32 v[128:129], v[14:15]
	v_mov_b64_e32 v[112:113], v[14:15]
	v_mov_b64_e32 v[96:97], v[14:15]
	v_mov_b64_e32 v[80:81], v[14:15]
	v_mov_b64_e32 v[64:65], v[14:15]
	v_mov_b64_e32 v[48:49], v[14:15]
	v_mov_b64_e32 v[32:33], v[14:15]
	v_mov_b64_e32 v[126:127], v[12:13]
	v_mov_b64_e32 v[124:125], v[10:11]
	v_mov_b64_e32 v[122:123], v[8:9]
	v_mov_b64_e32 v[120:121], v[6:7]
	v_mov_b64_e32 v[118:119], v[4:5]
	v_mov_b64_e32 v[116:117], v[2:3]
	v_mov_b64_e32 v[114:115], v[0:1]
	v_mov_b64_e32 v[110:111], v[12:13]
	v_mov_b64_e32 v[108:109], v[10:11]
	v_mov_b64_e32 v[106:107], v[8:9]
	v_mov_b64_e32 v[104:105], v[6:7]
	v_mov_b64_e32 v[102:103], v[4:5]
	v_mov_b64_e32 v[100:101], v[2:3]
	v_mov_b64_e32 v[98:99], v[0:1]
	v_mov_b64_e32 v[94:95], v[12:13]
	v_mov_b64_e32 v[92:93], v[10:11]
	v_mov_b64_e32 v[90:91], v[8:9]
	v_mov_b64_e32 v[88:89], v[6:7]
	v_mov_b64_e32 v[86:87], v[4:5]
	v_mov_b64_e32 v[84:85], v[2:3]
	v_mov_b64_e32 v[82:83], v[0:1]
	v_mov_b64_e32 v[78:79], v[12:13]
	v_mov_b64_e32 v[76:77], v[10:11]
	v_mov_b64_e32 v[74:75], v[8:9]
	v_mov_b64_e32 v[72:73], v[6:7]
	v_mov_b64_e32 v[70:71], v[4:5]
	v_mov_b64_e32 v[68:69], v[2:3]
	v_mov_b64_e32 v[66:67], v[0:1]
	v_mov_b64_e32 v[62:63], v[12:13]
	v_mov_b64_e32 v[60:61], v[10:11]
	v_mov_b64_e32 v[58:59], v[8:9]
	v_mov_b64_e32 v[56:57], v[6:7]
	v_mov_b64_e32 v[54:55], v[4:5]
	v_mov_b64_e32 v[52:53], v[2:3]
	v_mov_b64_e32 v[50:51], v[0:1]
	v_mov_b64_e32 v[46:47], v[12:13]
	v_mov_b64_e32 v[44:45], v[10:11]
	v_mov_b64_e32 v[42:43], v[8:9]
	v_mov_b64_e32 v[40:41], v[6:7]
	v_mov_b64_e32 v[38:39], v[4:5]
	v_mov_b64_e32 v[36:37], v[2:3]
	v_mov_b64_e32 v[34:35], v[0:1]
	v_mov_b64_e32 v[30:31], v[12:13]
	v_mov_b64_e32 v[28:29], v[10:11]
	v_mov_b64_e32 v[26:27], v[8:9]
	v_mov_b64_e32 v[24:25], v[6:7]
	v_mov_b64_e32 v[22:23], v[4:5]
	v_mov_b64_e32 v[20:21], v[2:3]
	v_mov_b64_e32 v[18:19], v[0:1]
	v_mov_b64_e32 v[16:17], v[14:15]
	s_mov_b32 s3, s61
	v_add_u32_e32 v233, s4, v221
	v_and_b32_e32 v232, 15, v209
	v_lshl_add_u32 v232, v232, 2, s57
	v_lshl_add_u32 v231, v212, 4, s57
	v_mov_b32_e32 v237, 0xf149f2ca
	s_movk_i32 s56, 0x7f
	s_mov_b64 s[34:35], s[6:7]
	s_mov_b32 s57, 2
	v_mov_b64_e32 v[14:15], v[12:13]
	v_mov_b64_e32 v[12:13], v[10:11]
	v_mov_b64_e32 v[10:11], v[8:9]
	v_mov_b64_e32 v[8:9], v[6:7]
	v_mov_b64_e32 v[6:7], v[4:5]
	v_mov_b64_e32 v[4:5], v[2:3]
	v_mov_b64_e32 v[2:3], v[0:1]
	v_mov_b32_e32 v0, 0
	v_mov_b32_e32 v222, 0xf149f2ca
	v_mov_b32_e32 v223, 0
	s_waitcnt lgkmcnt(0)
	s_barrier
	s_branch .LBB0_788
.Ld16a_bot:
	s_waitcnt vmcnt(0)
	s_add_i32 s57, s57, 2
	s_add_u32 s34, s34, 0x180000
	s_addc_u32 s35, s35, 0
	v_add_u32_e32 v233, 0xffffff80, v233
	s_addk_i32 s56, 0x80
	s_and_b64 vcc, exec, s[36:37]
	s_waitcnt vmcnt(0) lgkmcnt(0)
	s_barrier
	s_cbranch_vccnz .LBB0_803

.LBB0_790:
	ds_read_b128 v[238:241], v218 offset:0
	ds_read_b128 v[242:245], v219 offset:0
	ds_read_b128 v[246:249], v218 offset:128
	s_waitcnt lgkmcnt(2)
	v_mfma_f32_16x16x32_bf16 v[130:133], v[238:241], v[162:165], 0
	v_mfma_f32_16x16x32_bf16 v[146:149], v[238:241], v[178:181], 0
	ds_read_b128 v[238:241], v219 offset:128
	s_waitcnt lgkmcnt(2)
	v_mfma_f32_16x16x32_bf16 v[130:133], v[242:245], v[166:169], v[130:133]
	v_mfma_f32_16x16x32_bf16 v[146:149], v[242:245], v[182:185], v[146:149]
	ds_read_b128 v[242:245], v218 offset:4096
	s_waitcnt lgkmcnt(2)
	v_mfma_f32_16x16x32_bf16 v[130:133], v[246:249], v[170:173], v[130:133]
	v_mfma_f32_16x16x32_bf16 v[146:149], v[246:249], v[186:189], v[146:149]
	ds_read_b128 v[246:249], v219 offset:4096
	s_waitcnt lgkmcnt(2)
	v_mfma_f32_16x16x32_bf16 v[130:133], v[238:241], v[174:177], v[130:133]
	v_mfma_f32_16x16x32_bf16 v[146:149], v[238:241], v[190:193], v[146:149]
	ds_read_b128 v[238:241], v218 offset:4224
	s_waitcnt lgkmcnt(2)
	v_mfma_f32_16x16x32_bf16 v[134:137], v[242:245], v[162:165], 0
	v_mfma_f32_16x16x32_bf16 v[150:153], v[242:245], v[178:181], 0
	ds_read_b128 v[242:245], v219 offset:4224
	s_waitcnt lgkmcnt(2)
	v_mfma_f32_16x16x32_bf16 v[134:137], v[246:249], v[166:169], v[134:137]
	v_mfma_f32_16x16x32_bf16 v[150:153], v[246:249], v[182:185], v[150:153]
	ds_read_b128 v[246:249], v218 offset:8192
	s_waitcnt lgkmcnt(2)
	v_mfma_f32_16x16x32_bf16 v[134:137], v[238:241], v[170:173], v[134:137]
	v_mfma_f32_16x16x32_bf16 v[150:153], v[238:241], v[186:189], v[150:153]
	ds_read_b128 v[238:241], v219 offset:8192
	s_waitcnt lgkmcnt(2)
	v_mfma_f32_16x16x32_bf16 v[134:137], v[242:245], v[174:177], v[134:137]
	v_mfma_f32_16x16x32_bf16 v[150:153], v[242:245], v[190:193], v[150:153]
	ds_read_b128 v[242:245], v218 offset:8320
	s_waitcnt lgkmcnt(2)
	v_mfma_f32_16x16x32_bf16 v[138:141], v[246:249], v[162:165], 0
	v_mfma_f32_16x16x32_bf16 v[154:157], v[246:249], v[178:181], 0
	ds_read_b128 v[246:249], v219 offset:8320
	s_waitcnt lgkmcnt(2)
	v_mfma_f32_16x16x32_bf16 v[138:141], v[238:241], v[166:169], v[138:141]
	v_mfma_f32_16x16x32_bf16 v[154:157], v[238:241], v[182:185], v[154:157]
	ds_read_b128 v[238:241], v218 offset:12288
	s_waitcnt lgkmcnt(2)
	v_mfma_f32_16x16x32_bf16 v[138:141], v[242:245], v[170:173], v[138:141]
	v_mfma_f32_16x16x32_bf16 v[154:157], v[242:245], v[186:189], v[154:157]
	ds_read_b128 v[242:245], v219 offset:12288
	s_waitcnt lgkmcnt(2)
	v_mfma_f32_16x16x32_bf16 v[138:141], v[246:249], v[174:177], v[138:141]
	v_mfma_f32_16x16x32_bf16 v[154:157], v[246:249], v[190:193], v[154:157]
	ds_read_b128 v[246:249], v218 offset:12416
	s_waitcnt lgkmcnt(2)
	v_mfma_f32_16x16x32_bf16 v[142:145], v[238:241], v[162:165], 0
	v_mfma_f32_16x16x32_bf16 v[158:161], v[238:241], v[178:181], 0
	ds_read_b128 v[238:241], v219 offset:12416
	s_waitcnt lgkmcnt(2)
	v_mfma_f32_16x16x32_bf16 v[142:145], v[242:245], v[166:169], v[142:145]
	v_mfma_f32_16x16x32_bf16 v[158:161], v[242:245], v[182:185], v[158:161]
	s_waitcnt lgkmcnt(1)
	v_mfma_f32_16x16x32_bf16 v[142:145], v[246:249], v[170:173], v[142:145]
	v_mfma_f32_16x16x32_bf16 v[158:161], v[246:249], v[186:189], v[158:161]
	s_waitcnt lgkmcnt(0)
	v_mfma_f32_16x16x32_bf16 v[142:145], v[238:241], v[174:177], v[142:145]
	v_mfma_f32_16x16x32_bf16 v[158:161], v[238:241], v[190:193], v[158:161]
	s_nop 7
	s_nop 1
	s_sub_i32 s36, s56, 64
	s_cmp_le_i32 s36, s4
	s_cbranch_scc1 .Ld16a_nm0
	v_cmp_gt_i32_e64 s[74:75], 0, v233
	v_cmp_gt_i32_e64 s[76:77], 1, v233
	v_cmp_gt_i32_e64 s[78:79], 2, v233
	v_cmp_gt_i32_e64 s[80:81], 3, v233
	v_cndmask_b32_e64 v130, v130, v230, s[74:75]
	v_cndmask_b32_e64 v131, v131, v230, s[76:77]
	v_cndmask_b32_e64 v132, v132, v230, s[78:79]
	v_cndmask_b32_e64 v133, v133, v230, s[80:81]
	v_cmp_gt_i32_e64 s[74:75], 16, v233
	v_cmp_gt_i32_e64 s[76:77], 17, v233
	v_cmp_gt_i32_e64 s[78:79], 18, v233
	v_cmp_gt_i32_e64 s[80:81], 19, v233
	v_cndmask_b32_e64 v134, v134, v230, s[74:75]
	v_cndmask_b32_e64 v135, v135, v230, s[76:77]
	v_cndmask_b32_e64 v136, v136, v230, s[78:79]
	v_cndmask_b32_e64 v137, v137, v230, s[80:81]
	v_cmp_gt_i32_e64 s[74:75], 32, v233
	v_cmp_gt_i32_e64 s[76:77], 33, v233
	v_cmp_gt_i32_e64 s[78:79], 34, v233
	v_cmp_gt_i32_e64 s[80:81], 35, v233
	v_cndmask_b32_e64 v138, v138, v230, s[74:75]
	v_cndmask_b32_e64 v139, v139, v230, s[76:77]
	v_cndmask_b32_e64 v140, v140, v230, s[78:79]
	v_cndmask_b32_e64 v141, v141, v230, s[80:81]
	v_cmp_gt_i32_e64 s[74:75], 48, v233
	v_cmp_gt_i32_e64 s[76:77], 49, v233
	v_cmp_gt_i32_e64 s[78:79], 50, v233
	v_cmp_gt_i32_e64 s[80:81], 51, v233
	v_cndmask_b32_e64 v142, v142, v230, s[74:75]
	v_cndmask_b32_e64 v143, v143, v230, s[76:77]
	v_cndmask_b32_e64 v144, v144, v230, s[78:79]
	v_cndmask_b32_e64 v145, v145, v230, s[80:81]
	v_cmp_gt_i32_e64 s[74:75], -16, v233
	v_cmp_gt_i32_e64 s[76:77], -15, v233
	v_cmp_gt_i32_e64 s[78:79], -14, v233
	v_cmp_gt_i32_e64 s[80:81], -13, v233
	v_cndmask_b32_e64 v146, v146, v230, s[74:75]
	v_cndmask_b32_e64 v147, v147, v230, s[76:77]
	v_cndmask_b32_e64 v148, v148, v230, s[78:79]
	v_cndmask_b32_e64 v149, v149, v230, s[80:81]
	v_cmp_gt_i32_e64 s[74:75], 0, v233
	v_cmp_gt_i32_e64 s[76:77], 1, v233
	v_cmp_gt_i32_e64 s[78:79], 2, v233
	v_cmp_gt_i32_e64 s[80:81], 3, v233
	v_cndmask_b32_e64 v150, v150, v230, s[74:75]
	v_cndmask_b32_e64 v151, v151, v230, s[76:77]
	v_cndmask_b32_e64 v152, v152, v230, s[78:79]
	v_cndmask_b32_e64 v153, v153, v230, s[80:81]
	v_cmp_gt_i32_e64 s[74:75], 16, v233
	v_cmp_gt_i32_e64 s[76:77], 17, v233
	v_cmp_gt_i32_e64 s[78:79], 18, v233
	v_cmp_gt_i32_e64 s[80:81], 19, v233
	v_cndmask_b32_e64 v154, v154, v230, s[74:75]
	v_cndmask_b32_e64 v155, v155, v230, s[76:77]
	v_cndmask_b32_e64 v156, v156, v230, s[78:79]
	v_cndmask_b32_e64 v157, v157, v230, s[80:81]
	v_cmp_gt_i32_e64 s[74:75], 32, v233
	v_cmp_gt_i32_e64 s[76:77], 33, v233
	v_cmp_gt_i32_e64 s[78:79], 34, v233
	v_cmp_gt_i32_e64 s[80:81], 35, v233
	v_cndmask_b32_e64 v158, v158, v230, s[74:75]
	v_cndmask_b32_e64 v159, v159, v230, s[76:77]
	v_cndmask_b32_e64 v160, v160, v230, s[78:79]
	v_cndmask_b32_e64 v161, v161, v230, s[80:81]
.Ld16a_nm0:
	v_max3_f32 v234, v130, v131, v132
	v_max3_f32 v234, v234, v133, v134
	v_max3_f32 v234, v234, v135, v136
	v_max3_f32 v234, v234, v137, v138
	v_max3_f32 v234, v234, v139, v140
	v_max3_f32 v234, v234, v141, v142
	v_max3_f32 v234, v234, v143, v144
	v_max_f32_e32 v234, v234, v145
	v_max3_f32 v235, v146, v147, v148
	v_max3_f32 v235, v235, v149, v150
	v_max3_f32 v235, v235, v151, v152
	v_max3_f32 v235, v235, v153, v154
	v_max3_f32 v235, v235, v155, v156
	v_max3_f32 v235, v235, v157, v158
	v_max3_f32 v235, v235, v159, v160
	v_max_f32_e32 v235, v235, v161
	ds_bpermute_b32 v246, v224, v234
	ds_bpermute_b32 v247, v224, v235
	s_waitcnt lgkmcnt(0)
	v_max_f32_e32 v234, v234, v246
	v_max_f32_e32 v235, v235, v247
	v_mov_b32_e32 v246, v234
	v_mov_b32_e32 v247, v235
	s_nop 1
	v_permlane32_swap_b32_e32 v234, v246
	v_permlane32_swap_b32_e32 v235, v247
	v_max_f32_e32 v234, v234, v246
	v_max_f32_e32 v235, v235, v247
	v_sub_f32_e32 v246, v234, v237
	v_sub_f32_e32 v247, v235, v222
	v_max_f32_e32 v246, v246, v247
	v_mul_f32_e32 v246, 0x3db504f3, v246
	v_cmp_ge_f32_e32 vcc, s47, v246
	v_max_f32_e32 v234, v237, v234
	v_max_f32_e32 v235, v222, v235
	v_sub_f32_e32 v246, v237, v234
	v_sub_f32_e32 v247, v222, v235
	v_mul_f32_e32 v246, 0x3e0293ee, v246
	v_mul_f32_e32 v247, 0x3e0293ee, v247
	v_exp_f32_e32 v246, v246
	v_exp_f32_e32 v247, v247
	s_cmp_eq_u64 vcc, exec
	s_cselect_b64 vcc, -1, 0
	v_cndmask_b32_e32 v237, v234, v237, vcc
	v_cndmask_b32_e32 v222, v235, v222, vcc
	v_cndmask_b32_e64 v234, v246, 1.0, vcc
	v_cndmask_b32_e64 v235, v247, 1.0, vcc
	v_mul_f32_e32 v246, 0xbe0293ee, v237
	v_mul_f32_e32 v247, 0xbe0293ee, v222
	v_fmamk_f32 v130, v130, 0x3e0293ee, v246
	v_fmamk_f32 v131, v131, 0x3e0293ee, v246
	v_fmamk_f32 v132, v132, 0x3e0293ee, v246
	v_fmamk_f32 v133, v133, 0x3e0293ee, v246
	v_fmamk_f32 v134, v134, 0x3e0293ee, v246
	v_fmamk_f32 v135, v135, 0x3e0293ee, v246
	v_fmamk_f32 v136, v136, 0x3e0293ee, v246
	v_fmamk_f32 v137, v137, 0x3e0293ee, v246
	v_fmamk_f32 v138, v138, 0x3e0293ee, v246
	v_fmamk_f32 v139, v139, 0x3e0293ee, v246
	v_fmamk_f32 v140, v140, 0x3e0293ee, v246
	v_fmamk_f32 v141, v141, 0x3e0293ee, v246
	v_fmamk_f32 v142, v142, 0x3e0293ee, v246
	v_fmamk_f32 v143, v143, 0x3e0293ee, v246
	v_fmamk_f32 v144, v144, 0x3e0293ee, v246
	v_fmamk_f32 v145, v145, 0x3e0293ee, v246
	v_fmamk_f32 v146, v146, 0x3e0293ee, v247
	v_fmamk_f32 v147, v147, 0x3e0293ee, v247
	v_fmamk_f32 v148, v148, 0x3e0293ee, v247
	v_fmamk_f32 v149, v149, 0x3e0293ee, v247
	v_fmamk_f32 v150, v150, 0x3e0293ee, v247
	v_fmamk_f32 v151, v151, 0x3e0293ee, v247
	v_fmamk_f32 v152, v152, 0x3e0293ee, v247
	v_fmamk_f32 v153, v153, 0x3e0293ee, v247
	v_fmamk_f32 v154, v154, 0x3e0293ee, v247
	v_fmamk_f32 v155, v155, 0x3e0293ee, v247
	v_fmamk_f32 v156, v156, 0x3e0293ee, v247
	v_fmamk_f32 v157, v157, 0x3e0293ee, v247
	v_fmamk_f32 v158, v158, 0x3e0293ee, v247
	v_fmamk_f32 v159, v159, 0x3e0293ee, v247
	v_fmamk_f32 v160, v160, 0x3e0293ee, v247
	v_fmamk_f32 v161, v161, 0x3e0293ee, v247
	v_exp_f32_e32 v130, v130
	v_exp_f32_e32 v131, v131
	v_exp_f32_e32 v132, v132
	v_exp_f32_e32 v133, v133
	v_exp_f32_e32 v134, v134
	v_exp_f32_e32 v135, v135
	v_exp_f32_e32 v136, v136
	v_exp_f32_e32 v137, v137
	v_exp_f32_e32 v138, v138
	v_exp_f32_e32 v139, v139
	v_exp_f32_e32 v140, v140
	v_exp_f32_e32 v141, v141
	v_exp_f32_e32 v142, v142
	v_exp_f32_e32 v143, v143
	v_exp_f32_e32 v144, v144
	v_exp_f32_e32 v145, v145
	v_exp_f32_e32 v146, v146
	v_exp_f32_e32 v147, v147
	v_exp_f32_e32 v148, v148
	v_exp_f32_e32 v149, v149
	v_exp_f32_e32 v150, v150
	v_exp_f32_e32 v151, v151
	v_exp_f32_e32 v152, v152
	v_exp_f32_e32 v153, v153
	v_exp_f32_e32 v154, v154
	v_exp_f32_e32 v155, v155
	v_exp_f32_e32 v156, v156
	v_exp_f32_e32 v157, v157
	v_exp_f32_e32 v158, v158
	v_exp_f32_e32 v159, v159
	v_exp_f32_e32 v160, v160
	v_exp_f32_e32 v161, v161
	v_add_f32_e32 v248, v130, v131
	v_add_f32_e32 v249, v146, v147
	v_add_f32_e32 v248, v248, v132
	v_add_f32_e32 v249, v249, v148
	v_add_f32_e32 v248, v248, v133
	v_add_f32_e32 v249, v249, v149
	v_add_f32_e32 v248, v248, v134
	v_add_f32_e32 v249, v249, v150
	v_add_f32_e32 v248, v248, v135
	v_add_f32_e32 v249, v249, v151
	v_add_f32_e32 v248, v248, v136
	v_add_f32_e32 v249, v249, v152
	v_add_f32_e32 v248, v248, v137
	v_add_f32_e32 v249, v249, v153
	v_add_f32_e32 v248, v248, v138
	v_add_f32_e32 v249, v249, v154
	v_add_f32_e32 v248, v248, v139
	v_add_f32_e32 v249, v249, v155
	v_add_f32_e32 v248, v248, v140
	v_add_f32_e32 v249, v249, v156
	v_add_f32_e32 v248, v248, v141
	v_add_f32_e32 v249, v249, v157
	v_add_f32_e32 v248, v248, v142
	v_add_f32_e32 v249, v249, v158
	v_add_f32_e32 v248, v248, v143
	v_add_f32_e32 v249, v249, v159
	v_add_f32_e32 v248, v248, v144
	v_add_f32_e32 v249, v249, v160
	v_add_f32_e32 v248, v248, v145
	v_add_f32_e32 v249, v249, v161
	ds_bpermute_b32 v246, v224, v248
	ds_bpermute_b32 v247, v224, v249
	s_waitcnt lgkmcnt(0)
	v_add_f32_e32 v248, v248, v246
	v_add_f32_e32 v249, v249, v247
	v_mov_b32_e32 v246, v248
	v_mov_b32_e32 v247, v249
	s_nop 1
	v_permlane32_swap_b32_e32 v248, v246
	v_permlane32_swap_b32_e32 v249, v247
	v_add_f32_e32 v248, v248, v246
	v_add_f32_e32 v249, v249, v247
	v_fma_f32 v0, v0, v234, v248
	v_fma_f32 v223, v223, v235, v249
	v_cvt_pk_bf16_f32 v130, v130, v131
	v_cvt_pk_bf16_f32 v131, v132, v133
	v_cvt_pk_bf16_f32 v132, v134, v135
	v_cvt_pk_bf16_f32 v133, v136, v137
	v_cvt_pk_bf16_f32 v134, v138, v139
	v_cvt_pk_bf16_f32 v135, v140, v141
	v_cvt_pk_bf16_f32 v136, v142, v143
	v_cvt_pk_bf16_f32 v137, v144, v145
	v_cvt_pk_bf16_f32 v138, v146, v147
	v_cvt_pk_bf16_f32 v139, v148, v149
	v_cvt_pk_bf16_f32 v140, v150, v151
	v_cvt_pk_bf16_f32 v141, v152, v153
	v_cvt_pk_bf16_f32 v142, v154, v155
	v_cvt_pk_bf16_f32 v143, v156, v157
	v_cvt_pk_bf16_f32 v144, v158, v159
	v_cvt_pk_bf16_f32 v145, v160, v161
	v_min_f32_e32 v246, v234, v235
	v_cmp_gt_f32_e32 vcc, 1.0, v246
	s_cbranch_vccz .Ld16a_nr0
	s_and_saveexec_b64 s[76:77], s[0:1]
	ds_write_b32 v232, v234 offset:128
	ds_write_b32 v232, v235 offset:192
	s_or_b64 exec, exec, s[76:77]
	s_waitcnt lgkmcnt(0)
	ds_read_b128 v[146:149], v231 offset:128
	ds_read_b128 v[150:153], v231 offset:192
	s_waitcnt lgkmcnt(0)
	v_pk_mul_f32 v[2:3], v[2:3], v[146:147]
	v_pk_mul_f32 v[4:5], v[4:5], v[148:149]
	v_pk_mul_f32 v[6:7], v[6:7], v[146:147]
	v_pk_mul_f32 v[8:9], v[8:9], v[148:149]
	v_pk_mul_f32 v[10:11], v[10:11], v[146:147]
	v_pk_mul_f32 v[12:13], v[12:13], v[148:149]
	v_pk_mul_f32 v[14:15], v[14:15], v[146:147]
	v_pk_mul_f32 v[16:17], v[16:17], v[148:149]
	v_pk_mul_f32 v[18:19], v[18:19], v[146:147]
	v_pk_mul_f32 v[20:21], v[20:21], v[148:149]
	v_pk_mul_f32 v[22:23], v[22:23], v[146:147]
	v_pk_mul_f32 v[24:25], v[24:25], v[148:149]
	v_pk_mul_f32 v[26:27], v[26:27], v[146:147]
	v_pk_mul_f32 v[28:29], v[28:29], v[148:149]
	v_pk_mul_f32 v[30:31], v[30:31], v[146:147]
	v_pk_mul_f32 v[32:33], v[32:33], v[148:149]
	v_pk_mul_f32 v[34:35], v[34:35], v[146:147]
	v_pk_mul_f32 v[36:37], v[36:37], v[148:149]
	v_pk_mul_f32 v[38:39], v[38:39], v[146:147]
	v_pk_mul_f32 v[40:41], v[40:41], v[148:149]
	v_pk_mul_f32 v[42:43], v[42:43], v[146:147]
	v_pk_mul_f32 v[44:45], v[44:45], v[148:149]
	v_pk_mul_f32 v[46:47], v[46:47], v[146:147]
	v_pk_mul_f32 v[48:49], v[48:49], v[148:149]
	v_pk_mul_f32 v[50:51], v[50:51], v[146:147]
	v_pk_mul_f32 v[52:53], v[52:53], v[148:149]
	v_pk_mul_f32 v[54:55], v[54:55], v[146:147]
	v_pk_mul_f32 v[56:57], v[56:57], v[148:149]
	v_pk_mul_f32 v[58:59], v[58:59], v[146:147]
	v_pk_mul_f32 v[60:61], v[60:61], v[148:149]
	v_pk_mul_f32 v[62:63], v[62:63], v[146:147]
	v_pk_mul_f32 v[64:65], v[64:65], v[148:149]
	v_pk_mul_f32 v[66:67], v[66:67], v[150:151]
	v_pk_mul_f32 v[68:69], v[68:69], v[152:153]
	v_pk_mul_f32 v[70:71], v[70:71], v[150:151]
	v_pk_mul_f32 v[72:73], v[72:73], v[152:153]
	v_pk_mul_f32 v[74:75], v[74:75], v[150:151]
	v_pk_mul_f32 v[76:77], v[76:77], v[152:153]
	v_pk_mul_f32 v[78:79], v[78:79], v[150:151]
	v_pk_mul_f32 v[80:81], v[80:81], v[152:153]
	v_pk_mul_f32 v[82:83], v[82:83], v[150:151]
	v_pk_mul_f32 v[84:85], v[84:85], v[152:153]
	v_pk_mul_f32 v[86:87], v[86:87], v[150:151]
	v_pk_mul_f32 v[88:89], v[88:89], v[152:153]
	v_pk_mul_f32 v[90:91], v[90:91], v[150:151]
	v_pk_mul_f32 v[92:93], v[92:93], v[152:153]
	v_pk_mul_f32 v[94:95], v[94:95], v[150:151]
	v_pk_mul_f32 v[96:97], v[96:97], v[152:153]
	v_pk_mul_f32 v[98:99], v[98:99], v[150:151]
	v_pk_mul_f32 v[100:101], v[100:101], v[152:153]
	v_pk_mul_f32 v[102:103], v[102:103], v[150:151]
	v_pk_mul_f32 v[104:105], v[104:105], v[152:153]
	v_pk_mul_f32 v[106:107], v[106:107], v[150:151]
	v_pk_mul_f32 v[108:109], v[108:109], v[152:153]
	v_pk_mul_f32 v[110:111], v[110:111], v[150:151]
	v_pk_mul_f32 v[112:113], v[112:113], v[152:153]
	v_pk_mul_f32 v[114:115], v[114:115], v[150:151]
	v_pk_mul_f32 v[116:117], v[116:117], v[152:153]
	v_pk_mul_f32 v[118:119], v[118:119], v[150:151]
	v_pk_mul_f32 v[120:121], v[120:121], v[152:153]
	v_pk_mul_f32 v[122:123], v[122:123], v[150:151]
	v_pk_mul_f32 v[124:125], v[124:125], v[152:153]
	v_pk_mul_f32 v[126:127], v[126:127], v[150:151]
	v_pk_mul_f32 v[128:129], v[128:129], v[152:153]
.Ld16a_nr0:
	ds_read_b64_tr_b16 v[146:147], v217 offset:0
	ds_read_b64_tr_b16 v[148:149], v217 offset:8192
	ds_read_b64_tr_b16 v[150:151], v217 offset:16384
	ds_read_b64_tr_b16 v[152:153], v217 offset:24576
	ds_read_b64_tr_b16 v[154:155], v217 offset:256
	ds_read_b64_tr_b16 v[156:157], v217 offset:8448
	ds_read_b64_tr_b16 v[158:159], v217 offset:16640
	ds_read_b64_tr_b16 v[160:161], v217 offset:24832
	s_waitcnt lgkmcnt(6)
	v_mfma_f32_16x16x32_bf16 v[2:5], v[130:133], v[146:149], v[2:5]
	v_mfma_f32_16x16x32_bf16 v[66:69], v[138:141], v[146:149], v[66:69]
	ds_read_b64_tr_b16 v[146:147], v217 offset:512
	ds_read_b64_tr_b16 v[148:149], v217 offset:8704
	s_waitcnt lgkmcnt(6)
	v_mfma_f32_16x16x32_bf16 v[2:5], v[134:137], v[150:153], v[2:5]
	v_mfma_f32_16x16x32_bf16 v[66:69], v[142:145], v[150:153], v[66:69]
	ds_read_b64_tr_b16 v[150:151], v217 offset:16896
	ds_read_b64_tr_b16 v[152:153], v217 offset:25088
	s_waitcnt lgkmcnt(6)
	v_mfma_f32_16x16x32_bf16 v[6:9], v[130:133], v[154:157], v[6:9]
	v_mfma_f32_16x16x32_bf16 v[70:73], v[138:141], v[154:157], v[70:73]
	ds_read_b64_tr_b16 v[154:155], v217 offset:768
	ds_read_b64_tr_b16 v[156:157], v217 offset:8960
	s_waitcnt lgkmcnt(6)
	v_mfma_f32_16x16x32_bf16 v[6:9], v[134:137], v[158:161], v[6:9]
	v_mfma_f32_16x16x32_bf16 v[70:73], v[142:145], v[158:161], v[70:73]
	ds_read_b64_tr_b16 v[158:159], v217 offset:17152
	ds_read_b64_tr_b16 v[160:161], v217 offset:25344
	s_waitcnt lgkmcnt(6)
	v_mfma_f32_16x16x32_bf16 v[10:13], v[130:133], v[146:149], v[10:13]
	v_mfma_f32_16x16x32_bf16 v[74:77], v[138:141], v[146:149], v[74:77]
	ds_read_b64_tr_b16 v[146:147], v217 offset:1024
	ds_read_b64_tr_b16 v[148:149], v217 offset:9216
	s_waitcnt lgkmcnt(6)
	v_mfma_f32_16x16x32_bf16 v[10:13], v[134:137], v[150:153], v[10:13]
	v_mfma_f32_16x16x32_bf16 v[74:77], v[142:145], v[150:153], v[74:77]
	ds_read_b64_tr_b16 v[150:151], v217 offset:17408
	ds_read_b64_tr_b16 v[152:153], v217 offset:25600
	s_waitcnt lgkmcnt(6)
	v_mfma_f32_16x16x32_bf16 v[14:17], v[130:133], v[154:157], v[14:17]
	v_mfma_f32_16x16x32_bf16 v[78:81], v[138:141], v[154:157], v[78:81]
	ds_read_b64_tr_b16 v[154:155], v217 offset:1280
	ds_read_b64_tr_b16 v[156:157], v217 offset:9472
	s_waitcnt lgkmcnt(6)
	v_mfma_f32_16x16x32_bf16 v[14:17], v[134:137], v[158:161], v[14:17]
	v_mfma_f32_16x16x32_bf16 v[78:81], v[142:145], v[158:161], v[78:81]
	ds_read_b64_tr_b16 v[158:159], v217 offset:17664
	ds_read_b64_tr_b16 v[160:161], v217 offset:25856
	s_waitcnt lgkmcnt(6)
	v_mfma_f32_16x16x32_bf16 v[18:21], v[130:133], v[146:149], v[18:21]
	v_mfma_f32_16x16x32_bf16 v[82:85], v[138:141], v[146:149], v[82:85]
	ds_read_b64_tr_b16 v[146:147], v217 offset:1536
	ds_read_b64_tr_b16 v[148:149], v217 offset:9728
	s_waitcnt lgkmcnt(6)
	v_mfma_f32_16x16x32_bf16 v[18:21], v[134:137], v[150:153], v[18:21]
	v_mfma_f32_16x16x32_bf16 v[82:85], v[142:145], v[150:153], v[82:85]
	ds_read_b64_tr_b16 v[150:151], v217 offset:17920
	ds_read_b64_tr_b16 v[152:153], v217 offset:26112
	s_waitcnt lgkmcnt(6)
	v_mfma_f32_16x16x32_bf16 v[22:25], v[130:133], v[154:157], v[22:25]
	v_mfma_f32_16x16x32_bf16 v[86:89], v[138:141], v[154:157], v[86:89]
	ds_read_b64_tr_b16 v[154:155], v217 offset:1792
	ds_read_b64_tr_b16 v[156:157], v217 offset:9984
	s_waitcnt lgkmcnt(6)
	v_mfma_f32_16x16x32_bf16 v[22:25], v[134:137], v[158:161], v[22:25]
	v_mfma_f32_16x16x32_bf16 v[86:89], v[142:145], v[158:161], v[86:89]
	ds_read_b64_tr_b16 v[158:159], v217 offset:18176
	ds_read_b64_tr_b16 v[160:161], v217 offset:26368
	s_waitcnt lgkmcnt(6)
	v_mfma_f32_16x16x32_bf16 v[26:29], v[130:133], v[146:149], v[26:29]
	v_mfma_f32_16x16x32_bf16 v[90:93], v[138:141], v[146:149], v[90:93]
	ds_read_b64_tr_b16 v[146:147], v217 offset:2048
	ds_read_b64_tr_b16 v[148:149], v217 offset:10240
	s_waitcnt lgkmcnt(6)
	v_mfma_f32_16x16x32_bf16 v[26:29], v[134:137], v[150:153], v[26:29]
	v_mfma_f32_16x16x32_bf16 v[90:93], v[142:145], v[150:153], v[90:93]
	ds_read_b64_tr_b16 v[150:151], v217 offset:18432
	ds_read_b64_tr_b16 v[152:153], v217 offset:26624
	s_waitcnt lgkmcnt(6)
	v_mfma_f32_16x16x32_bf16 v[30:33], v[130:133], v[154:157], v[30:33]
	v_mfma_f32_16x16x32_bf16 v[94:97], v[138:141], v[154:157], v[94:97]
	ds_read_b64_tr_b16 v[154:155], v217 offset:2304
	ds_read_b64_tr_b16 v[156:157], v217 offset:10496
	s_waitcnt lgkmcnt(6)
	v_mfma_f32_16x16x32_bf16 v[30:33], v[134:137], v[158:161], v[30:33]
	v_mfma_f32_16x16x32_bf16 v[94:97], v[142:145], v[158:161], v[94:97]
	ds_read_b64_tr_b16 v[158:159], v217 offset:18688
	ds_read_b64_tr_b16 v[160:161], v217 offset:26880
	s_waitcnt lgkmcnt(6)
	v_mfma_f32_16x16x32_bf16 v[34:37], v[130:133], v[146:149], v[34:37]
	v_mfma_f32_16x16x32_bf16 v[98:101], v[138:141], v[146:149], v[98:101]
	ds_read_b64_tr_b16 v[146:147], v217 offset:2560
	ds_read_b64_tr_b16 v[148:149], v217 offset:10752
	s_waitcnt lgkmcnt(6)
	v_mfma_f32_16x16x32_bf16 v[34:37], v[134:137], v[150:153], v[34:37]
	v_mfma_f32_16x16x32_bf16 v[98:101], v[142:145], v[150:153], v[98:101]
	ds_read_b64_tr_b16 v[150:151], v217 offset:18944
	ds_read_b64_tr_b16 v[152:153], v217 offset:27136
	s_waitcnt lgkmcnt(6)
	v_mfma_f32_16x16x32_bf16 v[38:41], v[130:133], v[154:157], v[38:41]
	v_mfma_f32_16x16x32_bf16 v[102:105], v[138:141], v[154:157], v[102:105]
	ds_read_b64_tr_b16 v[154:155], v217 offset:2816
	ds_read_b64_tr_b16 v[156:157], v217 offset:11008
	s_waitcnt lgkmcnt(6)
	v_mfma_f32_16x16x32_bf16 v[38:41], v[134:137], v[158:161], v[38:41]
	v_mfma_f32_16x16x32_bf16 v[102:105], v[142:145], v[158:161], v[102:105]
	ds_read_b64_tr_b16 v[158:159], v217 offset:19200
	ds_read_b64_tr_b16 v[160:161], v217 offset:27392
	s_waitcnt lgkmcnt(6)
	v_mfma_f32_16x16x32_bf16 v[42:45], v[130:133], v[146:149], v[42:45]
	v_mfma_f32_16x16x32_bf16 v[106:109], v[138:141], v[146:149], v[106:109]
	ds_read_b64_tr_b16 v[146:147], v217 offset:3072
	ds_read_b64_tr_b16 v[148:149], v217 offset:11264
	s_waitcnt lgkmcnt(6)
	v_mfma_f32_16x16x32_bf16 v[42:45], v[134:137], v[150:153], v[42:45]
	v_mfma_f32_16x16x32_bf16 v[106:109], v[142:145], v[150:153], v[106:109]
	ds_read_b64_tr_b16 v[150:151], v217 offset:19456
	ds_read_b64_tr_b16 v[152:153], v217 offset:27648
	s_waitcnt lgkmcnt(6)
	v_mfma_f32_16x16x32_bf16 v[46:49], v[130:133], v[154:157], v[46:49]
	v_mfma_f32_16x16x32_bf16 v[110:113], v[138:141], v[154:157], v[110:113]
	ds_read_b64_tr_b16 v[154:155], v217 offset:3328
	ds_read_b64_tr_b16 v[156:157], v217 offset:11520
	s_waitcnt lgkmcnt(6)
	v_mfma_f32_16x16x32_bf16 v[46:49], v[134:137], v[158:161], v[46:49]
	v_mfma_f32_16x16x32_bf16 v[110:113], v[142:145], v[158:161], v[110:113]
	ds_read_b64_tr_b16 v[158:159], v217 offset:19712
	ds_read_b64_tr_b16 v[160:161], v217 offset:27904
	s_waitcnt lgkmcnt(6)
	v_mfma_f32_16x16x32_bf16 v[50:53], v[130:133], v[146:149], v[50:53]
	v_mfma_f32_16x16x32_bf16 v[114:117], v[138:141], v[146:149], v[114:117]
	ds_read_b64_tr_b16 v[146:147], v217 offset:3584
	ds_read_b64_tr_b16 v[148:149], v217 offset:11776
	s_waitcnt lgkmcnt(6)
	v_mfma_f32_16x16x32_bf16 v[50:53], v[134:137], v[150:153], v[50:53]
	v_mfma_f32_16x16x32_bf16 v[114:117], v[142:145], v[150:153], v[114:117]
	ds_read_b64_tr_b16 v[150:151], v217 offset:19968
	ds_read_b64_tr_b16 v[152:153], v217 offset:28160
	s_waitcnt lgkmcnt(6)
	v_mfma_f32_16x16x32_bf16 v[54:57], v[130:133], v[154:157], v[54:57]
	v_mfma_f32_16x16x32_bf16 v[118:121], v[138:141], v[154:157], v[118:121]
	ds_read_b64_tr_b16 v[154:155], v217 offset:3840
	ds_read_b64_tr_b16 v[156:157], v217 offset:12032
	s_waitcnt lgkmcnt(6)
	v_mfma_f32_16x16x32_bf16 v[54:57], v[134:137], v[158:161], v[54:57]
	v_mfma_f32_16x16x32_bf16 v[118:121], v[142:145], v[158:161], v[118:121]
	ds_read_b64_tr_b16 v[158:159], v217 offset:20224
	ds_read_b64_tr_b16 v[160:161], v217 offset:28416
	s_waitcnt lgkmcnt(6)
	v_mfma_f32_16x16x32_bf16 v[58:61], v[130:133], v[146:149], v[58:61]
	v_mfma_f32_16x16x32_bf16 v[122:125], v[138:141], v[146:149], v[122:125]
	s_waitcnt lgkmcnt(4)
	v_mfma_f32_16x16x32_bf16 v[58:61], v[134:137], v[150:153], v[58:61]
	v_mfma_f32_16x16x32_bf16 v[122:125], v[142:145], v[150:153], v[122:125]
	s_waitcnt lgkmcnt(2)
	v_mfma_f32_16x16x32_bf16 v[62:65], v[130:133], v[154:157], v[62:65]
	v_mfma_f32_16x16x32_bf16 v[126:129], v[138:141], v[154:157], v[126:129]
	s_waitcnt lgkmcnt(0)
	v_mfma_f32_16x16x32_bf16 v[62:65], v[134:137], v[158:161], v[62:65]
	v_mfma_f32_16x16x32_bf16 v[126:129], v[142:145], v[158:161], v[126:129]
	s_waitcnt vmcnt(0)
	s_cmp_gt_u32 s57, s55
	s_cselect_b64 s[36:37], -1, 0
	s_and_b64 vcc, exec, s[36:37]
	s_waitcnt vmcnt(0) lgkmcnt(0)
	s_barrier
	s_cbranch_vccnz .LBB0_798
	s_mov_b64 s[38:39], src_shared_base
	s_cmp_lg_u32 0, -1
	s_cselect_b32 s38, 0, 0
	s_cselect_b32 s39, s39, 0
	s_add_u32 s38, s38, 0x10000
	s_addc_u32 s39, s39, 0
	s_cmp_lg_u64 s[38:39], 0
	s_cselect_b32 s38, s38, -1
	s_add_i32 s38, s38, s53
	v_lshl_add_u64 v[130:131], v[206:207], 0, s[20:21]
	s_mov_b32 m0, s38
	s_nop 0
	global_load_lds_dwordx4 v[130:131], off
	v_lshl_add_u64 v[130:131], v[204:205], 0, s[20:21]
	s_add_i32 m0, s38, 0x400
	s_add_i32 s38, s54, 0
	global_load_lds_dwordx4 v[130:131], off
	v_lshl_add_u64 v[130:131], v[202:203], 0, s[22:23]
	s_mov_b32 m0, s38
	s_nop 0
	global_load_lds_dwordx4 v[130:131], off
	v_lshl_add_u64 v[130:131], v[202:203], 0, s[24:25]
	s_add_i32 m0, s38, 0x400
	s_nop 0
	global_load_lds_dwordx4 v[130:131], off
	v_lshl_add_u64 v[130:131], v[202:203], 0, s[26:27]
	s_add_i32 m0, s38, 0x800
	s_nop 0
	global_load_lds_dwordx4 v[130:131], off
	v_lshl_add_u64 v[130:131], v[202:203], 0, s[28:29]
	s_add_i32 m0, s38, 0xc00
	s_nop 0
	global_load_lds_dwordx4 v[130:131], off
.LBB0_798:
	ds_read_b128 v[238:241], v218 offset:16384
	ds_read_b128 v[242:245], v219 offset:16384
	ds_read_b128 v[246:249], v218 offset:16512
	s_waitcnt lgkmcnt(2)
	v_mfma_f32_16x16x32_bf16 v[130:133], v[238:241], v[162:165], 0
	v_mfma_f32_16x16x32_bf16 v[146:149], v[238:241], v[178:181], 0
	ds_read_b128 v[238:241], v219 offset:16512
	s_waitcnt lgkmcnt(2)
	v_mfma_f32_16x16x32_bf16 v[130:133], v[242:245], v[166:169], v[130:133]
	v_mfma_f32_16x16x32_bf16 v[146:149], v[242:245], v[182:185], v[146:149]
	ds_read_b128 v[242:245], v218 offset:20480
	s_waitcnt lgkmcnt(2)
	v_mfma_f32_16x16x32_bf16 v[130:133], v[246:249], v[170:173], v[130:133]
	v_mfma_f32_16x16x32_bf16 v[146:149], v[246:249], v[186:189], v[146:149]
	ds_read_b128 v[246:249], v219 offset:20480
	s_waitcnt lgkmcnt(2)
	v_mfma_f32_16x16x32_bf16 v[130:133], v[238:241], v[174:177], v[130:133]
	v_mfma_f32_16x16x32_bf16 v[146:149], v[238:241], v[190:193], v[146:149]
	ds_read_b128 v[238:241], v218 offset:20608
	s_waitcnt lgkmcnt(2)
	v_mfma_f32_16x16x32_bf16 v[134:137], v[242:245], v[162:165], 0
	v_mfma_f32_16x16x32_bf16 v[150:153], v[242:245], v[178:181], 0
	ds_read_b128 v[242:245], v219 offset:20608
	s_waitcnt lgkmcnt(2)
	v_mfma_f32_16x16x32_bf16 v[134:137], v[246:249], v[166:169], v[134:137]
	v_mfma_f32_16x16x32_bf16 v[150:153], v[246:249], v[182:185], v[150:153]
	ds_read_b128 v[246:249], v218 offset:24576
	s_waitcnt lgkmcnt(2)
	v_mfma_f32_16x16x32_bf16 v[134:137], v[238:241], v[170:173], v[134:137]
	v_mfma_f32_16x16x32_bf16 v[150:153], v[238:241], v[186:189], v[150:153]
	ds_read_b128 v[238:241], v219 offset:24576
	s_waitcnt lgkmcnt(2)
	v_mfma_f32_16x16x32_bf16 v[134:137], v[242:245], v[174:177], v[134:137]
	v_mfma_f32_16x16x32_bf16 v[150:153], v[242:245], v[190:193], v[150:153]
	ds_read_b128 v[242:245], v218 offset:24704
	s_waitcnt lgkmcnt(2)
	v_mfma_f32_16x16x32_bf16 v[138:141], v[246:249], v[162:165], 0
	v_mfma_f32_16x16x32_bf16 v[154:157], v[246:249], v[178:181], 0
	ds_read_b128 v[246:249], v219 offset:24704
	s_waitcnt lgkmcnt(2)
	v_mfma_f32_16x16x32_bf16 v[138:141], v[238:241], v[166:169], v[138:141]
	v_mfma_f32_16x16x32_bf16 v[154:157], v[238:241], v[182:185], v[154:157]
	ds_read_b128 v[238:241], v218 offset:28672
	s_waitcnt lgkmcnt(2)
	v_mfma_f32_16x16x32_bf16 v[138:141], v[242:245], v[170:173], v[138:141]
	v_mfma_f32_16x16x32_bf16 v[154:157], v[242:245], v[186:189], v[154:157]
	ds_read_b128 v[242:245], v219 offset:28672
	s_waitcnt lgkmcnt(2)
	v_mfma_f32_16x16x32_bf16 v[138:141], v[246:249], v[174:177], v[138:141]
	v_mfma_f32_16x16x32_bf16 v[154:157], v[246:249], v[190:193], v[154:157]
	ds_read_b128 v[246:249], v218 offset:28800
	s_waitcnt lgkmcnt(2)
	v_mfma_f32_16x16x32_bf16 v[142:145], v[238:241], v[162:165], 0
	v_mfma_f32_16x16x32_bf16 v[158:161], v[238:241], v[178:181], 0
	ds_read_b128 v[238:241], v219 offset:28800
	s_waitcnt lgkmcnt(2)
	v_mfma_f32_16x16x32_bf16 v[142:145], v[242:245], v[166:169], v[142:145]
	v_mfma_f32_16x16x32_bf16 v[158:161], v[242:245], v[182:185], v[158:161]
	s_waitcnt lgkmcnt(1)
	v_mfma_f32_16x16x32_bf16 v[142:145], v[246:249], v[170:173], v[142:145]
	v_mfma_f32_16x16x32_bf16 v[158:161], v[246:249], v[186:189], v[158:161]
	s_waitcnt lgkmcnt(0)
	v_mfma_f32_16x16x32_bf16 v[142:145], v[238:241], v[174:177], v[142:145]
	v_mfma_f32_16x16x32_bf16 v[158:161], v[238:241], v[190:193], v[158:161]
	s_nop 7
	s_nop 1
	s_cmp_le_i32 s56, s4
	s_cbranch_scc1 .Ld16a_nm1
	v_subrev_u32_e32 v246, 64, v233
	v_cmp_gt_i32_e64 s[74:75], 0, v246
	v_cmp_gt_i32_e64 s[76:77], 1, v246
	v_cmp_gt_i32_e64 s[78:79], 2, v246
	v_cmp_gt_i32_e64 s[80:81], 3, v246
	v_cndmask_b32_e64 v130, v130, v230, s[74:75]
	v_cndmask_b32_e64 v131, v131, v230, s[76:77]
	v_cndmask_b32_e64 v132, v132, v230, s[78:79]
	v_cndmask_b32_e64 v133, v133, v230, s[80:81]
	v_cmp_gt_i32_e64 s[74:75], 16, v246
	v_cmp_gt_i32_e64 s[76:77], 17, v246
	v_cmp_gt_i32_e64 s[78:79], 18, v246
	v_cmp_gt_i32_e64 s[80:81], 19, v246
	v_cndmask_b32_e64 v134, v134, v230, s[74:75]
	v_cndmask_b32_e64 v135, v135, v230, s[76:77]
	v_cndmask_b32_e64 v136, v136, v230, s[78:79]
	v_cndmask_b32_e64 v137, v137, v230, s[80:81]
	v_cmp_gt_i32_e64 s[74:75], 32, v246
	v_cmp_gt_i32_e64 s[76:77], 33, v246
	v_cmp_gt_i32_e64 s[78:79], 34, v246
	v_cmp_gt_i32_e64 s[80:81], 35, v246
	v_cndmask_b32_e64 v138, v138, v230, s[74:75]
	v_cndmask_b32_e64 v139, v139, v230, s[76:77]
	v_cndmask_b32_e64 v140, v140, v230, s[78:79]
	v_cndmask_b32_e64 v141, v141, v230, s[80:81]
	v_cmp_gt_i32_e64 s[74:75], 48, v246
	v_cmp_gt_i32_e64 s[76:77], 49, v246
	v_cmp_gt_i32_e64 s[78:79], 50, v246
	v_cmp_gt_i32_e64 s[80:81], 51, v246
	v_cndmask_b32_e64 v142, v142, v230, s[74:75]
	v_cndmask_b32_e64 v143, v143, v230, s[76:77]
	v_cndmask_b32_e64 v144, v144, v230, s[78:79]
	v_cndmask_b32_e64 v145, v145, v230, s[80:81]
	v_cmp_gt_i32_e64 s[74:75], -16, v246
	v_cmp_gt_i32_e64 s[76:77], -15, v246
	v_cmp_gt_i32_e64 s[78:79], -14, v246
	v_cmp_gt_i32_e64 s[80:81], -13, v246
	v_cndmask_b32_e64 v146, v146, v230, s[74:75]
	v_cndmask_b32_e64 v147, v147, v230, s[76:77]
	v_cndmask_b32_e64 v148, v148, v230, s[78:79]
	v_cndmask_b32_e64 v149, v149, v230, s[80:81]
	v_cmp_gt_i32_e64 s[74:75], 0, v246
	v_cmp_gt_i32_e64 s[76:77], 1, v246
	v_cmp_gt_i32_e64 s[78:79], 2, v246
	v_cmp_gt_i32_e64 s[80:81], 3, v246
	v_cndmask_b32_e64 v150, v150, v230, s[74:75]
	v_cndmask_b32_e64 v151, v151, v230, s[76:77]
	v_cndmask_b32_e64 v152, v152, v230, s[78:79]
	v_cndmask_b32_e64 v153, v153, v230, s[80:81]
	v_cmp_gt_i32_e64 s[74:75], 16, v246
	v_cmp_gt_i32_e64 s[76:77], 17, v246
	v_cmp_gt_i32_e64 s[78:79], 18, v246
	v_cmp_gt_i32_e64 s[80:81], 19, v246
	v_cndmask_b32_e64 v154, v154, v230, s[74:75]
	v_cndmask_b32_e64 v155, v155, v230, s[76:77]
	v_cndmask_b32_e64 v156, v156, v230, s[78:79]
	v_cndmask_b32_e64 v157, v157, v230, s[80:81]
	v_cmp_gt_i32_e64 s[74:75], 32, v246
	v_cmp_gt_i32_e64 s[76:77], 33, v246
	v_cmp_gt_i32_e64 s[78:79], 34, v246
	v_cmp_gt_i32_e64 s[80:81], 35, v246
	v_cndmask_b32_e64 v158, v158, v230, s[74:75]
	v_cndmask_b32_e64 v159, v159, v230, s[76:77]
	v_cndmask_b32_e64 v160, v160, v230, s[78:79]
	v_cndmask_b32_e64 v161, v161, v230, s[80:81]

.Ld16a_nr1:
	ds_read_b64_tr_b16 v[146:147], v217 offset:32768
	ds_read_b64_tr_b16 v[148:149], v217 offset:40960
	ds_read_b64_tr_b16 v[150:151], v217 offset:49152
	ds_read_b64_tr_b16 v[152:153], v217 offset:57344
	ds_read_b64_tr_b16 v[154:155], v217 offset:33024
	ds_read_b64_tr_b16 v[156:157], v217 offset:41216
	ds_read_b64_tr_b16 v[158:159], v217 offset:49408
	ds_read_b64_tr_b16 v[160:161], v217 offset:57600
	s_waitcnt lgkmcnt(6)
	v_mfma_f32_16x16x32_bf16 v[2:5], v[130:133], v[146:149], v[2:5]
	v_mfma_f32_16x16x32_bf16 v[66:69], v[138:141], v[146:149], v[66:69]
	ds_read_b64_tr_b16 v[146:147], v217 offset:33280
	ds_read_b64_tr_b16 v[148:149], v217 offset:41472
	s_waitcnt lgkmcnt(6)
	v_mfma_f32_16x16x32_bf16 v[2:5], v[134:137], v[150:153], v[2:5]
	v_mfma_f32_16x16x32_bf16 v[66:69], v[142:145], v[150:153], v[66:69]
	ds_read_b64_tr_b16 v[150:151], v217 offset:49664
	ds_read_b64_tr_b16 v[152:153], v217 offset:57856
	s_waitcnt lgkmcnt(6)
	v_mfma_f32_16x16x32_bf16 v[6:9], v[130:133], v[154:157], v[6:9]
	v_mfma_f32_16x16x32_bf16 v[70:73], v[138:141], v[154:157], v[70:73]
	ds_read_b64_tr_b16 v[154:155], v217 offset:33536
	ds_read_b64_tr_b16 v[156:157], v217 offset:41728
	s_waitcnt lgkmcnt(6)
	v_mfma_f32_16x16x32_bf16 v[6:9], v[134:137], v[158:161], v[6:9]
	v_mfma_f32_16x16x32_bf16 v[70:73], v[142:145], v[158:161], v[70:73]
	ds_read_b64_tr_b16 v[158:159], v217 offset:49920
	ds_read_b64_tr_b16 v[160:161], v217 offset:58112
	s_waitcnt lgkmcnt(6)
	v_mfma_f32_16x16x32_bf16 v[10:13], v[130:133], v[146:149], v[10:13]
	v_mfma_f32_16x16x32_bf16 v[74:77], v[138:141], v[146:149], v[74:77]
	ds_read_b64_tr_b16 v[146:147], v217 offset:33792
	ds_read_b64_tr_b16 v[148:149], v217 offset:41984
	s_waitcnt lgkmcnt(6)
	v_mfma_f32_16x16x32_bf16 v[10:13], v[134:137], v[150:153], v[10:13]
	v_mfma_f32_16x16x32_bf16 v[74:77], v[142:145], v[150:153], v[74:77]
	ds_read_b64_tr_b16 v[150:151], v217 offset:50176
	ds_read_b64_tr_b16 v[152:153], v217 offset:58368
	s_waitcnt lgkmcnt(6)
	v_mfma_f32_16x16x32_bf16 v[14:17], v[130:133], v[154:157], v[14:17]
	v_mfma_f32_16x16x32_bf16 v[78:81], v[138:141], v[154:157], v[78:81]
	ds_read_b64_tr_b16 v[154:155], v217 offset:34048
	ds_read_b64_tr_b16 v[156:157], v217 offset:42240
	s_waitcnt lgkmcnt(6)
	v_mfma_f32_16x16x32_bf16 v[14:17], v[134:137], v[158:161], v[14:17]
	v_mfma_f32_16x16x32_bf16 v[78:81], v[142:145], v[158:161], v[78:81]
	ds_read_b64_tr_b16 v[158:159], v217 offset:50432
	ds_read_b64_tr_b16 v[160:161], v217 offset:58624
	s_waitcnt lgkmcnt(6)
	v_mfma_f32_16x16x32_bf16 v[18:21], v[130:133], v[146:149], v[18:21]
	v_mfma_f32_16x16x32_bf16 v[82:85], v[138:141], v[146:149], v[82:85]
	ds_read_b64_tr_b16 v[146:147], v217 offset:34304
	ds_read_b64_tr_b16 v[148:149], v217 offset:42496
	s_waitcnt lgkmcnt(6)
	v_mfma_f32_16x16x32_bf16 v[18:21], v[134:137], v[150:153], v[18:21]
	v_mfma_f32_16x16x32_bf16 v[82:85], v[142:145], v[150:153], v[82:85]
	ds_read_b64_tr_b16 v[150:151], v217 offset:50688
	ds_read_b64_tr_b16 v[152:153], v217 offset:58880
	s_waitcnt lgkmcnt(6)
	v_mfma_f32_16x16x32_bf16 v[22:25], v[130:133], v[154:157], v[22:25]
	v_mfma_f32_16x16x32_bf16 v[86:89], v[138:141], v[154:157], v[86:89]
	ds_read_b64_tr_b16 v[154:155], v217 offset:34560
	ds_read_b64_tr_b16 v[156:157], v217 offset:42752
	s_waitcnt lgkmcnt(6)
	v_mfma_f32_16x16x32_bf16 v[22:25], v[134:137], v[158:161], v[22:25]
	v_mfma_f32_16x16x32_bf16 v[86:89], v[142:145], v[158:161], v[86:89]
	ds_read_b64_tr_b16 v[158:159], v217 offset:50944
	ds_read_b64_tr_b16 v[160:161], v217 offset:59136
	s_waitcnt lgkmcnt(6)
	v_mfma_f32_16x16x32_bf16 v[26:29], v[130:133], v[146:149], v[26:29]
	v_mfma_f32_16x16x32_bf16 v[90:93], v[138:141], v[146:149], v[90:93]
	ds_read_b64_tr_b16 v[146:147], v217 offset:34816
	ds_read_b64_tr_b16 v[148:149], v217 offset:43008
	s_waitcnt lgkmcnt(6)
	v_mfma_f32_16x16x32_bf16 v[26:29], v[134:137], v[150:153], v[26:29]
	v_mfma_f32_16x16x32_bf16 v[90:93], v[142:145], v[150:153], v[90:93]
	ds_read_b64_tr_b16 v[150:151], v217 offset:51200
	ds_read_b64_tr_b16 v[152:153], v217 offset:59392
	s_waitcnt lgkmcnt(6)
	v_mfma_f32_16x16x32_bf16 v[30:33], v[130:133], v[154:157], v[30:33]
	v_mfma_f32_16x16x32_bf16 v[94:97], v[138:141], v[154:157], v[94:97]
	ds_read_b64_tr_b16 v[154:155], v217 offset:35072
	ds_read_b64_tr_b16 v[156:157], v217 offset:43264
	s_waitcnt lgkmcnt(6)
	v_mfma_f32_16x16x32_bf16 v[30:33], v[134:137], v[158:161], v[30:33]
	v_mfma_f32_16x16x32_bf16 v[94:97], v[142:145], v[158:161], v[94:97]
	ds_read_b64_tr_b16 v[158:159], v217 offset:51456
	ds_read_b64_tr_b16 v[160:161], v217 offset:59648
	s_waitcnt lgkmcnt(6)
	v_mfma_f32_16x16x32_bf16 v[34:37], v[130:133], v[146:149], v[34:37]
	v_mfma_f32_16x16x32_bf16 v[98:101], v[138:141], v[146:149], v[98:101]
	ds_read_b64_tr_b16 v[146:147], v217 offset:35328
	ds_read_b64_tr_b16 v[148:149], v217 offset:43520
	s_waitcnt lgkmcnt(6)
	v_mfma_f32_16x16x32_bf16 v[34:37], v[134:137], v[150:153], v[34:37]
	v_mfma_f32_16x16x32_bf16 v[98:101], v[142:145], v[150:153], v[98:101]
	ds_read_b64_tr_b16 v[150:151], v217 offset:51712
	ds_read_b64_tr_b16 v[152:153], v217 offset:59904
	s_waitcnt lgkmcnt(6)
	v_mfma_f32_16x16x32_bf16 v[38:41], v[130:133], v[154:157], v[38:41]
	v_mfma_f32_16x16x32_bf16 v[102:105], v[138:141], v[154:157], v[102:105]
	ds_read_b64_tr_b16 v[154:155], v217 offset:35584
	ds_read_b64_tr_b16 v[156:157], v217 offset:43776
	s_waitcnt lgkmcnt(6)
	v_mfma_f32_16x16x32_bf16 v[38:41], v[134:137], v[158:161], v[38:41]
	v_mfma_f32_16x16x32_bf16 v[102:105], v[142:145], v[158:161], v[102:105]
	ds_read_b64_tr_b16 v[158:159], v217 offset:51968
	ds_read_b64_tr_b16 v[160:161], v217 offset:60160
	s_waitcnt lgkmcnt(6)
	v_mfma_f32_16x16x32_bf16 v[42:45], v[130:133], v[146:149], v[42:45]
	v_mfma_f32_16x16x32_bf16 v[106:109], v[138:141], v[146:149], v[106:109]
	ds_read_b64_tr_b16 v[146:147], v217 offset:35840
	ds_read_b64_tr_b16 v[148:149], v217 offset:44032
	s_waitcnt lgkmcnt(6)
	v_mfma_f32_16x16x32_bf16 v[42:45], v[134:137], v[150:153], v[42:45]
	v_mfma_f32_16x16x32_bf16 v[106:109], v[142:145], v[150:153], v[106:109]
	ds_read_b64_tr_b16 v[150:151], v217 offset:52224
	ds_read_b64_tr_b16 v[152:153], v217 offset:60416
	s_waitcnt lgkmcnt(6)
	v_mfma_f32_16x16x32_bf16 v[46:49], v[130:133], v[154:157], v[46:49]
	v_mfma_f32_16x16x32_bf16 v[110:113], v[138:141], v[154:157], v[110:113]
	ds_read_b64_tr_b16 v[154:155], v217 offset:36096
	ds_read_b64_tr_b16 v[156:157], v217 offset:44288
	s_waitcnt lgkmcnt(6)
	v_mfma_f32_16x16x32_bf16 v[46:49], v[134:137], v[158:161], v[46:49]
	v_mfma_f32_16x16x32_bf16 v[110:113], v[142:145], v[158:161], v[110:113]
	ds_read_b64_tr_b16 v[158:159], v217 offset:52480
	ds_read_b64_tr_b16 v[160:161], v217 offset:60672
	s_waitcnt lgkmcnt(6)
	v_mfma_f32_16x16x32_bf16 v[50:53], v[130:133], v[146:149], v[50:53]
	v_mfma_f32_16x16x32_bf16 v[114:117], v[138:141], v[146:149], v[114:117]
	ds_read_b64_tr_b16 v[146:147], v217 offset:36352
	ds_read_b64_tr_b16 v[148:149], v217 offset:44544
	s_waitcnt lgkmcnt(6)
	v_mfma_f32_16x16x32_bf16 v[50:53], v[134:137], v[150:153], v[50:53]
	v_mfma_f32_16x16x32_bf16 v[114:117], v[142:145], v[150:153], v[114:117]
	ds_read_b64_tr_b16 v[150:151], v217 offset:52736
	ds_read_b64_tr_b16 v[152:153], v217 offset:60928
	s_waitcnt lgkmcnt(6)
	v_mfma_f32_16x16x32_bf16 v[54:57], v[130:133], v[154:157], v[54:57]
	v_mfma_f32_16x16x32_bf16 v[118:121], v[138:141], v[154:157], v[118:121]
	ds_read_b64_tr_b16 v[154:155], v217 offset:36608
	ds_read_b64_tr_b16 v[156:157], v217 offset:44800
	s_waitcnt lgkmcnt(6)
	v_mfma_f32_16x16x32_bf16 v[54:57], v[134:137], v[158:161], v[54:57]
	v_mfma_f32_16x16x32_bf16 v[118:121], v[142:145], v[158:161], v[118:121]
	ds_read_b64_tr_b16 v[158:159], v217 offset:52992
	ds_read_b64_tr_b16 v[160:161], v217 offset:61184
	s_waitcnt lgkmcnt(6)
	v_mfma_f32_16x16x32_bf16 v[58:61], v[130:133], v[146:149], v[58:61]
	v_mfma_f32_16x16x32_bf16 v[122:125], v[138:141], v[146:149], v[122:125]
	s_waitcnt lgkmcnt(4)
	v_mfma_f32_16x16x32_bf16 v[58:61], v[134:137], v[150:153], v[58:61]
	v_mfma_f32_16x16x32_bf16 v[122:125], v[142:145], v[150:153], v[122:125]
	s_waitcnt lgkmcnt(2)
	v_mfma_f32_16x16x32_bf16 v[62:65], v[130:133], v[154:157], v[62:65]
	v_mfma_f32_16x16x32_bf16 v[126:129], v[138:141], v[154:157], v[126:129]
	s_waitcnt lgkmcnt(0)
	v_mfma_f32_16x16x32_bf16 v[62:65], v[134:137], v[158:161], v[62:65]
	v_mfma_f32_16x16x32_bf16 v[126:129], v[142:145], v[158:161], v[126:129]
	s_branch .Ld16a_bot
.LBB0_803:
	s_and_saveexec_b64 s[34:35], s[0:1]
	ds_write_b32 v232, v0
	ds_write_b32 v232, v223 offset:64
	s_or_b64 exec, exec, s[34:35]
	s_waitcnt lgkmcnt(0)
	ds_read_b128 v[146:149], v231
	ds_read_b128 v[150:153], v231 offset:64
	s_lshl_b64 s[2:3], s[2:3], 12
	s_add_u32 s2, s42, s2
	s_addc_u32 s3, s43, s3
	s_lshl_b32 s4, s52, 9
	s_add_u32 s4, s2, s4
	s_addc_u32 s34, s3, 0
	s_lshl_b64 s[2:3], s[30:31], 12
	s_add_u32 s30, s4, s2
	s_addc_u32 s31, s34, s3
	v_mbcnt_lo_u32_b32 v202, -1, 0
	v_mbcnt_hi_u32_b32 v202, -1, v202
	v_and_b32_e32 v203, 15, v202
	v_lshrrev_b32_e32 v204, 4, v202
	v_lshlrev_b32_e32 v204, 14, v204
	v_lshl_or_b32 v204, v203, 1, v204
	v_and_b32_e32 v203, 1, v202
	v_cmp_eq_u32_e64 s[76:77], 0, v203
	s_waitcnt lgkmcnt(0)
	v_rcp_f32_e32 v146, v146
	v_rcp_f32_e32 v147, v147
	v_rcp_f32_e32 v148, v148
	v_rcp_f32_e32 v149, v149
	v_rcp_f32_e32 v150, v150
	v_rcp_f32_e32 v151, v151
	v_rcp_f32_e32 v152, v152
	v_rcp_f32_e32 v153, v153
	s_nop 0
	v_mov_b32_e32 v205, v204
	v_mul_f32_e32 v2, v2, v146
	v_mul_f32_e32 v6, v6, v146
	v_mul_f32_e32 v10, v10, v146
	v_mul_f32_e32 v14, v14, v146
	v_mul_f32_e32 v18, v18, v146
	v_mul_f32_e32 v22, v22, v146
	v_mul_f32_e32 v26, v26, v146
	v_mul_f32_e32 v30, v30, v146
	v_mul_f32_e32 v34, v34, v146
	v_mul_f32_e32 v38, v38, v146
	v_mul_f32_e32 v42, v42, v146
	v_mul_f32_e32 v46, v46, v146
	v_mul_f32_e32 v50, v50, v146
	v_mul_f32_e32 v54, v54, v146
	v_mul_f32_e32 v58, v58, v146
	v_mul_f32_e32 v62, v62, v146
	v_mov_b32_dpp v162, v2 quad_perm:[1,0,3,2] row_mask:0xf bank_mask:0xf
	v_mov_b32_dpp v163, v6 quad_perm:[1,0,3,2] row_mask:0xf bank_mask:0xf
	v_mov_b32_dpp v164, v10 quad_perm:[1,0,3,2] row_mask:0xf bank_mask:0xf
	v_mov_b32_dpp v165, v14 quad_perm:[1,0,3,2] row_mask:0xf bank_mask:0xf
	v_mov_b32_dpp v166, v18 quad_perm:[1,0,3,2] row_mask:0xf bank_mask:0xf
	v_mov_b32_dpp v167, v22 quad_perm:[1,0,3,2] row_mask:0xf bank_mask:0xf
	v_mov_b32_dpp v168, v26 quad_perm:[1,0,3,2] row_mask:0xf bank_mask:0xf
	v_mov_b32_dpp v169, v30 quad_perm:[1,0,3,2] row_mask:0xf bank_mask:0xf
	v_mov_b32_dpp v170, v34 quad_perm:[1,0,3,2] row_mask:0xf bank_mask:0xf
	v_mov_b32_dpp v171, v38 quad_perm:[1,0,3,2] row_mask:0xf bank_mask:0xf
	v_mov_b32_dpp v172, v42 quad_perm:[1,0,3,2] row_mask:0xf bank_mask:0xf
	v_mov_b32_dpp v173, v46 quad_perm:[1,0,3,2] row_mask:0xf bank_mask:0xf
	v_mov_b32_dpp v174, v50 quad_perm:[1,0,3,2] row_mask:0xf bank_mask:0xf
	v_mov_b32_dpp v175, v54 quad_perm:[1,0,3,2] row_mask:0xf bank_mask:0xf
	v_mov_b32_dpp v176, v58 quad_perm:[1,0,3,2] row_mask:0xf bank_mask:0xf
	v_mov_b32_dpp v177, v62 quad_perm:[1,0,3,2] row_mask:0xf bank_mask:0xf
	v_cvt_pk_bf16_f32 v2, v2, v162
	v_cvt_pk_bf16_f32 v6, v6, v163
	v_cvt_pk_bf16_f32 v10, v10, v164
	v_cvt_pk_bf16_f32 v14, v14, v165
	v_cvt_pk_bf16_f32 v18, v18, v166
	v_cvt_pk_bf16_f32 v22, v22, v167
	v_cvt_pk_bf16_f32 v26, v26, v168
	v_cvt_pk_bf16_f32 v30, v30, v169
	v_cvt_pk_bf16_f32 v34, v34, v170
	v_cvt_pk_bf16_f32 v38, v38, v171
	v_cvt_pk_bf16_f32 v42, v42, v172
	v_cvt_pk_bf16_f32 v46, v46, v173
	v_cvt_pk_bf16_f32 v50, v50, v174
	v_cvt_pk_bf16_f32 v54, v54, v175
	v_cvt_pk_bf16_f32 v58, v58, v176
	v_cvt_pk_bf16_f32 v62, v62, v177
	s_mov_b64 exec, s[76:77]
	global_store_dword v205, v2, s[30:31] offset:0
	global_store_dword v205, v6, s[30:31] offset:32
	global_store_dword v205, v10, s[30:31] offset:64
	global_store_dword v205, v14, s[30:31] offset:96
	global_store_dword v205, v18, s[30:31] offset:128
	global_store_dword v205, v22, s[30:31] offset:160
	global_store_dword v205, v26, s[30:31] offset:192
	global_store_dword v205, v30, s[30:31] offset:224
	global_store_dword v205, v34, s[30:31] offset:256
	global_store_dword v205, v38, s[30:31] offset:288
	global_store_dword v205, v42, s[30:31] offset:320
	global_store_dword v205, v46, s[30:31] offset:352
	global_store_dword v205, v50, s[30:31] offset:384
	global_store_dword v205, v54, s[30:31] offset:416
	global_store_dword v205, v58, s[30:31] offset:448
	global_store_dword v205, v62, s[30:31] offset:480
	s_mov_b64 exec, -1
	v_add_u32_e32 v205, 0x1000, v204
	v_mul_f32_e32 v3, v3, v147
	v_mul_f32_e32 v7, v7, v147
	v_mul_f32_e32 v11, v11, v147
	v_mul_f32_e32 v15, v15, v147
	v_mul_f32_e32 v19, v19, v147
	v_mul_f32_e32 v23, v23, v147
	v_mul_f32_e32 v27, v27, v147
	v_mul_f32_e32 v31, v31, v147
	v_mul_f32_e32 v35, v35, v147
	v_mul_f32_e32 v39, v39, v147
	v_mul_f32_e32 v43, v43, v147
	v_mul_f32_e32 v47, v47, v147
	v_mul_f32_e32 v51, v51, v147
	v_mul_f32_e32 v55, v55, v147
	v_mul_f32_e32 v59, v59, v147
	v_mul_f32_e32 v63, v63, v147
	v_mov_b32_dpp v162, v3 quad_perm:[1,0,3,2] row_mask:0xf bank_mask:0xf
	v_mov_b32_dpp v163, v7 quad_perm:[1,0,3,2] row_mask:0xf bank_mask:0xf
	v_mov_b32_dpp v164, v11 quad_perm:[1,0,3,2] row_mask:0xf bank_mask:0xf
	v_mov_b32_dpp v165, v15 quad_perm:[1,0,3,2] row_mask:0xf bank_mask:0xf
	v_mov_b32_dpp v166, v19 quad_perm:[1,0,3,2] row_mask:0xf bank_mask:0xf
	v_mov_b32_dpp v167, v23 quad_perm:[1,0,3,2] row_mask:0xf bank_mask:0xf
	v_mov_b32_dpp v168, v27 quad_perm:[1,0,3,2] row_mask:0xf bank_mask:0xf
	v_mov_b32_dpp v169, v31 quad_perm:[1,0,3,2] row_mask:0xf bank_mask:0xf
	v_mov_b32_dpp v170, v35 quad_perm:[1,0,3,2] row_mask:0xf bank_mask:0xf
	v_mov_b32_dpp v171, v39 quad_perm:[1,0,3,2] row_mask:0xf bank_mask:0xf
	v_mov_b32_dpp v172, v43 quad_perm:[1,0,3,2] row_mask:0xf bank_mask:0xf
	v_mov_b32_dpp v173, v47 quad_perm:[1,0,3,2] row_mask:0xf bank_mask:0xf
	v_mov_b32_dpp v174, v51 quad_perm:[1,0,3,2] row_mask:0xf bank_mask:0xf
	v_mov_b32_dpp v175, v55 quad_perm:[1,0,3,2] row_mask:0xf bank_mask:0xf
	v_mov_b32_dpp v176, v59 quad_perm:[1,0,3,2] row_mask:0xf bank_mask:0xf
	v_mov_b32_dpp v177, v63 quad_perm:[1,0,3,2] row_mask:0xf bank_mask:0xf
	v_cvt_pk_bf16_f32 v3, v3, v162
	v_cvt_pk_bf16_f32 v7, v7, v163
	v_cvt_pk_bf16_f32 v11, v11, v164
	v_cvt_pk_bf16_f32 v15, v15, v165
	v_cvt_pk_bf16_f32 v19, v19, v166
	v_cvt_pk_bf16_f32 v23, v23, v167
	v_cvt_pk_bf16_f32 v27, v27, v168
	v_cvt_pk_bf16_f32 v31, v31, v169
	v_cvt_pk_bf16_f32 v35, v35, v170
	v_cvt_pk_bf16_f32 v39, v39, v171
	v_cvt_pk_bf16_f32 v43, v43, v172
	v_cvt_pk_bf16_f32 v47, v47, v173
	v_cvt_pk_bf16_f32 v51, v51, v174
	v_cvt_pk_bf16_f32 v55, v55, v175
	v_cvt_pk_bf16_f32 v59, v59, v176
	v_cvt_pk_bf16_f32 v63, v63, v177
	s_mov_b64 exec, s[76:77]
	global_store_dword v205, v3, s[30:31] offset:0
	global_store_dword v205, v7, s[30:31] offset:32
	global_store_dword v205, v11, s[30:31] offset:64
	global_store_dword v205, v15, s[30:31] offset:96
	global_store_dword v205, v19, s[30:31] offset:128
	global_store_dword v205, v23, s[30:31] offset:160
	global_store_dword v205, v27, s[30:31] offset:192
	global_store_dword v205, v31, s[30:31] offset:224
	global_store_dword v205, v35, s[30:31] offset:256
	global_store_dword v205, v39, s[30:31] offset:288
	global_store_dword v205, v43, s[30:31] offset:320
	global_store_dword v205, v47, s[30:31] offset:352
	global_store_dword v205, v51, s[30:31] offset:384
	global_store_dword v205, v55, s[30:31] offset:416
	global_store_dword v205, v59, s[30:31] offset:448
	global_store_dword v205, v63, s[30:31] offset:480
	s_mov_b64 exec, -1
	v_add_u32_e32 v205, 0x2000, v204
	v_mul_f32_e32 v4, v4, v148
	v_mul_f32_e32 v8, v8, v148
	v_mul_f32_e32 v12, v12, v148
	v_mul_f32_e32 v16, v16, v148
	v_mul_f32_e32 v20, v20, v148
	v_mul_f32_e32 v24, v24, v148
	v_mul_f32_e32 v28, v28, v148
	v_mul_f32_e32 v32, v32, v148
	v_mul_f32_e32 v36, v36, v148
	v_mul_f32_e32 v40, v40, v148
	v_mul_f32_e32 v44, v44, v148
	v_mul_f32_e32 v48, v48, v148
	v_mul_f32_e32 v52, v52, v148
	v_mul_f32_e32 v56, v56, v148
	v_mul_f32_e32 v60, v60, v148
	v_mul_f32_e32 v64, v64, v148
	v_mov_b32_dpp v162, v4 quad_perm:[1,0,3,2] row_mask:0xf bank_mask:0xf
	v_mov_b32_dpp v163, v8 quad_perm:[1,0,3,2] row_mask:0xf bank_mask:0xf
	v_mov_b32_dpp v164, v12 quad_perm:[1,0,3,2] row_mask:0xf bank_mask:0xf
	v_mov_b32_dpp v165, v16 quad_perm:[1,0,3,2] row_mask:0xf bank_mask:0xf
	v_mov_b32_dpp v166, v20 quad_perm:[1,0,3,2] row_mask:0xf bank_mask:0xf
	v_mov_b32_dpp v167, v24 quad_perm:[1,0,3,2] row_mask:0xf bank_mask:0xf
	v_mov_b32_dpp v168, v28 quad_perm:[1,0,3,2] row_mask:0xf bank_mask:0xf
	v_mov_b32_dpp v169, v32 quad_perm:[1,0,3,2] row_mask:0xf bank_mask:0xf
	v_mov_b32_dpp v170, v36 quad_perm:[1,0,3,2] row_mask:0xf bank_mask:0xf
	v_mov_b32_dpp v171, v40 quad_perm:[1,0,3,2] row_mask:0xf bank_mask:0xf
	v_mov_b32_dpp v172, v44 quad_perm:[1,0,3,2] row_mask:0xf bank_mask:0xf
	v_mov_b32_dpp v173, v48 quad_perm:[1,0,3,2] row_mask:0xf bank_mask:0xf
	v_mov_b32_dpp v174, v52 quad_perm:[1,0,3,2] row_mask:0xf bank_mask:0xf
	v_mov_b32_dpp v175, v56 quad_perm:[1,0,3,2] row_mask:0xf bank_mask:0xf
	v_mov_b32_dpp v176, v60 quad_perm:[1,0,3,2] row_mask:0xf bank_mask:0xf
	v_mov_b32_dpp v177, v64 quad_perm:[1,0,3,2] row_mask:0xf bank_mask:0xf
	v_cvt_pk_bf16_f32 v4, v4, v162
	v_cvt_pk_bf16_f32 v8, v8, v163
	v_cvt_pk_bf16_f32 v12, v12, v164
	v_cvt_pk_bf16_f32 v16, v16, v165
	v_cvt_pk_bf16_f32 v20, v20, v166
	v_cvt_pk_bf16_f32 v24, v24, v167
	v_cvt_pk_bf16_f32 v28, v28, v168
	v_cvt_pk_bf16_f32 v32, v32, v169
	v_cvt_pk_bf16_f32 v36, v36, v170
	v_cvt_pk_bf16_f32 v40, v40, v171
	v_cvt_pk_bf16_f32 v44, v44, v172
	v_cvt_pk_bf16_f32 v48, v48, v173
	v_cvt_pk_bf16_f32 v52, v52, v174
	v_cvt_pk_bf16_f32 v56, v56, v175
	v_cvt_pk_bf16_f32 v60, v60, v176
	v_cvt_pk_bf16_f32 v64, v64, v177
	s_mov_b64 exec, s[76:77]
	global_store_dword v205, v4, s[30:31] offset:0
	global_store_dword v205, v8, s[30:31] offset:32
	global_store_dword v205, v12, s[30:31] offset:64
	global_store_dword v205, v16, s[30:31] offset:96
	global_store_dword v205, v20, s[30:31] offset:128
	global_store_dword v205, v24, s[30:31] offset:160
	global_store_dword v205, v28, s[30:31] offset:192
	global_store_dword v205, v32, s[30:31] offset:224
	global_store_dword v205, v36, s[30:31] offset:256
	global_store_dword v205, v40, s[30:31] offset:288
	global_store_dword v205, v44, s[30:31] offset:320
	global_store_dword v205, v48, s[30:31] offset:352
	global_store_dword v205, v52, s[30:31] offset:384
	global_store_dword v205, v56, s[30:31] offset:416
	global_store_dword v205, v60, s[30:31] offset:448
	global_store_dword v205, v64, s[30:31] offset:480
	s_mov_b64 exec, -1
	v_add_u32_e32 v205, 0x3000, v204
	v_mul_f32_e32 v5, v5, v149
	v_mul_f32_e32 v9, v9, v149
	v_mul_f32_e32 v13, v13, v149
	v_mul_f32_e32 v17, v17, v149
	v_mul_f32_e32 v21, v21, v149
	v_mul_f32_e32 v25, v25, v149
	v_mul_f32_e32 v29, v29, v149
	v_mul_f32_e32 v33, v33, v149
	v_mul_f32_e32 v37, v37, v149
	v_mul_f32_e32 v41, v41, v149
	v_mul_f32_e32 v45, v45, v149
	v_mul_f32_e32 v49, v49, v149
	v_mul_f32_e32 v53, v53, v149
	v_mul_f32_e32 v57, v57, v149
	v_mul_f32_e32 v61, v61, v149
	v_mul_f32_e32 v65, v65, v149
	v_mov_b32_dpp v162, v5 quad_perm:[1,0,3,2] row_mask:0xf bank_mask:0xf
	v_mov_b32_dpp v163, v9 quad_perm:[1,0,3,2] row_mask:0xf bank_mask:0xf
	v_mov_b32_dpp v164, v13 quad_perm:[1,0,3,2] row_mask:0xf bank_mask:0xf
	v_mov_b32_dpp v165, v17 quad_perm:[1,0,3,2] row_mask:0xf bank_mask:0xf
	v_mov_b32_dpp v166, v21 quad_perm:[1,0,3,2] row_mask:0xf bank_mask:0xf
	v_mov_b32_dpp v167, v25 quad_perm:[1,0,3,2] row_mask:0xf bank_mask:0xf
	v_mov_b32_dpp v168, v29 quad_perm:[1,0,3,2] row_mask:0xf bank_mask:0xf
	v_mov_b32_dpp v169, v33 quad_perm:[1,0,3,2] row_mask:0xf bank_mask:0xf
	v_mov_b32_dpp v170, v37 quad_perm:[1,0,3,2] row_mask:0xf bank_mask:0xf
	v_mov_b32_dpp v171, v41 quad_perm:[1,0,3,2] row_mask:0xf bank_mask:0xf
	v_mov_b32_dpp v172, v45 quad_perm:[1,0,3,2] row_mask:0xf bank_mask:0xf
	v_mov_b32_dpp v173, v49 quad_perm:[1,0,3,2] row_mask:0xf bank_mask:0xf
	v_mov_b32_dpp v174, v53 quad_perm:[1,0,3,2] row_mask:0xf bank_mask:0xf
	v_mov_b32_dpp v175, v57 quad_perm:[1,0,3,2] row_mask:0xf bank_mask:0xf
	v_mov_b32_dpp v176, v61 quad_perm:[1,0,3,2] row_mask:0xf bank_mask:0xf
	v_mov_b32_dpp v177, v65 quad_perm:[1,0,3,2] row_mask:0xf bank_mask:0xf
	v_cvt_pk_bf16_f32 v5, v5, v162
	v_cvt_pk_bf16_f32 v9, v9, v163
	v_cvt_pk_bf16_f32 v13, v13, v164
	v_cvt_pk_bf16_f32 v17, v17, v165
	v_cvt_pk_bf16_f32 v21, v21, v166
	v_cvt_pk_bf16_f32 v25, v25, v167
	v_cvt_pk_bf16_f32 v29, v29, v168
	v_cvt_pk_bf16_f32 v33, v33, v169
	v_cvt_pk_bf16_f32 v37, v37, v170
	v_cvt_pk_bf16_f32 v41, v41, v171
	v_cvt_pk_bf16_f32 v45, v45, v172
	v_cvt_pk_bf16_f32 v49, v49, v173
	v_cvt_pk_bf16_f32 v53, v53, v174
	v_cvt_pk_bf16_f32 v57, v57, v175
	v_cvt_pk_bf16_f32 v61, v61, v176
	v_cvt_pk_bf16_f32 v65, v65, v177
	s_mov_b64 exec, s[76:77]
	global_store_dword v205, v5, s[30:31] offset:0
	global_store_dword v205, v9, s[30:31] offset:32
	global_store_dword v205, v13, s[30:31] offset:64
	global_store_dword v205, v17, s[30:31] offset:96
	global_store_dword v205, v21, s[30:31] offset:128
	global_store_dword v205, v25, s[30:31] offset:160
	global_store_dword v205, v29, s[30:31] offset:192
	global_store_dword v205, v33, s[30:31] offset:224
	global_store_dword v205, v37, s[30:31] offset:256
	global_store_dword v205, v41, s[30:31] offset:288
	global_store_dword v205, v45, s[30:31] offset:320
	global_store_dword v205, v49, s[30:31] offset:352
	global_store_dword v205, v53, s[30:31] offset:384
	global_store_dword v205, v57, s[30:31] offset:416
	global_store_dword v205, v61, s[30:31] offset:448
	global_store_dword v205, v65, s[30:31] offset:480
	s_mov_b64 exec, -1
	v_add_u32_e32 v205, 0x10000, v204
	v_mul_f32_e32 v66, v66, v150
	v_mul_f32_e32 v70, v70, v150
	v_mul_f32_e32 v74, v74, v150
	v_mul_f32_e32 v78, v78, v150
	v_mul_f32_e32 v82, v82, v150
	v_mul_f32_e32 v86, v86, v150
	v_mul_f32_e32 v90, v90, v150
	v_mul_f32_e32 v94, v94, v150
	v_mul_f32_e32 v98, v98, v150
	v_mul_f32_e32 v102, v102, v150
	v_mul_f32_e32 v106, v106, v150
	v_mul_f32_e32 v110, v110, v150
	v_mul_f32_e32 v114, v114, v150
	v_mul_f32_e32 v118, v118, v150
	v_mul_f32_e32 v122, v122, v150
	v_mul_f32_e32 v126, v126, v150
	v_mov_b32_dpp v162, v66 quad_perm:[1,0,3,2] row_mask:0xf bank_mask:0xf
	v_mov_b32_dpp v163, v70 quad_perm:[1,0,3,2] row_mask:0xf bank_mask:0xf
	v_mov_b32_dpp v164, v74 quad_perm:[1,0,3,2] row_mask:0xf bank_mask:0xf
	v_mov_b32_dpp v165, v78 quad_perm:[1,0,3,2] row_mask:0xf bank_mask:0xf
	v_mov_b32_dpp v166, v82 quad_perm:[1,0,3,2] row_mask:0xf bank_mask:0xf
	v_mov_b32_dpp v167, v86 quad_perm:[1,0,3,2] row_mask:0xf bank_mask:0xf
	v_mov_b32_dpp v168, v90 quad_perm:[1,0,3,2] row_mask:0xf bank_mask:0xf
	v_mov_b32_dpp v169, v94 quad_perm:[1,0,3,2] row_mask:0xf bank_mask:0xf
	v_mov_b32_dpp v170, v98 quad_perm:[1,0,3,2] row_mask:0xf bank_mask:0xf
	v_mov_b32_dpp v171, v102 quad_perm:[1,0,3,2] row_mask:0xf bank_mask:0xf
	v_mov_b32_dpp v172, v106 quad_perm:[1,0,3,2] row_mask:0xf bank_mask:0xf
	v_mov_b32_dpp v173, v110 quad_perm:[1,0,3,2] row_mask:0xf bank_mask:0xf
	v_mov_b32_dpp v174, v114 quad_perm:[1,0,3,2] row_mask:0xf bank_mask:0xf
	v_mov_b32_dpp v175, v118 quad_perm:[1,0,3,2] row_mask:0xf bank_mask:0xf
	v_mov_b32_dpp v176, v122 quad_perm:[1,0,3,2] row_mask:0xf bank_mask:0xf
	v_mov_b32_dpp v177, v126 quad_perm:[1,0,3,2] row_mask:0xf bank_mask:0xf
	v_cvt_pk_bf16_f32 v66, v66, v162
	v_cvt_pk_bf16_f32 v70, v70, v163
	v_cvt_pk_bf16_f32 v74, v74, v164
	v_cvt_pk_bf16_f32 v78, v78, v165
	v_cvt_pk_bf16_f32 v82, v82, v166
	v_cvt_pk_bf16_f32 v86, v86, v167
	v_cvt_pk_bf16_f32 v90, v90, v168
	v_cvt_pk_bf16_f32 v94, v94, v169
	v_cvt_pk_bf16_f32 v98, v98, v170
	v_cvt_pk_bf16_f32 v102, v102, v171
	v_cvt_pk_bf16_f32 v106, v106, v172
	v_cvt_pk_bf16_f32 v110, v110, v173
	v_cvt_pk_bf16_f32 v114, v114, v174
	v_cvt_pk_bf16_f32 v118, v118, v175
	v_cvt_pk_bf16_f32 v122, v122, v176
	v_cvt_pk_bf16_f32 v126, v126, v177
	s_mov_b64 exec, s[76:77]
	global_store_dword v205, v66, s[30:31] offset:0
	global_store_dword v205, v70, s[30:31] offset:32
	global_store_dword v205, v74, s[30:31] offset:64
	global_store_dword v205, v78, s[30:31] offset:96
	global_store_dword v205, v82, s[30:31] offset:128
	global_store_dword v205, v86, s[30:31] offset:160
	global_store_dword v205, v90, s[30:31] offset:192
	global_store_dword v205, v94, s[30:31] offset:224
	global_store_dword v205, v98, s[30:31] offset:256
	global_store_dword v205, v102, s[30:31] offset:288
	global_store_dword v205, v106, s[30:31] offset:320
	global_store_dword v205, v110, s[30:31] offset:352
	global_store_dword v205, v114, s[30:31] offset:384
	global_store_dword v205, v118, s[30:31] offset:416
	global_store_dword v205, v122, s[30:31] offset:448
	global_store_dword v205, v126, s[30:31] offset:480
	s_mov_b64 exec, -1
	v_add_u32_e32 v205, 0x11000, v204
	v_mul_f32_e32 v67, v67, v151
	v_mul_f32_e32 v71, v71, v151
	v_mul_f32_e32 v75, v75, v151
	v_mul_f32_e32 v79, v79, v151
	v_mul_f32_e32 v83, v83, v151
	v_mul_f32_e32 v87, v87, v151
	v_mul_f32_e32 v91, v91, v151
	v_mul_f32_e32 v95, v95, v151
	v_mul_f32_e32 v99, v99, v151
	v_mul_f32_e32 v103, v103, v151
	v_mul_f32_e32 v107, v107, v151
	v_mul_f32_e32 v111, v111, v151
	v_mul_f32_e32 v115, v115, v151
	v_mul_f32_e32 v119, v119, v151
	v_mul_f32_e32 v123, v123, v151
	v_mul_f32_e32 v127, v127, v151
	v_mov_b32_dpp v162, v67 quad_perm:[1,0,3,2] row_mask:0xf bank_mask:0xf
	v_mov_b32_dpp v163, v71 quad_perm:[1,0,3,2] row_mask:0xf bank_mask:0xf
	v_mov_b32_dpp v164, v75 quad_perm:[1,0,3,2] row_mask:0xf bank_mask:0xf
	v_mov_b32_dpp v165, v79 quad_perm:[1,0,3,2] row_mask:0xf bank_mask:0xf
	v_mov_b32_dpp v166, v83 quad_perm:[1,0,3,2] row_mask:0xf bank_mask:0xf
	v_mov_b32_dpp v167, v87 quad_perm:[1,0,3,2] row_mask:0xf bank_mask:0xf
	v_mov_b32_dpp v168, v91 quad_perm:[1,0,3,2] row_mask:0xf bank_mask:0xf
	v_mov_b32_dpp v169, v95 quad_perm:[1,0,3,2] row_mask:0xf bank_mask:0xf
	v_mov_b32_dpp v170, v99 quad_perm:[1,0,3,2] row_mask:0xf bank_mask:0xf
	v_mov_b32_dpp v171, v103 quad_perm:[1,0,3,2] row_mask:0xf bank_mask:0xf
	v_mov_b32_dpp v172, v107 quad_perm:[1,0,3,2] row_mask:0xf bank_mask:0xf
	v_mov_b32_dpp v173, v111 quad_perm:[1,0,3,2] row_mask:0xf bank_mask:0xf
	v_mov_b32_dpp v174, v115 quad_perm:[1,0,3,2] row_mask:0xf bank_mask:0xf
	v_mov_b32_dpp v175, v119 quad_perm:[1,0,3,2] row_mask:0xf bank_mask:0xf
	v_mov_b32_dpp v176, v123 quad_perm:[1,0,3,2] row_mask:0xf bank_mask:0xf
	v_mov_b32_dpp v177, v127 quad_perm:[1,0,3,2] row_mask:0xf bank_mask:0xf
	v_cvt_pk_bf16_f32 v67, v67, v162
	v_cvt_pk_bf16_f32 v71, v71, v163
	v_cvt_pk_bf16_f32 v75, v75, v164
	v_cvt_pk_bf16_f32 v79, v79, v165
	v_cvt_pk_bf16_f32 v83, v83, v166
	v_cvt_pk_bf16_f32 v87, v87, v167
	v_cvt_pk_bf16_f32 v91, v91, v168
	v_cvt_pk_bf16_f32 v95, v95, v169
	v_cvt_pk_bf16_f32 v99, v99, v170
	v_cvt_pk_bf16_f32 v103, v103, v171
	v_cvt_pk_bf16_f32 v107, v107, v172
	v_cvt_pk_bf16_f32 v111, v111, v173
	v_cvt_pk_bf16_f32 v115, v115, v174
	v_cvt_pk_bf16_f32 v119, v119, v175
	v_cvt_pk_bf16_f32 v123, v123, v176
	v_cvt_pk_bf16_f32 v127, v127, v177
	s_mov_b64 exec, s[76:77]
	global_store_dword v205, v67, s[30:31] offset:0
	global_store_dword v205, v71, s[30:31] offset:32
	global_store_dword v205, v75, s[30:31] offset:64
	global_store_dword v205, v79, s[30:31] offset:96
	global_store_dword v205, v83, s[30:31] offset:128
	global_store_dword v205, v87, s[30:31] offset:160
	global_store_dword v205, v91, s[30:31] offset:192
	global_store_dword v205, v95, s[30:31] offset:224
	global_store_dword v205, v99, s[30:31] offset:256
	global_store_dword v205, v103, s[30:31] offset:288
	global_store_dword v205, v107, s[30:31] offset:320
	global_store_dword v205, v111, s[30:31] offset:352
	global_store_dword v205, v115, s[30:31] offset:384
	global_store_dword v205, v119, s[30:31] offset:416
	global_store_dword v205, v123, s[30:31] offset:448
	global_store_dword v205, v127, s[30:31] offset:480
	s_mov_b64 exec, -1
	v_add_u32_e32 v205, 0x12000, v204
	v_mul_f32_e32 v68, v68, v152
	v_mul_f32_e32 v72, v72, v152
	v_mul_f32_e32 v76, v76, v152
	v_mul_f32_e32 v80, v80, v152
	v_mul_f32_e32 v84, v84, v152
	v_mul_f32_e32 v88, v88, v152
	v_mul_f32_e32 v92, v92, v152
	v_mul_f32_e32 v96, v96, v152
	v_mul_f32_e32 v100, v100, v152
	v_mul_f32_e32 v104, v104, v152
	v_mul_f32_e32 v108, v108, v152
	v_mul_f32_e32 v112, v112, v152
	v_mul_f32_e32 v116, v116, v152
	v_mul_f32_e32 v120, v120, v152
	v_mul_f32_e32 v124, v124, v152
	v_mul_f32_e32 v128, v128, v152
	v_mov_b32_dpp v162, v68 quad_perm:[1,0,3,2] row_mask:0xf bank_mask:0xf
	v_mov_b32_dpp v163, v72 quad_perm:[1,0,3,2] row_mask:0xf bank_mask:0xf
	v_mov_b32_dpp v164, v76 quad_perm:[1,0,3,2] row_mask:0xf bank_mask:0xf
	v_mov_b32_dpp v165, v80 quad_perm:[1,0,3,2] row_mask:0xf bank_mask:0xf
	v_mov_b32_dpp v166, v84 quad_perm:[1,0,3,2] row_mask:0xf bank_mask:0xf
	v_mov_b32_dpp v167, v88 quad_perm:[1,0,3,2] row_mask:0xf bank_mask:0xf
	v_mov_b32_dpp v168, v92 quad_perm:[1,0,3,2] row_mask:0xf bank_mask:0xf
	v_mov_b32_dpp v169, v96 quad_perm:[1,0,3,2] row_mask:0xf bank_mask:0xf
	v_mov_b32_dpp v170, v100 quad_perm:[1,0,3,2] row_mask:0xf bank_mask:0xf
	v_mov_b32_dpp v171, v104 quad_perm:[1,0,3,2] row_mask:0xf bank_mask:0xf
	v_mov_b32_dpp v172, v108 quad_perm:[1,0,3,2] row_mask:0xf bank_mask:0xf
	v_mov_b32_dpp v173, v112 quad_perm:[1,0,3,2] row_mask:0xf bank_mask:0xf
	v_mov_b32_dpp v174, v116 quad_perm:[1,0,3,2] row_mask:0xf bank_mask:0xf
	v_mov_b32_dpp v175, v120 quad_perm:[1,0,3,2] row_mask:0xf bank_mask:0xf
	v_mov_b32_dpp v176, v124 quad_perm:[1,0,3,2] row_mask:0xf bank_mask:0xf
	v_mov_b32_dpp v177, v128 quad_perm:[1,0,3,2] row_mask:0xf bank_mask:0xf
	v_cvt_pk_bf16_f32 v68, v68, v162
	v_cvt_pk_bf16_f32 v72, v72, v163
	v_cvt_pk_bf16_f32 v76, v76, v164
	v_cvt_pk_bf16_f32 v80, v80, v165
	v_cvt_pk_bf16_f32 v84, v84, v166
	v_cvt_pk_bf16_f32 v88, v88, v167
	v_cvt_pk_bf16_f32 v92, v92, v168
	v_cvt_pk_bf16_f32 v96, v96, v169
	v_cvt_pk_bf16_f32 v100, v100, v170
	v_cvt_pk_bf16_f32 v104, v104, v171
	v_cvt_pk_bf16_f32 v108, v108, v172
	v_cvt_pk_bf16_f32 v112, v112, v173
	v_cvt_pk_bf16_f32 v116, v116, v174
	v_cvt_pk_bf16_f32 v120, v120, v175
	v_cvt_pk_bf16_f32 v124, v124, v176
	v_cvt_pk_bf16_f32 v128, v128, v177
	s_mov_b64 exec, s[76:77]
	global_store_dword v205, v68, s[30:31] offset:0
	global_store_dword v205, v72, s[30:31] offset:32
	global_store_dword v205, v76, s[30:31] offset:64
	global_store_dword v205, v80, s[30:31] offset:96
	global_store_dword v205, v84, s[30:31] offset:128
	global_store_dword v205, v88, s[30:31] offset:160
	global_store_dword v205, v92, s[30:31] offset:192
	global_store_dword v205, v96, s[30:31] offset:224
	global_store_dword v205, v100, s[30:31] offset:256
	global_store_dword v205, v104, s[30:31] offset:288
	global_store_dword v205, v108, s[30:31] offset:320
	global_store_dword v205, v112, s[30:31] offset:352
	global_store_dword v205, v116, s[30:31] offset:384
	global_store_dword v205, v120, s[30:31] offset:416
	global_store_dword v205, v124, s[30:31] offset:448
	global_store_dword v205, v128, s[30:31] offset:480
	s_mov_b64 exec, -1
	v_add_u32_e32 v205, 0x13000, v204
	v_mul_f32_e32 v69, v69, v153
	v_mul_f32_e32 v73, v73, v153
	v_mul_f32_e32 v77, v77, v153
	v_mul_f32_e32 v81, v81, v153
	v_mul_f32_e32 v85, v85, v153
	v_mul_f32_e32 v89, v89, v153
	v_mul_f32_e32 v93, v93, v153
	v_mul_f32_e32 v97, v97, v153
	v_mul_f32_e32 v101, v101, v153
	v_mul_f32_e32 v105, v105, v153
	v_mul_f32_e32 v109, v109, v153
	v_mul_f32_e32 v113, v113, v153
	v_mul_f32_e32 v117, v117, v153
	v_mul_f32_e32 v121, v121, v153
	v_mul_f32_e32 v125, v125, v153
	v_mul_f32_e32 v129, v129, v153
	v_mov_b32_dpp v162, v69 quad_perm:[1,0,3,2] row_mask:0xf bank_mask:0xf
	v_mov_b32_dpp v163, v73 quad_perm:[1,0,3,2] row_mask:0xf bank_mask:0xf
	v_mov_b32_dpp v164, v77 quad_perm:[1,0,3,2] row_mask:0xf bank_mask:0xf
	v_mov_b32_dpp v165, v81 quad_perm:[1,0,3,2] row_mask:0xf bank_mask:0xf
	v_mov_b32_dpp v166, v85 quad_perm:[1,0,3,2] row_mask:0xf bank_mask:0xf
	v_mov_b32_dpp v167, v89 quad_perm:[1,0,3,2] row_mask:0xf bank_mask:0xf
	v_mov_b32_dpp v168, v93 quad_perm:[1,0,3,2] row_mask:0xf bank_mask:0xf
	v_mov_b32_dpp v169, v97 quad_perm:[1,0,3,2] row_mask:0xf bank_mask:0xf
	v_mov_b32_dpp v170, v101 quad_perm:[1,0,3,2] row_mask:0xf bank_mask:0xf
	v_mov_b32_dpp v171, v105 quad_perm:[1,0,3,2] row_mask:0xf bank_mask:0xf
	v_mov_b32_dpp v172, v109 quad_perm:[1,0,3,2] row_mask:0xf bank_mask:0xf
	v_mov_b32_dpp v173, v113 quad_perm:[1,0,3,2] row_mask:0xf bank_mask:0xf
	v_mov_b32_dpp v174, v117 quad_perm:[1,0,3,2] row_mask:0xf bank_mask:0xf
	v_mov_b32_dpp v175, v121 quad_perm:[1,0,3,2] row_mask:0xf bank_mask:0xf
	v_mov_b32_dpp v176, v125 quad_perm:[1,0,3,2] row_mask:0xf bank_mask:0xf
	v_mov_b32_dpp v177, v129 quad_perm:[1,0,3,2] row_mask:0xf bank_mask:0xf
	v_cvt_pk_bf16_f32 v69, v69, v162
	v_cvt_pk_bf16_f32 v73, v73, v163
	v_cvt_pk_bf16_f32 v77, v77, v164
	v_cvt_pk_bf16_f32 v81, v81, v165
	v_cvt_pk_bf16_f32 v85, v85, v166
	v_cvt_pk_bf16_f32 v89, v89, v167
	v_cvt_pk_bf16_f32 v93, v93, v168
	v_cvt_pk_bf16_f32 v97, v97, v169
	v_cvt_pk_bf16_f32 v101, v101, v170
	v_cvt_pk_bf16_f32 v105, v105, v171
	v_cvt_pk_bf16_f32 v109, v109, v172
	v_cvt_pk_bf16_f32 v113, v113, v173
	v_cvt_pk_bf16_f32 v117, v117, v174
	v_cvt_pk_bf16_f32 v121, v121, v175
	v_cvt_pk_bf16_f32 v125, v125, v176
	v_cvt_pk_bf16_f32 v129, v129, v177
	s_mov_b64 exec, s[76:77]
	global_store_dword v205, v69, s[30:31] offset:0
	global_store_dword v205, v73, s[30:31] offset:32
	global_store_dword v205, v77, s[30:31] offset:64
	global_store_dword v205, v81, s[30:31] offset:96
	global_store_dword v205, v85, s[30:31] offset:128
	global_store_dword v205, v89, s[30:31] offset:160
	global_store_dword v205, v93, s[30:31] offset:192
	global_store_dword v205, v97, s[30:31] offset:224
	global_store_dword v205, v101, s[30:31] offset:256
	global_store_dword v205, v105, s[30:31] offset:288
	global_store_dword v205, v109, s[30:31] offset:320
	global_store_dword v205, v113, s[30:31] offset:352
	global_store_dword v205, v117, s[30:31] offset:384
	global_store_dword v205, v121, s[30:31] offset:416
	global_store_dword v205, v125, s[30:31] offset:448
	global_store_dword v205, v129, s[30:31] offset:480
	s_mov_b64 exec, -1
	s_mov_b64 s[30:31], -1
	s_branch .LBB0_784

.LBB0_2403:
	v_readlane_b32 s10, v251, 42
	s_add_u32 s0, s48, s10
	v_readlane_b32 s4, v251, 43
	s_addc_u32 s1, s49, s4
	s_add_u32 s44, s0, 0x2000
	v_readlane_b32 s2, v251, 38
	s_addc_u32 s45, s1, 0
	s_lshl_b32 s2, s2, 1
	s_add_u32 s0, s0, s2
	s_addc_u32 s1, s1, 0
	s_add_u32 s8, s0, 0x2800
	v_readlane_b32 s0, v251, 8
	s_addc_u32 s9, s1, 0
	v_mbcnt_lo_u32_b32 v0, -1, 0
	v_mbcnt_hi_u32_b32 v0, -1, v0
	v_readlane_b32 s2, v251, 40
	v_add_u32_e32 v208, s0, v0
	s_mov_b64 s[0:1], s[68:69]
	s_load_dwordx2 s[0:1], s[0:1], 0x88
	s_lshl_b32 s2, s2, 1
	v_and_b32_e32 v2, 63, v0
	v_lshlrev_b32_e32 v5, 4, v0
	s_waitcnt lgkmcnt(0)
	v_lshlrev_b32_e32 v4, 3, v2
	s_add_u32 s0, s0, s2
	v_and_b32_e32 v6, 0xc0, v5
	v_lshlrev_b32_e32 v7, 1, v0
	s_addc_u32 s1, s1, 0
	v_and_or_b32 v6, v4, 24, v6
	v_and_b32_e32 v7, 32, v7
	v_and_b32_e32 v4, 0x100, v4
	v_bfe_u32 v212, v0, 4, 2
	s_add_u32 s46, s0, 0x37e00000
	v_bfe_u32 v1, v0, 5, 1
	v_or3_b32 v4, v6, v7, v4
	v_bitop3_b32 v7, v212, v0, 15 bitop3:0x78
	s_addc_u32 s47, s1, 0
	v_lshlrev_b32_e32 v210, 2, v1
	v_lshlrev_b32_e32 v213, 4, v7
	v_lshlrev_b32_e32 v7, 4, v1
	v_lshrrev_b32_e32 v1, 1, v0
	v_and_b32_e32 v209, 31, v0
	v_and_b32_e32 v215, 8, v1
	v_lshlrev_b32_e32 v1, 3, v0
	s_cmp_lg_u32 0, -1
	v_mul_u32_u24_e32 v3, 0x3000, v209
	v_and_b32_e32 v1, 24, v1
	s_cselect_b32 s2, 0, 0
	s_movk_i32 s0, 0x70
	v_and_b32_e32 v6, 15, v0
	v_or_b32_e32 v194, v7, v3
	v_bfe_u32 v214, v0, 2, 3
	v_and_or_b32 v216, v0, 32, v1
	v_add_u32_e32 v217, s2, v4
	v_lshlrev_b32_e32 v0, 8, v209
	v_and_b32_e32 v3, 0x70, v5
	s_add_i32 s1, s2, 0x10000
	v_bitop3_b32 v5, v7, v5, s0 bitop3:0x78
	s_movk_i32 s0, 0x60
	s_add_i32 s2, s2, 0x14000
	v_add_u32_e32 v4, s1, v0
	v_bitop3_b32 v8, v7, v3, 32 bitop3:0x36
	v_bitop3_b32 v9, v7, v3, 64 bitop3:0x36
	v_bitop3_b32 v3, v7, v3, s0 bitop3:0x36
	v_add_u32_e32 v0, s2, v0
	v_add_u32_e32 v222, v5, v0
	v_add_u32_e32 v223, v8, v0
	v_add_u32_e32 v224, v9, v0
	v_add_u32_e32 v225, v3, v0
	v_mul_u32_u24_e32 v0, 0x3000, v212
	s_movk_i32 s50, 0x3000
	v_mov_b32_e32 v1, 0
	v_cmp_gt_u32_e64 s[0:1], 32, v2
	s_add_u32 s6, s6, s10
	v_mov_b32_e32 v2, 0xc000
	v_or_b32_e32 v227, v0, v213
	v_bitop3_b32 v0, v212, v6, 4 bitop3:0x36
	v_sub_u32_e32 v211, v209, v210
	v_mov_b32_e32 v195, v1
	s_mov_b32 s51, 0
	v_add_u32_e32 v218, v5, v4
	v_add_u32_e32 v219, v8, v4
	v_add_u32_e32 v220, v9, v4
	v_add_u32_e32 v221, v3, v4
	s_addc_u32 s7, s7, s4
	v_mad_u32_u24 v226, v212, s50, v2
	v_lshlrev_b32_e32 v228, 4, v0
	v_mov_b32_e32 v229, 0x7ffffff3
	s_movk_i32 s52, 0x1800
	s_mov_b64 s[10:11], 0x100
	s_mov_b64 s[12:13], 0x180
	s_mov_b64 s[14:15], 0x1fec2000
	s_mov_b64 s[16:17], 0x1fec2800
	s_mov_b64 s[18:19], 0x1fec2880
	s_mov_b64 s[20:21], 0x1fec2900
	s_mov_b64 s[22:23], 0x1fec2980
	s_brev_b32 s53, -3
	s_mov_b32 s54, 0x41000000
	s_mov_b64 s[24:25], 0x1ff82000
	s_mov_b64 s[26:27], 0x1ff82800
	s_mov_b64 s[28:29], 0x1ff82880
	s_mov_b64 s[30:31], 0x1ff82900
	s_mov_b64 s[34:35], 0x1ff82980
	s_mov_b32 s55, 0x7fffe000
	v_mov_b32_e32 v230, 0xff800000
	s_waitcnt vmcnt(63) expcnt(7) lgkmcnt(15)
	v_mbcnt_lo_u32_b32 v238, -1, 0
	v_mbcnt_hi_u32_b32 v238, -1, v238
	v_and_b32_e32 v239, 15, v238
	v_lshrrev_b32_e32 v240, 4, v238
	v_and_b32_e32 v241, 3, v238
	v_bfe_u32 v242, v238, 2, 2
	v_lshrrev_b32_e32 v243, 1, v240
	v_lshlrev_b32_e32 v217, 12, v243
	v_and_b32_e32 v243, 1, v240
	v_lshl_or_b32 v217, v243, 7, v217
	v_lshl_or_b32 v217, v242, 5, v217
	v_lshl_or_b32 v217, v241, 3, v217
	v_xor_b32_e32 v243, v240, v241
	v_lshlrev_b32_e32 v218, 8, v239
	v_lshl_or_b32 v218, v243, 4, v218
	v_bfe_u32 v243, v238, 2, 1
	v_lshl_or_b32 v218, v243, 6, v218
	v_or_b32_e32 v218, 0x10000, v218
	v_xor_b32_e32 v219, 64, v218
	v_bfe_u32 v243, v238, 1, 3
	v_mul_u32_u24_e32 v220, 0x3000, v243
	v_lshl_or_b32 v220, v240, 5, v220
	v_and_b32_e32 v243, 1, v238
	v_lshl_or_b32 v220, v243, 4, v220
	v_lshlrev_b32_e32 v243, 2, v240
	v_sub_u32_e32 v221, v239, v243
	v_mul_u32_u24_e32 v194, 0x3000, v239
	v_lshl_or_b32 v194, v240, 4, v194
	v_add_u32_e32 v194, 0x1800, v194
	v_mov_b32_e32 v195, 0
	v_xor_b32_e32 v224, 16, v238
	v_lshlrev_b32_e32 v224, 2, v224
	v_cmp_gt_u32_e64 s[0:1], 16, v238
	s_barrier
	v_readlane_b32 s3, v251, 41
	s_branch .LBB0_2405

.LBB0_2405:
	s_lshr_b32 s56, s51, 1
	s_lshl_b32 s2, s56, 7
	v_readlane_b32 s3, v251, 38
	s_add_i32 s4, s3, s2
	s_lshl_b64 s[38:39], s[4:5], 1
	s_bitcmp0_b32 s51, 0
	v_readlane_b32 s2, v251, 34
	v_readlane_b32 s3, v251, 36
	s_cselect_b32 s3, s3, s2
	v_readlane_b32 s64, v251, 32
	s_or_b32 s2, s64, s3
	s_mul_hi_u32 s4, s2, 0x3000
	v_readlane_b32 s36, v251, 44
	s_add_i32 s4, s4, s36
	s_mul_i32 s36, s2, 0x3000
	s_add_u32 s36, s48, s36
	s_addc_u32 s4, s49, s4
	s_add_u32 s42, s36, s38
	s_addc_u32 s43, s4, s39
	s_add_u32 s40, s44, s38
	v_readfirstlane_b32 s4, v208
	s_addc_u32 s41, s45, s39
	s_ashr_i32 s60, s4, 6
	s_and_b32 s4, s4, 0x3fffffc0
	s_lshl_b32 s4, s4, 2
	s_lshl_b32 s37, s60, 3
	s_lshl_b32 s36, s60, 5
	s_add_i32 s4, s4, 0
	v_or_b32_e32 v0, s37, v212
	v_bitop3_b32 v7, s37, v229, v214 bitop3:0xc8
	s_lshl_b32 s37, s60, 2
	s_add_i32 s61, s4, 0x18000
	s_add_i32 s4, s36, s3
	s_and_b32 s62, s37, 4
	s_lshl_b32 s57, s60, 11
	s_lshl_b32 s58, s60, 12
	s_ashr_i32 s37, s36, 31
	s_mul_i32 s59, s60, 0x60000
	s_mul_hi_i32 s63, s36, 0x3000
	s_add_u32 s42, s42, s59
	v_or3_b32 v2, v215, v7, s62
	s_addc_u32 s43, s43, s63
	s_lshr_b32 s3, s3, 6
	v_mul_lo_u32 v2, v2, s52
	s_or_b32 s59, s3, 3
	v_or_b32_e32 v8, v2, v216
	v_lshl_add_u64 v[2:3], s[42:43], 0, v[194:195]
	s_mov_b64 s[42:43], 0x30000
	s_cmp_lg_u32 0, -1
	v_lshl_add_u64 v[4:5], v[2:3], 0, s[42:43]
	s_movk_i32 s42, 0x1000
	s_cselect_b32 s3, 0, 0
	v_mul_lo_u32 v0, v0, s50
	s_add_i32 s42, s3, s57
	v_or_b32_e32 v6, v0, v213
	v_or_b32_e32 v0, v0, v228
	global_load_dwordx4 v[162:165], v[2:3], off
	global_load_dwordx4 v[166:169], v[2:3], off offset:64
	global_load_dwordx4 v[170:173], v[2:3], off offset:128
	global_load_dwordx4 v[174:177], v[2:3], off offset:192
	global_load_dwordx4 v[178:181], v[4:5], off
	global_load_dwordx4 v[182:185], v[4:5], off offset:64
	global_load_dwordx4 v[186:189], v[4:5], off offset:128
	global_load_dwordx4 v[190:193], v[4:5], off offset:192
	s_add_i32 m0, s42, 0x10000
	v_add_u32_e32 v0, 0xc000, v0
	global_load_lds_dwordx4 v6, s[40:41]
	s_add_i32 m0, s42, 0x10400
	s_add_i32 s3, s58, s3
	global_load_lds_dwordx4 v0, s[40:41]
	s_mul_i32 s73, s60, 0x18000
	v_add_u32_e32 v0, s73, v220
	v_lshl_add_u64 v[2:3], s[8:9], 0, v[0:1]
	s_mov_b32 m0, s3
	s_mov_b64 s[40:41], 0x80
	global_load_lds_dwordx4 v0, s[8:9]
	v_lshl_add_u64 v[4:5], v[2:3], 0, s[40:41]
	s_add_i32 m0, s3, 0x400
	v_add3_u32 v0, v215, v7, s62
	global_load_lds_dwordx4 v[4:5], off
	v_lshl_add_u64 v[4:5], v[2:3], 0, s[10:11]
	s_add_i32 m0, s3, 0x800
	v_lshl_add_u64 v[2:3], v[2:3], 0, s[12:13]
	global_load_lds_dwordx4 v[4:5], off
	s_add_i32 m0, s3, 0xc00
	v_mul_lo_u32 v0, v0, s52
	global_load_lds_dwordx4 v[2:3], off
	v_or_b32_e32 v0, v216, v0
	v_readlane_b32 s40, v251, 40
	v_lshlrev_b32_e32 v0, 1, v0
	v_readlane_b32 s41, v251, 41
	s_mul_i32 s60, s60, 0x18000
	v_mov_b32_e32 v14, v1
	v_add_u32_e32 v0, s60, v220
	v_lshl_add_u64 v[196:197], s[40:41], 0, v[0:1]
	v_add3_u32 v0, v226, s60, v228
	v_lshl_add_u64 v[198:199], s[38:39], 0, v[0:1]
	v_add_u32_e32 v0, s60, v227
	v_mov_b32_e32 v15, v1
	s_waitcnt vmcnt(0)
	v_lshl_add_u64 v[200:201], s[38:39], 0, v[0:1]
	v_mov_b32_e32 v0, v1
	v_mov_b32_e32 v2, v1
	v_mov_b32_e32 v3, v1
	v_mov_b32_e32 v4, v1
	v_mov_b32_e32 v5, v1
	v_mov_b32_e32 v6, v1
	v_mov_b32_e32 v7, v1
	v_mov_b32_e32 v8, v1
	v_mov_b32_e32 v9, v1
	v_mov_b32_e32 v10, v1
	v_mov_b32_e32 v11, v1
	v_mov_b32_e32 v12, v1
	v_mov_b32_e32 v13, v1
	s_waitcnt vmcnt(0)
	v_mov_b64_e32 v[128:129], v[14:15]
	v_mov_b64_e32 v[112:113], v[14:15]
	v_mov_b64_e32 v[96:97], v[14:15]
	v_mov_b64_e32 v[80:81], v[14:15]
	v_mov_b64_e32 v[64:65], v[14:15]
	v_mov_b64_e32 v[48:49], v[14:15]
	v_mov_b64_e32 v[32:33], v[14:15]
	v_readlane_b32 s65, v251, 33
	v_mov_b64_e32 v[126:127], v[12:13]
	v_mov_b64_e32 v[124:125], v[10:11]
	v_mov_b64_e32 v[122:123], v[8:9]
	v_mov_b64_e32 v[120:121], v[6:7]
	v_mov_b64_e32 v[118:119], v[4:5]
	v_mov_b64_e32 v[116:117], v[2:3]
	v_mov_b64_e32 v[114:115], v[0:1]
	v_mov_b64_e32 v[110:111], v[12:13]
	v_mov_b64_e32 v[108:109], v[10:11]
	v_mov_b64_e32 v[106:107], v[8:9]
	v_mov_b64_e32 v[104:105], v[6:7]
	v_mov_b64_e32 v[102:103], v[4:5]
	v_mov_b64_e32 v[100:101], v[2:3]
	v_mov_b64_e32 v[98:99], v[0:1]
	v_mov_b64_e32 v[94:95], v[12:13]
	v_mov_b64_e32 v[92:93], v[10:11]
	v_mov_b64_e32 v[90:91], v[8:9]
	v_mov_b64_e32 v[88:89], v[6:7]
	v_mov_b64_e32 v[86:87], v[4:5]
	v_mov_b64_e32 v[84:85], v[2:3]
	v_mov_b64_e32 v[82:83], v[0:1]
	v_mov_b64_e32 v[78:79], v[12:13]
	v_mov_b64_e32 v[76:77], v[10:11]
	v_mov_b64_e32 v[74:75], v[8:9]
	v_mov_b64_e32 v[72:73], v[6:7]
	v_mov_b64_e32 v[70:71], v[4:5]
	v_mov_b64_e32 v[68:69], v[2:3]
	v_mov_b64_e32 v[66:67], v[0:1]
	v_mov_b64_e32 v[62:63], v[12:13]
	v_mov_b64_e32 v[60:61], v[10:11]
	v_mov_b64_e32 v[58:59], v[8:9]
	v_mov_b64_e32 v[56:57], v[6:7]
	v_mov_b64_e32 v[54:55], v[4:5]
	v_mov_b64_e32 v[52:53], v[2:3]
	v_mov_b64_e32 v[50:51], v[0:1]
	v_mov_b64_e32 v[46:47], v[12:13]
	v_mov_b64_e32 v[44:45], v[10:11]
	v_mov_b64_e32 v[42:43], v[8:9]
	v_mov_b64_e32 v[40:41], v[6:7]
	v_mov_b64_e32 v[38:39], v[4:5]
	v_mov_b64_e32 v[36:37], v[2:3]
	v_mov_b64_e32 v[34:35], v[0:1]
	v_mov_b64_e32 v[30:31], v[12:13]
	v_mov_b64_e32 v[28:29], v[10:11]
	v_mov_b64_e32 v[26:27], v[8:9]
	v_mov_b64_e32 v[24:25], v[6:7]
	v_mov_b64_e32 v[22:23], v[4:5]
	v_mov_b64_e32 v[20:21], v[2:3]
	v_mov_b64_e32 v[18:19], v[0:1]
	v_mov_b64_e32 v[16:17], v[14:15]
	s_mov_b32 s3, s65
	v_add_u32_e32 v233, s4, v221
	v_and_b32_e32 v232, 15, v209
	v_lshl_add_u32 v232, v232, 2, s61
	v_lshl_add_u32 v231, v212, 4, s61
	v_mov_b32_e32 v237, 0xf149f2ca
	s_movk_i32 s60, 0x7f
	s_mov_b64 s[38:39], s[6:7]
	s_mov_b32 s61, 2
	v_mov_b64_e32 v[14:15], v[12:13]
	v_mov_b64_e32 v[12:13], v[10:11]
	v_mov_b64_e32 v[10:11], v[8:9]
	v_mov_b64_e32 v[8:9], v[6:7]
	v_mov_b64_e32 v[6:7], v[4:5]
	v_mov_b64_e32 v[4:5], v[2:3]
	v_mov_b64_e32 v[2:3], v[0:1]
	v_mov_b32_e32 v0, 0
	v_mov_b32_e32 v222, 0xf149f2ca
	v_mov_b32_e32 v223, 0
	s_waitcnt lgkmcnt(0)
	s_barrier
	s_branch .LBB0_2408
.Ld16c_bot:
	s_waitcnt vmcnt(0)
	s_add_i32 s61, s61, 2
	s_add_u32 s38, s38, 0x180000
	s_addc_u32 s39, s39, 0
	v_add_u32_e32 v233, 0xffffff80, v233
	s_addk_i32 s60, 0x80
	s_and_b64 vcc, exec, s[40:41]
	s_waitcnt vmcnt(0) lgkmcnt(0)
	s_barrier
	s_cbranch_vccnz .LBB0_2423

.LBB0_2410:
	ds_read_b128 v[238:241], v218 offset:0
	ds_read_b128 v[242:245], v219 offset:0
	ds_read_b128 v[246:249], v218 offset:128
	s_waitcnt lgkmcnt(2)
	v_mfma_f32_16x16x32_bf16 v[130:133], v[238:241], v[162:165], 0
	v_mfma_f32_16x16x32_bf16 v[146:149], v[238:241], v[178:181], 0
	ds_read_b128 v[238:241], v219 offset:128
	s_waitcnt lgkmcnt(2)
	v_mfma_f32_16x16x32_bf16 v[130:133], v[242:245], v[166:169], v[130:133]
	v_mfma_f32_16x16x32_bf16 v[146:149], v[242:245], v[182:185], v[146:149]
	ds_read_b128 v[242:245], v218 offset:4096
	s_waitcnt lgkmcnt(2)
	v_mfma_f32_16x16x32_bf16 v[130:133], v[246:249], v[170:173], v[130:133]
	v_mfma_f32_16x16x32_bf16 v[146:149], v[246:249], v[186:189], v[146:149]
	ds_read_b128 v[246:249], v219 offset:4096
	s_waitcnt lgkmcnt(2)
	v_mfma_f32_16x16x32_bf16 v[130:133], v[238:241], v[174:177], v[130:133]
	v_mfma_f32_16x16x32_bf16 v[146:149], v[238:241], v[190:193], v[146:149]
	ds_read_b128 v[238:241], v218 offset:4224
	s_waitcnt lgkmcnt(2)
	v_mfma_f32_16x16x32_bf16 v[134:137], v[242:245], v[162:165], 0
	v_mfma_f32_16x16x32_bf16 v[150:153], v[242:245], v[178:181], 0
	ds_read_b128 v[242:245], v219 offset:4224
	s_waitcnt lgkmcnt(2)
	v_mfma_f32_16x16x32_bf16 v[134:137], v[246:249], v[166:169], v[134:137]
	v_mfma_f32_16x16x32_bf16 v[150:153], v[246:249], v[182:185], v[150:153]
	ds_read_b128 v[246:249], v218 offset:8192
	s_waitcnt lgkmcnt(2)
	v_mfma_f32_16x16x32_bf16 v[134:137], v[238:241], v[170:173], v[134:137]
	v_mfma_f32_16x16x32_bf16 v[150:153], v[238:241], v[186:189], v[150:153]
	ds_read_b128 v[238:241], v219 offset:8192
	s_waitcnt lgkmcnt(2)
	v_mfma_f32_16x16x32_bf16 v[134:137], v[242:245], v[174:177], v[134:137]
	v_mfma_f32_16x16x32_bf16 v[150:153], v[242:245], v[190:193], v[150:153]
	ds_read_b128 v[242:245], v218 offset:8320
	s_waitcnt lgkmcnt(2)
	v_mfma_f32_16x16x32_bf16 v[138:141], v[246:249], v[162:165], 0
	v_mfma_f32_16x16x32_bf16 v[154:157], v[246:249], v[178:181], 0
	ds_read_b128 v[246:249], v219 offset:8320
	s_waitcnt lgkmcnt(2)
	v_mfma_f32_16x16x32_bf16 v[138:141], v[238:241], v[166:169], v[138:141]
	v_mfma_f32_16x16x32_bf16 v[154:157], v[238:241], v[182:185], v[154:157]
	ds_read_b128 v[238:241], v218 offset:12288
	s_waitcnt lgkmcnt(2)
	v_mfma_f32_16x16x32_bf16 v[138:141], v[242:245], v[170:173], v[138:141]
	v_mfma_f32_16x16x32_bf16 v[154:157], v[242:245], v[186:189], v[154:157]
	ds_read_b128 v[242:245], v219 offset:12288
	s_waitcnt lgkmcnt(2)
	v_mfma_f32_16x16x32_bf16 v[138:141], v[246:249], v[174:177], v[138:141]
	v_mfma_f32_16x16x32_bf16 v[154:157], v[246:249], v[190:193], v[154:157]
	ds_read_b128 v[246:249], v218 offset:12416
	s_waitcnt lgkmcnt(2)
	v_mfma_f32_16x16x32_bf16 v[142:145], v[238:241], v[162:165], 0
	v_mfma_f32_16x16x32_bf16 v[158:161], v[238:241], v[178:181], 0
	ds_read_b128 v[238:241], v219 offset:12416
	s_waitcnt lgkmcnt(2)
	v_mfma_f32_16x16x32_bf16 v[142:145], v[242:245], v[166:169], v[142:145]
	v_mfma_f32_16x16x32_bf16 v[158:161], v[242:245], v[182:185], v[158:161]
	s_waitcnt lgkmcnt(1)
	v_mfma_f32_16x16x32_bf16 v[142:145], v[246:249], v[170:173], v[142:145]
	v_mfma_f32_16x16x32_bf16 v[158:161], v[246:249], v[186:189], v[158:161]
	s_waitcnt lgkmcnt(0)
	v_mfma_f32_16x16x32_bf16 v[142:145], v[238:241], v[174:177], v[142:145]
	v_mfma_f32_16x16x32_bf16 v[158:161], v[238:241], v[190:193], v[158:161]
	s_nop 7
	s_nop 1
	s_sub_i32 s40, s60, 64
	s_cmp_le_i32 s40, s4
	s_cbranch_scc1 .Ld16c_nm0
	v_cmp_gt_i32_e64 s[74:75], 0, v233
	v_cmp_gt_i32_e64 s[76:77], 1, v233
	v_cmp_gt_i32_e64 s[78:79], 2, v233
	v_cmp_gt_i32_e64 s[80:81], 3, v233
	v_cndmask_b32_e64 v130, v130, v230, s[74:75]
	v_cndmask_b32_e64 v131, v131, v230, s[76:77]
	v_cndmask_b32_e64 v132, v132, v230, s[78:79]
	v_cndmask_b32_e64 v133, v133, v230, s[80:81]
	v_cmp_gt_i32_e64 s[74:75], 16, v233
	v_cmp_gt_i32_e64 s[76:77], 17, v233
	v_cmp_gt_i32_e64 s[78:79], 18, v233
	v_cmp_gt_i32_e64 s[80:81], 19, v233
	v_cndmask_b32_e64 v134, v134, v230, s[74:75]
	v_cndmask_b32_e64 v135, v135, v230, s[76:77]
	v_cndmask_b32_e64 v136, v136, v230, s[78:79]
	v_cndmask_b32_e64 v137, v137, v230, s[80:81]
	v_cmp_gt_i32_e64 s[74:75], 32, v233
	v_cmp_gt_i32_e64 s[76:77], 33, v233
	v_cmp_gt_i32_e64 s[78:79], 34, v233
	v_cmp_gt_i32_e64 s[80:81], 35, v233
	v_cndmask_b32_e64 v138, v138, v230, s[74:75]
	v_cndmask_b32_e64 v139, v139, v230, s[76:77]
	v_cndmask_b32_e64 v140, v140, v230, s[78:79]
	v_cndmask_b32_e64 v141, v141, v230, s[80:81]
	v_cmp_gt_i32_e64 s[74:75], 48, v233
	v_cmp_gt_i32_e64 s[76:77], 49, v233
	v_cmp_gt_i32_e64 s[78:79], 50, v233
	v_cmp_gt_i32_e64 s[80:81], 51, v233
	v_cndmask_b32_e64 v142, v142, v230, s[74:75]
	v_cndmask_b32_e64 v143, v143, v230, s[76:77]
	v_cndmask_b32_e64 v144, v144, v230, s[78:79]
	v_cndmask_b32_e64 v145, v145, v230, s[80:81]
	v_cmp_gt_i32_e64 s[74:75], -16, v233
	v_cmp_gt_i32_e64 s[76:77], -15, v233
	v_cmp_gt_i32_e64 s[78:79], -14, v233
	v_cmp_gt_i32_e64 s[80:81], -13, v233
	v_cndmask_b32_e64 v146, v146, v230, s[74:75]
	v_cndmask_b32_e64 v147, v147, v230, s[76:77]
	v_cndmask_b32_e64 v148, v148, v230, s[78:79]
	v_cndmask_b32_e64 v149, v149, v230, s[80:81]
	v_cmp_gt_i32_e64 s[74:75], 0, v233
	v_cmp_gt_i32_e64 s[76:77], 1, v233
	v_cmp_gt_i32_e64 s[78:79], 2, v233
	v_cmp_gt_i32_e64 s[80:81], 3, v233
	v_cndmask_b32_e64 v150, v150, v230, s[74:75]
	v_cndmask_b32_e64 v151, v151, v230, s[76:77]
	v_cndmask_b32_e64 v152, v152, v230, s[78:79]
	v_cndmask_b32_e64 v153, v153, v230, s[80:81]
	v_cmp_gt_i32_e64 s[74:75], 16, v233
	v_cmp_gt_i32_e64 s[76:77], 17, v233
	v_cmp_gt_i32_e64 s[78:79], 18, v233
	v_cmp_gt_i32_e64 s[80:81], 19, v233
	v_cndmask_b32_e64 v154, v154, v230, s[74:75]
	v_cndmask_b32_e64 v155, v155, v230, s[76:77]
	v_cndmask_b32_e64 v156, v156, v230, s[78:79]
	v_cndmask_b32_e64 v157, v157, v230, s[80:81]
	v_cmp_gt_i32_e64 s[74:75], 32, v233
	v_cmp_gt_i32_e64 s[76:77], 33, v233
	v_cmp_gt_i32_e64 s[78:79], 34, v233
	v_cmp_gt_i32_e64 s[80:81], 35, v233
	v_cndmask_b32_e64 v158, v158, v230, s[74:75]
	v_cndmask_b32_e64 v159, v159, v230, s[76:77]
	v_cndmask_b32_e64 v160, v160, v230, s[78:79]
	v_cndmask_b32_e64 v161, v161, v230, s[80:81]
.Ld16c_nm0:
	v_max3_f32 v234, v130, v131, v132
	v_max3_f32 v234, v234, v133, v134
	v_max3_f32 v234, v234, v135, v136
	v_max3_f32 v234, v234, v137, v138
	v_max3_f32 v234, v234, v139, v140
	v_max3_f32 v234, v234, v141, v142
	v_max3_f32 v234, v234, v143, v144
	v_max_f32_e32 v234, v234, v145
	v_max3_f32 v235, v146, v147, v148
	v_max3_f32 v235, v235, v149, v150
	v_max3_f32 v235, v235, v151, v152
	v_max3_f32 v235, v235, v153, v154
	v_max3_f32 v235, v235, v155, v156
	v_max3_f32 v235, v235, v157, v158
	v_max3_f32 v235, v235, v159, v160
	v_max_f32_e32 v235, v235, v161
	ds_bpermute_b32 v246, v224, v234
	ds_bpermute_b32 v247, v224, v235
	s_waitcnt lgkmcnt(0)
	v_max_f32_e32 v234, v234, v246
	v_max_f32_e32 v235, v235, v247
	v_mov_b32_e32 v246, v234
	v_mov_b32_e32 v247, v235
	s_nop 1
	v_permlane32_swap_b32_e32 v234, v246
	v_permlane32_swap_b32_e32 v235, v247
	v_max_f32_e32 v234, v234, v246
	v_max_f32_e32 v235, v235, v247
	v_sub_f32_e32 v246, v234, v237
	v_sub_f32_e32 v247, v235, v222
	v_max_f32_e32 v246, v246, v247
	v_mul_f32_e32 v246, 0x3db504f3, v246
	v_cmp_ge_f32_e32 vcc, s54, v246
	v_max_f32_e32 v234, v237, v234
	v_max_f32_e32 v235, v222, v235
	v_sub_f32_e32 v246, v237, v234
	v_sub_f32_e32 v247, v222, v235
	v_mul_f32_e32 v246, 0x3e0293ee, v246
	v_mul_f32_e32 v247, 0x3e0293ee, v247
	v_exp_f32_e32 v246, v246
	v_exp_f32_e32 v247, v247
	s_cmp_eq_u64 vcc, exec
	s_cselect_b64 vcc, -1, 0
	v_cndmask_b32_e32 v237, v234, v237, vcc
	v_cndmask_b32_e32 v222, v235, v222, vcc
	v_cndmask_b32_e64 v234, v246, 1.0, vcc
	v_cndmask_b32_e64 v235, v247, 1.0, vcc
	v_mul_f32_e32 v246, 0xbe0293ee, v237
	v_mul_f32_e32 v247, 0xbe0293ee, v222
	v_fmamk_f32 v130, v130, 0x3e0293ee, v246
	v_fmamk_f32 v131, v131, 0x3e0293ee, v246
	v_fmamk_f32 v132, v132, 0x3e0293ee, v246
	v_fmamk_f32 v133, v133, 0x3e0293ee, v246
	v_fmamk_f32 v134, v134, 0x3e0293ee, v246
	v_fmamk_f32 v135, v135, 0x3e0293ee, v246
	v_fmamk_f32 v136, v136, 0x3e0293ee, v246
	v_fmamk_f32 v137, v137, 0x3e0293ee, v246
	v_fmamk_f32 v138, v138, 0x3e0293ee, v246
	v_fmamk_f32 v139, v139, 0x3e0293ee, v246
	v_fmamk_f32 v140, v140, 0x3e0293ee, v246
	v_fmamk_f32 v141, v141, 0x3e0293ee, v246
	v_fmamk_f32 v142, v142, 0x3e0293ee, v246
	v_fmamk_f32 v143, v143, 0x3e0293ee, v246
	v_fmamk_f32 v144, v144, 0x3e0293ee, v246
	v_fmamk_f32 v145, v145, 0x3e0293ee, v246
	v_fmamk_f32 v146, v146, 0x3e0293ee, v247
	v_fmamk_f32 v147, v147, 0x3e0293ee, v247
	v_fmamk_f32 v148, v148, 0x3e0293ee, v247
	v_fmamk_f32 v149, v149, 0x3e0293ee, v247
	v_fmamk_f32 v150, v150, 0x3e0293ee, v247
	v_fmamk_f32 v151, v151, 0x3e0293ee, v247
	v_fmamk_f32 v152, v152, 0x3e0293ee, v247
	v_fmamk_f32 v153, v153, 0x3e0293ee, v247
	v_fmamk_f32 v154, v154, 0x3e0293ee, v247
	v_fmamk_f32 v155, v155, 0x3e0293ee, v247
	v_fmamk_f32 v156, v156, 0x3e0293ee, v247
	v_fmamk_f32 v157, v157, 0x3e0293ee, v247
	v_fmamk_f32 v158, v158, 0x3e0293ee, v247
	v_fmamk_f32 v159, v159, 0x3e0293ee, v247
	v_fmamk_f32 v160, v160, 0x3e0293ee, v247
	v_fmamk_f32 v161, v161, 0x3e0293ee, v247
	v_exp_f32_e32 v130, v130
	v_exp_f32_e32 v131, v131
	v_exp_f32_e32 v132, v132
	v_exp_f32_e32 v133, v133
	v_exp_f32_e32 v134, v134
	v_exp_f32_e32 v135, v135
	v_exp_f32_e32 v136, v136
	v_exp_f32_e32 v137, v137
	v_exp_f32_e32 v138, v138
	v_exp_f32_e32 v139, v139
	v_exp_f32_e32 v140, v140
	v_exp_f32_e32 v141, v141
	v_exp_f32_e32 v142, v142
	v_exp_f32_e32 v143, v143
	v_exp_f32_e32 v144, v144
	v_exp_f32_e32 v145, v145
	v_exp_f32_e32 v146, v146
	v_exp_f32_e32 v147, v147
	v_exp_f32_e32 v148, v148
	v_exp_f32_e32 v149, v149
	v_exp_f32_e32 v150, v150
	v_exp_f32_e32 v151, v151
	v_exp_f32_e32 v152, v152
	v_exp_f32_e32 v153, v153
	v_exp_f32_e32 v154, v154
	v_exp_f32_e32 v155, v155
	v_exp_f32_e32 v156, v156
	v_exp_f32_e32 v157, v157
	v_exp_f32_e32 v158, v158
	v_exp_f32_e32 v159, v159
	v_exp_f32_e32 v160, v160
	v_exp_f32_e32 v161, v161
	v_add_f32_e32 v248, v130, v131
	v_add_f32_e32 v249, v146, v147
	v_add_f32_e32 v248, v248, v132
	v_add_f32_e32 v249, v249, v148
	v_add_f32_e32 v248, v248, v133
	v_add_f32_e32 v249, v249, v149
	v_add_f32_e32 v248, v248, v134
	v_add_f32_e32 v249, v249, v150
	v_add_f32_e32 v248, v248, v135
	v_add_f32_e32 v249, v249, v151
	v_add_f32_e32 v248, v248, v136
	v_add_f32_e32 v249, v249, v152
	v_add_f32_e32 v248, v248, v137
	v_add_f32_e32 v249, v249, v153
	v_add_f32_e32 v248, v248, v138
	v_add_f32_e32 v249, v249, v154
	v_add_f32_e32 v248, v248, v139
	v_add_f32_e32 v249, v249, v155
	v_add_f32_e32 v248, v248, v140
	v_add_f32_e32 v249, v249, v156
	v_add_f32_e32 v248, v248, v141
	v_add_f32_e32 v249, v249, v157
	v_add_f32_e32 v248, v248, v142
	v_add_f32_e32 v249, v249, v158
	v_add_f32_e32 v248, v248, v143
	v_add_f32_e32 v249, v249, v159
	v_add_f32_e32 v248, v248, v144
	v_add_f32_e32 v249, v249, v160
	v_add_f32_e32 v248, v248, v145
	v_add_f32_e32 v249, v249, v161
	ds_bpermute_b32 v246, v224, v248
	ds_bpermute_b32 v247, v224, v249
	s_waitcnt lgkmcnt(0)
	v_add_f32_e32 v248, v248, v246
	v_add_f32_e32 v249, v249, v247
	v_mov_b32_e32 v246, v248
	v_mov_b32_e32 v247, v249
	s_nop 1
	v_permlane32_swap_b32_e32 v248, v246
	v_permlane32_swap_b32_e32 v249, v247
	v_add_f32_e32 v248, v248, v246
	v_add_f32_e32 v249, v249, v247
	v_fma_f32 v0, v0, v234, v248
	v_fma_f32 v223, v223, v235, v249
	v_cvt_pk_bf16_f32 v130, v130, v131
	v_cvt_pk_bf16_f32 v131, v132, v133
	v_cvt_pk_bf16_f32 v132, v134, v135
	v_cvt_pk_bf16_f32 v133, v136, v137
	v_cvt_pk_bf16_f32 v134, v138, v139
	v_cvt_pk_bf16_f32 v135, v140, v141
	v_cvt_pk_bf16_f32 v136, v142, v143
	v_cvt_pk_bf16_f32 v137, v144, v145
	v_cvt_pk_bf16_f32 v138, v146, v147
	v_cvt_pk_bf16_f32 v139, v148, v149
	v_cvt_pk_bf16_f32 v140, v150, v151
	v_cvt_pk_bf16_f32 v141, v152, v153
	v_cvt_pk_bf16_f32 v142, v154, v155
	v_cvt_pk_bf16_f32 v143, v156, v157
	v_cvt_pk_bf16_f32 v144, v158, v159
	v_cvt_pk_bf16_f32 v145, v160, v161
	v_min_f32_e32 v246, v234, v235
	v_cmp_gt_f32_e32 vcc, 1.0, v246
	s_cbranch_vccz .Ld16c_nr0
	s_and_saveexec_b64 s[76:77], s[0:1]
	ds_write_b32 v232, v234 offset:128
	ds_write_b32 v232, v235 offset:192
	s_or_b64 exec, exec, s[76:77]
	s_waitcnt lgkmcnt(0)
	ds_read_b128 v[146:149], v231 offset:128
	ds_read_b128 v[150:153], v231 offset:192
	s_waitcnt lgkmcnt(0)
	v_pk_mul_f32 v[2:3], v[2:3], v[146:147]
	v_pk_mul_f32 v[4:5], v[4:5], v[148:149]
	v_pk_mul_f32 v[6:7], v[6:7], v[146:147]
	v_pk_mul_f32 v[8:9], v[8:9], v[148:149]
	v_pk_mul_f32 v[10:11], v[10:11], v[146:147]
	v_pk_mul_f32 v[12:13], v[12:13], v[148:149]
	v_pk_mul_f32 v[14:15], v[14:15], v[146:147]
	v_pk_mul_f32 v[16:17], v[16:17], v[148:149]
	v_pk_mul_f32 v[18:19], v[18:19], v[146:147]
	v_pk_mul_f32 v[20:21], v[20:21], v[148:149]
	v_pk_mul_f32 v[22:23], v[22:23], v[146:147]
	v_pk_mul_f32 v[24:25], v[24:25], v[148:149]
	v_pk_mul_f32 v[26:27], v[26:27], v[146:147]
	v_pk_mul_f32 v[28:29], v[28:29], v[148:149]
	v_pk_mul_f32 v[30:31], v[30:31], v[146:147]
	v_pk_mul_f32 v[32:33], v[32:33], v[148:149]
	v_pk_mul_f32 v[34:35], v[34:35], v[146:147]
	v_pk_mul_f32 v[36:37], v[36:37], v[148:149]
	v_pk_mul_f32 v[38:39], v[38:39], v[146:147]
	v_pk_mul_f32 v[40:41], v[40:41], v[148:149]
	v_pk_mul_f32 v[42:43], v[42:43], v[146:147]
	v_pk_mul_f32 v[44:45], v[44:45], v[148:149]
	v_pk_mul_f32 v[46:47], v[46:47], v[146:147]
	v_pk_mul_f32 v[48:49], v[48:49], v[148:149]
	v_pk_mul_f32 v[50:51], v[50:51], v[146:147]
	v_pk_mul_f32 v[52:53], v[52:53], v[148:149]
	v_pk_mul_f32 v[54:55], v[54:55], v[146:147]
	v_pk_mul_f32 v[56:57], v[56:57], v[148:149]
	v_pk_mul_f32 v[58:59], v[58:59], v[146:147]
	v_pk_mul_f32 v[60:61], v[60:61], v[148:149]
	v_pk_mul_f32 v[62:63], v[62:63], v[146:147]
	v_pk_mul_f32 v[64:65], v[64:65], v[148:149]
	v_pk_mul_f32 v[66:67], v[66:67], v[150:151]
	v_pk_mul_f32 v[68:69], v[68:69], v[152:153]
	v_pk_mul_f32 v[70:71], v[70:71], v[150:151]
	v_pk_mul_f32 v[72:73], v[72:73], v[152:153]
	v_pk_mul_f32 v[74:75], v[74:75], v[150:151]
	v_pk_mul_f32 v[76:77], v[76:77], v[152:153]
	v_pk_mul_f32 v[78:79], v[78:79], v[150:151]
	v_pk_mul_f32 v[80:81], v[80:81], v[152:153]
	v_pk_mul_f32 v[82:83], v[82:83], v[150:151]
	v_pk_mul_f32 v[84:85], v[84:85], v[152:153]
	v_pk_mul_f32 v[86:87], v[86:87], v[150:151]
	v_pk_mul_f32 v[88:89], v[88:89], v[152:153]
	v_pk_mul_f32 v[90:91], v[90:91], v[150:151]
	v_pk_mul_f32 v[92:93], v[92:93], v[152:153]
	v_pk_mul_f32 v[94:95], v[94:95], v[150:151]
	v_pk_mul_f32 v[96:97], v[96:97], v[152:153]
	v_pk_mul_f32 v[98:99], v[98:99], v[150:151]
	v_pk_mul_f32 v[100:101], v[100:101], v[152:153]
	v_pk_mul_f32 v[102:103], v[102:103], v[150:151]
	v_pk_mul_f32 v[104:105], v[104:105], v[152:153]
	v_pk_mul_f32 v[106:107], v[106:107], v[150:151]
	v_pk_mul_f32 v[108:109], v[108:109], v[152:153]
	v_pk_mul_f32 v[110:111], v[110:111], v[150:151]
	v_pk_mul_f32 v[112:113], v[112:113], v[152:153]
	v_pk_mul_f32 v[114:115], v[114:115], v[150:151]
	v_pk_mul_f32 v[116:117], v[116:117], v[152:153]
	v_pk_mul_f32 v[118:119], v[118:119], v[150:151]
	v_pk_mul_f32 v[120:121], v[120:121], v[152:153]
	v_pk_mul_f32 v[122:123], v[122:123], v[150:151]
	v_pk_mul_f32 v[124:125], v[124:125], v[152:153]
	v_pk_mul_f32 v[126:127], v[126:127], v[150:151]
	v_pk_mul_f32 v[128:129], v[128:129], v[152:153]
.Ld16c_nr0:
	ds_read_b64_tr_b16 v[146:147], v217 offset:0
	ds_read_b64_tr_b16 v[148:149], v217 offset:8192
	ds_read_b64_tr_b16 v[150:151], v217 offset:16384
	ds_read_b64_tr_b16 v[152:153], v217 offset:24576
	ds_read_b64_tr_b16 v[154:155], v217 offset:256
	ds_read_b64_tr_b16 v[156:157], v217 offset:8448
	ds_read_b64_tr_b16 v[158:159], v217 offset:16640
	ds_read_b64_tr_b16 v[160:161], v217 offset:24832
	s_waitcnt lgkmcnt(6)
	v_mfma_f32_16x16x32_bf16 v[2:5], v[130:133], v[146:149], v[2:5]
	v_mfma_f32_16x16x32_bf16 v[66:69], v[138:141], v[146:149], v[66:69]
	ds_read_b64_tr_b16 v[146:147], v217 offset:512
	ds_read_b64_tr_b16 v[148:149], v217 offset:8704
	s_waitcnt lgkmcnt(6)
	v_mfma_f32_16x16x32_bf16 v[2:5], v[134:137], v[150:153], v[2:5]
	v_mfma_f32_16x16x32_bf16 v[66:69], v[142:145], v[150:153], v[66:69]
	ds_read_b64_tr_b16 v[150:151], v217 offset:16896
	ds_read_b64_tr_b16 v[152:153], v217 offset:25088
	s_waitcnt lgkmcnt(6)
	v_mfma_f32_16x16x32_bf16 v[6:9], v[130:133], v[154:157], v[6:9]
	v_mfma_f32_16x16x32_bf16 v[70:73], v[138:141], v[154:157], v[70:73]
	ds_read_b64_tr_b16 v[154:155], v217 offset:768
	ds_read_b64_tr_b16 v[156:157], v217 offset:8960
	s_waitcnt lgkmcnt(6)
	v_mfma_f32_16x16x32_bf16 v[6:9], v[134:137], v[158:161], v[6:9]
	v_mfma_f32_16x16x32_bf16 v[70:73], v[142:145], v[158:161], v[70:73]
	ds_read_b64_tr_b16 v[158:159], v217 offset:17152
	ds_read_b64_tr_b16 v[160:161], v217 offset:25344
	s_waitcnt lgkmcnt(6)
	v_mfma_f32_16x16x32_bf16 v[10:13], v[130:133], v[146:149], v[10:13]
	v_mfma_f32_16x16x32_bf16 v[74:77], v[138:141], v[146:149], v[74:77]
	ds_read_b64_tr_b16 v[146:147], v217 offset:1024
	ds_read_b64_tr_b16 v[148:149], v217 offset:9216
	s_waitcnt lgkmcnt(6)
	v_mfma_f32_16x16x32_bf16 v[10:13], v[134:137], v[150:153], v[10:13]
	v_mfma_f32_16x16x32_bf16 v[74:77], v[142:145], v[150:153], v[74:77]
	ds_read_b64_tr_b16 v[150:151], v217 offset:17408
	ds_read_b64_tr_b16 v[152:153], v217 offset:25600
	s_waitcnt lgkmcnt(6)
	v_mfma_f32_16x16x32_bf16 v[14:17], v[130:133], v[154:157], v[14:17]
	v_mfma_f32_16x16x32_bf16 v[78:81], v[138:141], v[154:157], v[78:81]
	ds_read_b64_tr_b16 v[154:155], v217 offset:1280
	ds_read_b64_tr_b16 v[156:157], v217 offset:9472
	s_waitcnt lgkmcnt(6)
	v_mfma_f32_16x16x32_bf16 v[14:17], v[134:137], v[158:161], v[14:17]
	v_mfma_f32_16x16x32_bf16 v[78:81], v[142:145], v[158:161], v[78:81]
	ds_read_b64_tr_b16 v[158:159], v217 offset:17664
	ds_read_b64_tr_b16 v[160:161], v217 offset:25856
	s_waitcnt lgkmcnt(6)
	v_mfma_f32_16x16x32_bf16 v[18:21], v[130:133], v[146:149], v[18:21]
	v_mfma_f32_16x16x32_bf16 v[82:85], v[138:141], v[146:149], v[82:85]
	ds_read_b64_tr_b16 v[146:147], v217 offset:1536
	ds_read_b64_tr_b16 v[148:149], v217 offset:9728
	s_waitcnt lgkmcnt(6)
	v_mfma_f32_16x16x32_bf16 v[18:21], v[134:137], v[150:153], v[18:21]
	v_mfma_f32_16x16x32_bf16 v[82:85], v[142:145], v[150:153], v[82:85]
	ds_read_b64_tr_b16 v[150:151], v217 offset:17920
	ds_read_b64_tr_b16 v[152:153], v217 offset:26112
	s_waitcnt lgkmcnt(6)
	v_mfma_f32_16x16x32_bf16 v[22:25], v[130:133], v[154:157], v[22:25]
	v_mfma_f32_16x16x32_bf16 v[86:89], v[138:141], v[154:157], v[86:89]
	ds_read_b64_tr_b16 v[154:155], v217 offset:1792
	ds_read_b64_tr_b16 v[156:157], v217 offset:9984
	s_waitcnt lgkmcnt(6)
	v_mfma_f32_16x16x32_bf16 v[22:25], v[134:137], v[158:161], v[22:25]
	v_mfma_f32_16x16x32_bf16 v[86:89], v[142:145], v[158:161], v[86:89]
	ds_read_b64_tr_b16 v[158:159], v217 offset:18176
	ds_read_b64_tr_b16 v[160:161], v217 offset:26368
	s_waitcnt lgkmcnt(6)
	v_mfma_f32_16x16x32_bf16 v[26:29], v[130:133], v[146:149], v[26:29]
	v_mfma_f32_16x16x32_bf16 v[90:93], v[138:141], v[146:149], v[90:93]
	ds_read_b64_tr_b16 v[146:147], v217 offset:2048
	ds_read_b64_tr_b16 v[148:149], v217 offset:10240
	s_waitcnt lgkmcnt(6)
	v_mfma_f32_16x16x32_bf16 v[26:29], v[134:137], v[150:153], v[26:29]
	v_mfma_f32_16x16x32_bf16 v[90:93], v[142:145], v[150:153], v[90:93]
	ds_read_b64_tr_b16 v[150:151], v217 offset:18432
	ds_read_b64_tr_b16 v[152:153], v217 offset:26624
	s_waitcnt lgkmcnt(6)
	v_mfma_f32_16x16x32_bf16 v[30:33], v[130:133], v[154:157], v[30:33]
	v_mfma_f32_16x16x32_bf16 v[94:97], v[138:141], v[154:157], v[94:97]
	ds_read_b64_tr_b16 v[154:155], v217 offset:2304
	ds_read_b64_tr_b16 v[156:157], v217 offset:10496
	s_waitcnt lgkmcnt(6)
	v_mfma_f32_16x16x32_bf16 v[30:33], v[134:137], v[158:161], v[30:33]
	v_mfma_f32_16x16x32_bf16 v[94:97], v[142:145], v[158:161], v[94:97]
	ds_read_b64_tr_b16 v[158:159], v217 offset:18688
	ds_read_b64_tr_b16 v[160:161], v217 offset:26880
	s_waitcnt lgkmcnt(6)
	v_mfma_f32_16x16x32_bf16 v[34:37], v[130:133], v[146:149], v[34:37]
	v_mfma_f32_16x16x32_bf16 v[98:101], v[138:141], v[146:149], v[98:101]
	ds_read_b64_tr_b16 v[146:147], v217 offset:2560
	ds_read_b64_tr_b16 v[148:149], v217 offset:10752
	s_waitcnt lgkmcnt(6)
	v_mfma_f32_16x16x32_bf16 v[34:37], v[134:137], v[150:153], v[34:37]
	v_mfma_f32_16x16x32_bf16 v[98:101], v[142:145], v[150:153], v[98:101]
	ds_read_b64_tr_b16 v[150:151], v217 offset:18944
	ds_read_b64_tr_b16 v[152:153], v217 offset:27136
	s_waitcnt lgkmcnt(6)
	v_mfma_f32_16x16x32_bf16 v[38:41], v[130:133], v[154:157], v[38:41]
	v_mfma_f32_16x16x32_bf16 v[102:105], v[138:141], v[154:157], v[102:105]
	ds_read_b64_tr_b16 v[154:155], v217 offset:2816
	ds_read_b64_tr_b16 v[156:157], v217 offset:11008
	s_waitcnt lgkmcnt(6)
	v_mfma_f32_16x16x32_bf16 v[38:41], v[134:137], v[158:161], v[38:41]
	v_mfma_f32_16x16x32_bf16 v[102:105], v[142:145], v[158:161], v[102:105]
	ds_read_b64_tr_b16 v[158:159], v217 offset:19200
	ds_read_b64_tr_b16 v[160:161], v217 offset:27392
	s_waitcnt lgkmcnt(6)
	v_mfma_f32_16x16x32_bf16 v[42:45], v[130:133], v[146:149], v[42:45]
	v_mfma_f32_16x16x32_bf16 v[106:109], v[138:141], v[146:149], v[106:109]
	ds_read_b64_tr_b16 v[146:147], v217 offset:3072
	ds_read_b64_tr_b16 v[148:149], v217 offset:11264
	s_waitcnt lgkmcnt(6)
	v_mfma_f32_16x16x32_bf16 v[42:45], v[134:137], v[150:153], v[42:45]
	v_mfma_f32_16x16x32_bf16 v[106:109], v[142:145], v[150:153], v[106:109]
	ds_read_b64_tr_b16 v[150:151], v217 offset:19456
	ds_read_b64_tr_b16 v[152:153], v217 offset:27648
	s_waitcnt lgkmcnt(6)
	v_mfma_f32_16x16x32_bf16 v[46:49], v[130:133], v[154:157], v[46:49]
	v_mfma_f32_16x16x32_bf16 v[110:113], v[138:141], v[154:157], v[110:113]
	ds_read_b64_tr_b16 v[154:155], v217 offset:3328
	ds_read_b64_tr_b16 v[156:157], v217 offset:11520
	s_waitcnt lgkmcnt(6)
	v_mfma_f32_16x16x32_bf16 v[46:49], v[134:137], v[158:161], v[46:49]
	v_mfma_f32_16x16x32_bf16 v[110:113], v[142:145], v[158:161], v[110:113]
	ds_read_b64_tr_b16 v[158:159], v217 offset:19712
	ds_read_b64_tr_b16 v[160:161], v217 offset:27904
	s_waitcnt lgkmcnt(6)
	v_mfma_f32_16x16x32_bf16 v[50:53], v[130:133], v[146:149], v[50:53]
	v_mfma_f32_16x16x32_bf16 v[114:117], v[138:141], v[146:149], v[114:117]
	ds_read_b64_tr_b16 v[146:147], v217 offset:3584
	ds_read_b64_tr_b16 v[148:149], v217 offset:11776
	s_waitcnt lgkmcnt(6)
	v_mfma_f32_16x16x32_bf16 v[50:53], v[134:137], v[150:153], v[50:53]
	v_mfma_f32_16x16x32_bf16 v[114:117], v[142:145], v[150:153], v[114:117]
	ds_read_b64_tr_b16 v[150:151], v217 offset:19968
	ds_read_b64_tr_b16 v[152:153], v217 offset:28160
	s_waitcnt lgkmcnt(6)
	v_mfma_f32_16x16x32_bf16 v[54:57], v[130:133], v[154:157], v[54:57]
	v_mfma_f32_16x16x32_bf16 v[118:121], v[138:141], v[154:157], v[118:121]
	ds_read_b64_tr_b16 v[154:155], v217 offset:3840
	ds_read_b64_tr_b16 v[156:157], v217 offset:12032
	s_waitcnt lgkmcnt(6)
	v_mfma_f32_16x16x32_bf16 v[54:57], v[134:137], v[158:161], v[54:57]
	v_mfma_f32_16x16x32_bf16 v[118:121], v[142:145], v[158:161], v[118:121]
	ds_read_b64_tr_b16 v[158:159], v217 offset:20224
	ds_read_b64_tr_b16 v[160:161], v217 offset:28416
	s_waitcnt lgkmcnt(6)
	v_mfma_f32_16x16x32_bf16 v[58:61], v[130:133], v[146:149], v[58:61]
	v_mfma_f32_16x16x32_bf16 v[122:125], v[138:141], v[146:149], v[122:125]
	s_waitcnt lgkmcnt(4)
	v_mfma_f32_16x16x32_bf16 v[58:61], v[134:137], v[150:153], v[58:61]
	v_mfma_f32_16x16x32_bf16 v[122:125], v[142:145], v[150:153], v[122:125]
	s_waitcnt lgkmcnt(2)
	v_mfma_f32_16x16x32_bf16 v[62:65], v[130:133], v[154:157], v[62:65]
	v_mfma_f32_16x16x32_bf16 v[126:129], v[138:141], v[154:157], v[126:129]
	s_waitcnt lgkmcnt(0)
	v_mfma_f32_16x16x32_bf16 v[62:65], v[134:137], v[158:161], v[62:65]
	v_mfma_f32_16x16x32_bf16 v[126:129], v[142:145], v[158:161], v[126:129]
	s_waitcnt vmcnt(0)
	s_cmp_gt_u32 s61, s59
	s_cselect_b64 s[40:41], -1, 0
	s_and_b64 vcc, exec, s[40:41]
	s_waitcnt vmcnt(0) lgkmcnt(0)
	s_barrier
	s_cbranch_vccnz .LBB0_2418
	s_mov_b64 s[42:43], src_shared_base
	s_cmp_lg_u32 0, -1
	s_cselect_b32 s42, 0, 0
	s_cselect_b32 s43, s43, 0
	s_add_u32 s42, s42, 0x10000
	s_addc_u32 s43, s43, 0
	s_cmp_lg_u64 s[42:43], 0
	s_cselect_b32 s42, s42, -1
	s_add_i32 s42, s42, s57
	v_lshl_add_u64 v[130:131], v[206:207], 0, s[24:25]
	s_mov_b32 m0, s42
	s_nop 0
	global_load_lds_dwordx4 v[130:131], off
	v_lshl_add_u64 v[130:131], v[204:205], 0, s[24:25]
	s_add_i32 m0, s42, 0x400
	s_add_i32 s42, s58, 0
	global_load_lds_dwordx4 v[130:131], off
	v_lshl_add_u64 v[130:131], v[202:203], 0, s[26:27]
	s_mov_b32 m0, s42
	s_nop 0
	global_load_lds_dwordx4 v[130:131], off
	v_lshl_add_u64 v[130:131], v[202:203], 0, s[28:29]
	s_add_i32 m0, s42, 0x400
	s_nop 0
	global_load_lds_dwordx4 v[130:131], off
	v_lshl_add_u64 v[130:131], v[202:203], 0, s[30:31]
	s_add_i32 m0, s42, 0x800
	s_nop 0
	global_load_lds_dwordx4 v[130:131], off
	v_lshl_add_u64 v[130:131], v[202:203], 0, s[34:35]
	s_add_i32 m0, s42, 0xc00
	s_nop 0
	global_load_lds_dwordx4 v[130:131], off
.LBB0_2418:
	ds_read_b128 v[238:241], v218 offset:16384
	ds_read_b128 v[242:245], v219 offset:16384
	ds_read_b128 v[246:249], v218 offset:16512
	s_waitcnt lgkmcnt(2)
	v_mfma_f32_16x16x32_bf16 v[130:133], v[238:241], v[162:165], 0
	v_mfma_f32_16x16x32_bf16 v[146:149], v[238:241], v[178:181], 0
	ds_read_b128 v[238:241], v219 offset:16512
	s_waitcnt lgkmcnt(2)
	v_mfma_f32_16x16x32_bf16 v[130:133], v[242:245], v[166:169], v[130:133]
	v_mfma_f32_16x16x32_bf16 v[146:149], v[242:245], v[182:185], v[146:149]
	ds_read_b128 v[242:245], v218 offset:20480
	s_waitcnt lgkmcnt(2)
	v_mfma_f32_16x16x32_bf16 v[130:133], v[246:249], v[170:173], v[130:133]
	v_mfma_f32_16x16x32_bf16 v[146:149], v[246:249], v[186:189], v[146:149]
	ds_read_b128 v[246:249], v219 offset:20480
	s_waitcnt lgkmcnt(2)
	v_mfma_f32_16x16x32_bf16 v[130:133], v[238:241], v[174:177], v[130:133]
	v_mfma_f32_16x16x32_bf16 v[146:149], v[238:241], v[190:193], v[146:149]
	ds_read_b128 v[238:241], v218 offset:20608
	s_waitcnt lgkmcnt(2)
	v_mfma_f32_16x16x32_bf16 v[134:137], v[242:245], v[162:165], 0
	v_mfma_f32_16x16x32_bf16 v[150:153], v[242:245], v[178:181], 0
	ds_read_b128 v[242:245], v219 offset:20608
	s_waitcnt lgkmcnt(2)
	v_mfma_f32_16x16x32_bf16 v[134:137], v[246:249], v[166:169], v[134:137]
	v_mfma_f32_16x16x32_bf16 v[150:153], v[246:249], v[182:185], v[150:153]
	ds_read_b128 v[246:249], v218 offset:24576
	s_waitcnt lgkmcnt(2)
	v_mfma_f32_16x16x32_bf16 v[134:137], v[238:241], v[170:173], v[134:137]
	v_mfma_f32_16x16x32_bf16 v[150:153], v[238:241], v[186:189], v[150:153]
	ds_read_b128 v[238:241], v219 offset:24576
	s_waitcnt lgkmcnt(2)
	v_mfma_f32_16x16x32_bf16 v[134:137], v[242:245], v[174:177], v[134:137]
	v_mfma_f32_16x16x32_bf16 v[150:153], v[242:245], v[190:193], v[150:153]
	ds_read_b128 v[242:245], v218 offset:24704
	s_waitcnt lgkmcnt(2)
	v_mfma_f32_16x16x32_bf16 v[138:141], v[246:249], v[162:165], 0
	v_mfma_f32_16x16x32_bf16 v[154:157], v[246:249], v[178:181], 0
	ds_read_b128 v[246:249], v219 offset:24704
	s_waitcnt lgkmcnt(2)
	v_mfma_f32_16x16x32_bf16 v[138:141], v[238:241], v[166:169], v[138:141]
	v_mfma_f32_16x16x32_bf16 v[154:157], v[238:241], v[182:185], v[154:157]
	ds_read_b128 v[238:241], v218 offset:28672
	s_waitcnt lgkmcnt(2)
	v_mfma_f32_16x16x32_bf16 v[138:141], v[242:245], v[170:173], v[138:141]
	v_mfma_f32_16x16x32_bf16 v[154:157], v[242:245], v[186:189], v[154:157]
	ds_read_b128 v[242:245], v219 offset:28672
	s_waitcnt lgkmcnt(2)
	v_mfma_f32_16x16x32_bf16 v[138:141], v[246:249], v[174:177], v[138:141]
	v_mfma_f32_16x16x32_bf16 v[154:157], v[246:249], v[190:193], v[154:157]
	ds_read_b128 v[246:249], v218 offset:28800
	s_waitcnt lgkmcnt(2)
	v_mfma_f32_16x16x32_bf16 v[142:145], v[238:241], v[162:165], 0
	v_mfma_f32_16x16x32_bf16 v[158:161], v[238:241], v[178:181], 0
	ds_read_b128 v[238:241], v219 offset:28800
	s_waitcnt lgkmcnt(2)
	v_mfma_f32_16x16x32_bf16 v[142:145], v[242:245], v[166:169], v[142:145]
	v_mfma_f32_16x16x32_bf16 v[158:161], v[242:245], v[182:185], v[158:161]
	s_waitcnt lgkmcnt(1)
	v_mfma_f32_16x16x32_bf16 v[142:145], v[246:249], v[170:173], v[142:145]
	v_mfma_f32_16x16x32_bf16 v[158:161], v[246:249], v[186:189], v[158:161]
	s_waitcnt lgkmcnt(0)
	v_mfma_f32_16x16x32_bf16 v[142:145], v[238:241], v[174:177], v[142:145]
	v_mfma_f32_16x16x32_bf16 v[158:161], v[238:241], v[190:193], v[158:161]
	s_nop 7
	s_nop 1
	s_cmp_le_i32 s60, s4
	s_cbranch_scc1 .Ld16c_nm1
	v_subrev_u32_e32 v246, 64, v233
	v_cmp_gt_i32_e64 s[74:75], 0, v246
	v_cmp_gt_i32_e64 s[76:77], 1, v246
	v_cmp_gt_i32_e64 s[78:79], 2, v246
	v_cmp_gt_i32_e64 s[80:81], 3, v246
	v_cndmask_b32_e64 v130, v130, v230, s[74:75]
	v_cndmask_b32_e64 v131, v131, v230, s[76:77]
	v_cndmask_b32_e64 v132, v132, v230, s[78:79]
	v_cndmask_b32_e64 v133, v133, v230, s[80:81]
	v_cmp_gt_i32_e64 s[74:75], 16, v246
	v_cmp_gt_i32_e64 s[76:77], 17, v246
	v_cmp_gt_i32_e64 s[78:79], 18, v246
	v_cmp_gt_i32_e64 s[80:81], 19, v246
	v_cndmask_b32_e64 v134, v134, v230, s[74:75]
	v_cndmask_b32_e64 v135, v135, v230, s[76:77]
	v_cndmask_b32_e64 v136, v136, v230, s[78:79]
	v_cndmask_b32_e64 v137, v137, v230, s[80:81]
	v_cmp_gt_i32_e64 s[74:75], 32, v246
	v_cmp_gt_i32_e64 s[76:77], 33, v246
	v_cmp_gt_i32_e64 s[78:79], 34, v246
	v_cmp_gt_i32_e64 s[80:81], 35, v246
	v_cndmask_b32_e64 v138, v138, v230, s[74:75]
	v_cndmask_b32_e64 v139, v139, v230, s[76:77]
	v_cndmask_b32_e64 v140, v140, v230, s[78:79]
	v_cndmask_b32_e64 v141, v141, v230, s[80:81]
	v_cmp_gt_i32_e64 s[74:75], 48, v246
	v_cmp_gt_i32_e64 s[76:77], 49, v246
	v_cmp_gt_i32_e64 s[78:79], 50, v246
	v_cmp_gt_i32_e64 s[80:81], 51, v246
	v_cndmask_b32_e64 v142, v142, v230, s[74:75]
	v_cndmask_b32_e64 v143, v143, v230, s[76:77]
	v_cndmask_b32_e64 v144, v144, v230, s[78:79]
	v_cndmask_b32_e64 v145, v145, v230, s[80:81]
	v_cmp_gt_i32_e64 s[74:75], -16, v246
	v_cmp_gt_i32_e64 s[76:77], -15, v246
	v_cmp_gt_i32_e64 s[78:79], -14, v246
	v_cmp_gt_i32_e64 s[80:81], -13, v246
	v_cndmask_b32_e64 v146, v146, v230, s[74:75]
	v_cndmask_b32_e64 v147, v147, v230, s[76:77]
	v_cndmask_b32_e64 v148, v148, v230, s[78:79]
	v_cndmask_b32_e64 v149, v149, v230, s[80:81]
	v_cmp_gt_i32_e64 s[74:75], 0, v246
	v_cmp_gt_i32_e64 s[76:77], 1, v246
	v_cmp_gt_i32_e64 s[78:79], 2, v246
	v_cmp_gt_i32_e64 s[80:81], 3, v246
	v_cndmask_b32_e64 v150, v150, v230, s[74:75]
	v_cndmask_b32_e64 v151, v151, v230, s[76:77]
	v_cndmask_b32_e64 v152, v152, v230, s[78:79]
	v_cndmask_b32_e64 v153, v153, v230, s[80:81]
	v_cmp_gt_i32_e64 s[74:75], 16, v246
	v_cmp_gt_i32_e64 s[76:77], 17, v246
	v_cmp_gt_i32_e64 s[78:79], 18, v246
	v_cmp_gt_i32_e64 s[80:81], 19, v246
	v_cndmask_b32_e64 v154, v154, v230, s[74:75]
	v_cndmask_b32_e64 v155, v155, v230, s[76:77]
	v_cndmask_b32_e64 v156, v156, v230, s[78:79]
	v_cndmask_b32_e64 v157, v157, v230, s[80:81]
	v_cmp_gt_i32_e64 s[74:75], 32, v246
	v_cmp_gt_i32_e64 s[76:77], 33, v246
	v_cmp_gt_i32_e64 s[78:79], 34, v246
	v_cmp_gt_i32_e64 s[80:81], 35, v246
	v_cndmask_b32_e64 v158, v158, v230, s[74:75]
	v_cndmask_b32_e64 v159, v159, v230, s[76:77]
	v_cndmask_b32_e64 v160, v160, v230, s[78:79]
	v_cndmask_b32_e64 v161, v161, v230, s[80:81]

.LBB0_2423:
	s_and_saveexec_b64 s[38:39], s[0:1]
	ds_write_b32 v232, v0
	ds_write_b32 v232, v223 offset:64
	s_or_b64 exec, exec, s[38:39]
	s_waitcnt lgkmcnt(0)
	ds_read_b128 v[146:149], v231
	ds_read_b128 v[150:153], v231 offset:64
	s_lshl_b64 s[2:3], s[2:3], 12
	s_add_u32 s2, s46, s2
	s_addc_u32 s3, s47, s3
	s_lshl_b32 s4, s56, 9
	s_add_u32 s4, s2, s4
	s_addc_u32 s38, s3, 0
	s_lshl_b64 s[2:3], s[36:37], 12
	s_add_u32 s36, s4, s2
	s_addc_u32 s37, s38, s3
	v_mbcnt_lo_u32_b32 v202, -1, 0
	v_mbcnt_hi_u32_b32 v202, -1, v202
	v_and_b32_e32 v203, 15, v202
	v_lshrrev_b32_e32 v204, 4, v202
	v_lshlrev_b32_e32 v204, 14, v204
	v_lshl_or_b32 v204, v203, 1, v204
	v_and_b32_e32 v203, 1, v202
	v_cmp_eq_u32_e64 s[76:77], 0, v203
	s_waitcnt lgkmcnt(0)
	v_rcp_f32_e32 v146, v146
	v_rcp_f32_e32 v147, v147
	v_rcp_f32_e32 v148, v148
	v_rcp_f32_e32 v149, v149
	v_rcp_f32_e32 v150, v150
	v_rcp_f32_e32 v151, v151
	v_rcp_f32_e32 v152, v152
	v_rcp_f32_e32 v153, v153
	s_nop 0
	v_mov_b32_e32 v205, v204
	v_mul_f32_e32 v2, v2, v146
	v_mul_f32_e32 v6, v6, v146
	v_mul_f32_e32 v10, v10, v146
	v_mul_f32_e32 v14, v14, v146
	v_mul_f32_e32 v18, v18, v146
	v_mul_f32_e32 v22, v22, v146
	v_mul_f32_e32 v26, v26, v146
	v_mul_f32_e32 v30, v30, v146
	v_mul_f32_e32 v34, v34, v146
	v_mul_f32_e32 v38, v38, v146
	v_mul_f32_e32 v42, v42, v146
	v_mul_f32_e32 v46, v46, v146
	v_mul_f32_e32 v50, v50, v146
	v_mul_f32_e32 v54, v54, v146
	v_mul_f32_e32 v58, v58, v146
	v_mul_f32_e32 v62, v62, v146
	v_mov_b32_dpp v162, v2 quad_perm:[1,0,3,2] row_mask:0xf bank_mask:0xf
	v_mov_b32_dpp v163, v6 quad_perm:[1,0,3,2] row_mask:0xf bank_mask:0xf
	v_mov_b32_dpp v164, v10 quad_perm:[1,0,3,2] row_mask:0xf bank_mask:0xf
	v_mov_b32_dpp v165, v14 quad_perm:[1,0,3,2] row_mask:0xf bank_mask:0xf
	v_mov_b32_dpp v166, v18 quad_perm:[1,0,3,2] row_mask:0xf bank_mask:0xf
	v_mov_b32_dpp v167, v22 quad_perm:[1,0,3,2] row_mask:0xf bank_mask:0xf
	v_mov_b32_dpp v168, v26 quad_perm:[1,0,3,2] row_mask:0xf bank_mask:0xf
	v_mov_b32_dpp v169, v30 quad_perm:[1,0,3,2] row_mask:0xf bank_mask:0xf
	v_mov_b32_dpp v170, v34 quad_perm:[1,0,3,2] row_mask:0xf bank_mask:0xf
	v_mov_b32_dpp v171, v38 quad_perm:[1,0,3,2] row_mask:0xf bank_mask:0xf
	v_mov_b32_dpp v172, v42 quad_perm:[1,0,3,2] row_mask:0xf bank_mask:0xf
	v_mov_b32_dpp v173, v46 quad_perm:[1,0,3,2] row_mask:0xf bank_mask:0xf
	v_mov_b32_dpp v174, v50 quad_perm:[1,0,3,2] row_mask:0xf bank_mask:0xf
	v_mov_b32_dpp v175, v54 quad_perm:[1,0,3,2] row_mask:0xf bank_mask:0xf
	v_mov_b32_dpp v176, v58 quad_perm:[1,0,3,2] row_mask:0xf bank_mask:0xf
	v_mov_b32_dpp v177, v62 quad_perm:[1,0,3,2] row_mask:0xf bank_mask:0xf
	v_cvt_pk_bf16_f32 v2, v2, v162
	v_cvt_pk_bf16_f32 v6, v6, v163
	v_cvt_pk_bf16_f32 v10, v10, v164
	v_cvt_pk_bf16_f32 v14, v14, v165
	v_cvt_pk_bf16_f32 v18, v18, v166
	v_cvt_pk_bf16_f32 v22, v22, v167
	v_cvt_pk_bf16_f32 v26, v26, v168
	v_cvt_pk_bf16_f32 v30, v30, v169
	v_cvt_pk_bf16_f32 v34, v34, v170
	v_cvt_pk_bf16_f32 v38, v38, v171
	v_cvt_pk_bf16_f32 v42, v42, v172
	v_cvt_pk_bf16_f32 v46, v46, v173
	v_cvt_pk_bf16_f32 v50, v50, v174
	v_cvt_pk_bf16_f32 v54, v54, v175
	v_cvt_pk_bf16_f32 v58, v58, v176
	v_cvt_pk_bf16_f32 v62, v62, v177
	s_mov_b64 exec, s[76:77]
	global_store_dword v205, v2, s[36:37] offset:0
	global_store_dword v205, v6, s[36:37] offset:32
	global_store_dword v205, v10, s[36:37] offset:64
	global_store_dword v205, v14, s[36:37] offset:96
	global_store_dword v205, v18, s[36:37] offset:128
	global_store_dword v205, v22, s[36:37] offset:160
	global_store_dword v205, v26, s[36:37] offset:192
	global_store_dword v205, v30, s[36:37] offset:224
	global_store_dword v205, v34, s[36:37] offset:256
	global_store_dword v205, v38, s[36:37] offset:288
	global_store_dword v205, v42, s[36:37] offset:320
	global_store_dword v205, v46, s[36:37] offset:352
	global_store_dword v205, v50, s[36:37] offset:384
	global_store_dword v205, v54, s[36:37] offset:416
	global_store_dword v205, v58, s[36:37] offset:448
	global_store_dword v205, v62, s[36:37] offset:480
	s_mov_b64 exec, -1
	v_add_u32_e32 v205, 0x1000, v204
	v_mul_f32_e32 v3, v3, v147
	v_mul_f32_e32 v7, v7, v147
	v_mul_f32_e32 v11, v11, v147
	v_mul_f32_e32 v15, v15, v147
	v_mul_f32_e32 v19, v19, v147
	v_mul_f32_e32 v23, v23, v147
	v_mul_f32_e32 v27, v27, v147
	v_mul_f32_e32 v31, v31, v147
	v_mul_f32_e32 v35, v35, v147
	v_mul_f32_e32 v39, v39, v147
	v_mul_f32_e32 v43, v43, v147
	v_mul_f32_e32 v47, v47, v147
	v_mul_f32_e32 v51, v51, v147
	v_mul_f32_e32 v55, v55, v147
	v_mul_f32_e32 v59, v59, v147
	v_mul_f32_e32 v63, v63, v147
	v_mov_b32_dpp v162, v3 quad_perm:[1,0,3,2] row_mask:0xf bank_mask:0xf
	v_mov_b32_dpp v163, v7 quad_perm:[1,0,3,2] row_mask:0xf bank_mask:0xf
	v_mov_b32_dpp v164, v11 quad_perm:[1,0,3,2] row_mask:0xf bank_mask:0xf
	v_mov_b32_dpp v165, v15 quad_perm:[1,0,3,2] row_mask:0xf bank_mask:0xf
	v_mov_b32_dpp v166, v19 quad_perm:[1,0,3,2] row_mask:0xf bank_mask:0xf
	v_mov_b32_dpp v167, v23 quad_perm:[1,0,3,2] row_mask:0xf bank_mask:0xf
	v_mov_b32_dpp v168, v27 quad_perm:[1,0,3,2] row_mask:0xf bank_mask:0xf
	v_mov_b32_dpp v169, v31 quad_perm:[1,0,3,2] row_mask:0xf bank_mask:0xf
	v_mov_b32_dpp v170, v35 quad_perm:[1,0,3,2] row_mask:0xf bank_mask:0xf
	v_mov_b32_dpp v171, v39 quad_perm:[1,0,3,2] row_mask:0xf bank_mask:0xf
	v_mov_b32_dpp v172, v43 quad_perm:[1,0,3,2] row_mask:0xf bank_mask:0xf
	v_mov_b32_dpp v173, v47 quad_perm:[1,0,3,2] row_mask:0xf bank_mask:0xf
	v_mov_b32_dpp v174, v51 quad_perm:[1,0,3,2] row_mask:0xf bank_mask:0xf
	v_mov_b32_dpp v175, v55 quad_perm:[1,0,3,2] row_mask:0xf bank_mask:0xf
	v_mov_b32_dpp v176, v59 quad_perm:[1,0,3,2] row_mask:0xf bank_mask:0xf
	v_mov_b32_dpp v177, v63 quad_perm:[1,0,3,2] row_mask:0xf bank_mask:0xf
	v_cvt_pk_bf16_f32 v3, v3, v162
	v_cvt_pk_bf16_f32 v7, v7, v163
	v_cvt_pk_bf16_f32 v11, v11, v164
	v_cvt_pk_bf16_f32 v15, v15, v165
	v_cvt_pk_bf16_f32 v19, v19, v166
	v_cvt_pk_bf16_f32 v23, v23, v167
	v_cvt_pk_bf16_f32 v27, v27, v168
	v_cvt_pk_bf16_f32 v31, v31, v169
	v_cvt_pk_bf16_f32 v35, v35, v170
	v_cvt_pk_bf16_f32 v39, v39, v171
	v_cvt_pk_bf16_f32 v43, v43, v172
	v_cvt_pk_bf16_f32 v47, v47, v173
	v_cvt_pk_bf16_f32 v51, v51, v174
	v_cvt_pk_bf16_f32 v55, v55, v175
	v_cvt_pk_bf16_f32 v59, v59, v176
	v_cvt_pk_bf16_f32 v63, v63, v177
	s_mov_b64 exec, s[76:77]
	global_store_dword v205, v3, s[36:37] offset:0
	global_store_dword v205, v7, s[36:37] offset:32
	global_store_dword v205, v11, s[36:37] offset:64
	global_store_dword v205, v15, s[36:37] offset:96
	global_store_dword v205, v19, s[36:37] offset:128
	global_store_dword v205, v23, s[36:37] offset:160
	global_store_dword v205, v27, s[36:37] offset:192
	global_store_dword v205, v31, s[36:37] offset:224
	global_store_dword v205, v35, s[36:37] offset:256
	global_store_dword v205, v39, s[36:37] offset:288
	global_store_dword v205, v43, s[36:37] offset:320
	global_store_dword v205, v47, s[36:37] offset:352
	global_store_dword v205, v51, s[36:37] offset:384
	global_store_dword v205, v55, s[36:37] offset:416
	global_store_dword v205, v59, s[36:37] offset:448
	global_store_dword v205, v63, s[36:37] offset:480
	s_mov_b64 exec, -1
	v_add_u32_e32 v205, 0x2000, v204
	v_mul_f32_e32 v4, v4, v148
	v_mul_f32_e32 v8, v8, v148
	v_mul_f32_e32 v12, v12, v148
	v_mul_f32_e32 v16, v16, v148
	v_mul_f32_e32 v20, v20, v148
	v_mul_f32_e32 v24, v24, v148
	v_mul_f32_e32 v28, v28, v148
	v_mul_f32_e32 v32, v32, v148
	v_mul_f32_e32 v36, v36, v148
	v_mul_f32_e32 v40, v40, v148
	v_mul_f32_e32 v44, v44, v148
	v_mul_f32_e32 v48, v48, v148
	v_mul_f32_e32 v52, v52, v148
	v_mul_f32_e32 v56, v56, v148
	v_mul_f32_e32 v60, v60, v148
	v_mul_f32_e32 v64, v64, v148
	v_mov_b32_dpp v162, v4 quad_perm:[1,0,3,2] row_mask:0xf bank_mask:0xf
	v_mov_b32_dpp v163, v8 quad_perm:[1,0,3,2] row_mask:0xf bank_mask:0xf
	v_mov_b32_dpp v164, v12 quad_perm:[1,0,3,2] row_mask:0xf bank_mask:0xf
	v_mov_b32_dpp v165, v16 quad_perm:[1,0,3,2] row_mask:0xf bank_mask:0xf
	v_mov_b32_dpp v166, v20 quad_perm:[1,0,3,2] row_mask:0xf bank_mask:0xf
	v_mov_b32_dpp v167, v24 quad_perm:[1,0,3,2] row_mask:0xf bank_mask:0xf
	v_mov_b32_dpp v168, v28 quad_perm:[1,0,3,2] row_mask:0xf bank_mask:0xf
	v_mov_b32_dpp v169, v32 quad_perm:[1,0,3,2] row_mask:0xf bank_mask:0xf
	v_mov_b32_dpp v170, v36 quad_perm:[1,0,3,2] row_mask:0xf bank_mask:0xf
	v_mov_b32_dpp v171, v40 quad_perm:[1,0,3,2] row_mask:0xf bank_mask:0xf
	v_mov_b32_dpp v172, v44 quad_perm:[1,0,3,2] row_mask:0xf bank_mask:0xf
	v_mov_b32_dpp v173, v48 quad_perm:[1,0,3,2] row_mask:0xf bank_mask:0xf
	v_mov_b32_dpp v174, v52 quad_perm:[1,0,3,2] row_mask:0xf bank_mask:0xf
	v_mov_b32_dpp v175, v56 quad_perm:[1,0,3,2] row_mask:0xf bank_mask:0xf
	v_mov_b32_dpp v176, v60 quad_perm:[1,0,3,2] row_mask:0xf bank_mask:0xf
	v_mov_b32_dpp v177, v64 quad_perm:[1,0,3,2] row_mask:0xf bank_mask:0xf
	v_cvt_pk_bf16_f32 v4, v4, v162
	v_cvt_pk_bf16_f32 v8, v8, v163
	v_cvt_pk_bf16_f32 v12, v12, v164
	v_cvt_pk_bf16_f32 v16, v16, v165
	v_cvt_pk_bf16_f32 v20, v20, v166
	v_cvt_pk_bf16_f32 v24, v24, v167
	v_cvt_pk_bf16_f32 v28, v28, v168
	v_cvt_pk_bf16_f32 v32, v32, v169
	v_cvt_pk_bf16_f32 v36, v36, v170
	v_cvt_pk_bf16_f32 v40, v40, v171
	v_cvt_pk_bf16_f32 v44, v44, v172
	v_cvt_pk_bf16_f32 v48, v48, v173
	v_cvt_pk_bf16_f32 v52, v52, v174
	v_cvt_pk_bf16_f32 v56, v56, v175
	v_cvt_pk_bf16_f32 v60, v60, v176
	v_cvt_pk_bf16_f32 v64, v64, v177
	s_mov_b64 exec, s[76:77]
	global_store_dword v205, v4, s[36:37] offset:0
	global_store_dword v205, v8, s[36:37] offset:32
	global_store_dword v205, v12, s[36:37] offset:64
	global_store_dword v205, v16, s[36:37] offset:96
	global_store_dword v205, v20, s[36:37] offset:128
	global_store_dword v205, v24, s[36:37] offset:160
	global_store_dword v205, v28, s[36:37] offset:192
	global_store_dword v205, v32, s[36:37] offset:224
	global_store_dword v205, v36, s[36:37] offset:256
	global_store_dword v205, v40, s[36:37] offset:288
	global_store_dword v205, v44, s[36:37] offset:320
	global_store_dword v205, v48, s[36:37] offset:352
	global_store_dword v205, v52, s[36:37] offset:384
	global_store_dword v205, v56, s[36:37] offset:416
	global_store_dword v205, v60, s[36:37] offset:448
	global_store_dword v205, v64, s[36:37] offset:480
	s_mov_b64 exec, -1
	v_add_u32_e32 v205, 0x3000, v204
	v_mul_f32_e32 v5, v5, v149
	v_mul_f32_e32 v9, v9, v149
	v_mul_f32_e32 v13, v13, v149
	v_mul_f32_e32 v17, v17, v149
	v_mul_f32_e32 v21, v21, v149
	v_mul_f32_e32 v25, v25, v149
	v_mul_f32_e32 v29, v29, v149
	v_mul_f32_e32 v33, v33, v149
	v_mul_f32_e32 v37, v37, v149
	v_mul_f32_e32 v41, v41, v149
	v_mul_f32_e32 v45, v45, v149
	v_mul_f32_e32 v49, v49, v149
	v_mul_f32_e32 v53, v53, v149
	v_mul_f32_e32 v57, v57, v149
	v_mul_f32_e32 v61, v61, v149
	v_mul_f32_e32 v65, v65, v149
	v_mov_b32_dpp v162, v5 quad_perm:[1,0,3,2] row_mask:0xf bank_mask:0xf
	v_mov_b32_dpp v163, v9 quad_perm:[1,0,3,2] row_mask:0xf bank_mask:0xf
	v_mov_b32_dpp v164, v13 quad_perm:[1,0,3,2] row_mask:0xf bank_mask:0xf
	v_mov_b32_dpp v165, v17 quad_perm:[1,0,3,2] row_mask:0xf bank_mask:0xf
	v_mov_b32_dpp v166, v21 quad_perm:[1,0,3,2] row_mask:0xf bank_mask:0xf
	v_mov_b32_dpp v167, v25 quad_perm:[1,0,3,2] row_mask:0xf bank_mask:0xf
	v_mov_b32_dpp v168, v29 quad_perm:[1,0,3,2] row_mask:0xf bank_mask:0xf
	v_mov_b32_dpp v169, v33 quad_perm:[1,0,3,2] row_mask:0xf bank_mask:0xf
	v_mov_b32_dpp v170, v37 quad_perm:[1,0,3,2] row_mask:0xf bank_mask:0xf
	v_mov_b32_dpp v171, v41 quad_perm:[1,0,3,2] row_mask:0xf bank_mask:0xf
	v_mov_b32_dpp v172, v45 quad_perm:[1,0,3,2] row_mask:0xf bank_mask:0xf
	v_mov_b32_dpp v173, v49 quad_perm:[1,0,3,2] row_mask:0xf bank_mask:0xf
	v_mov_b32_dpp v174, v53 quad_perm:[1,0,3,2] row_mask:0xf bank_mask:0xf
	v_mov_b32_dpp v175, v57 quad_perm:[1,0,3,2] row_mask:0xf bank_mask:0xf
	v_mov_b32_dpp v176, v61 quad_perm:[1,0,3,2] row_mask:0xf bank_mask:0xf
	v_mov_b32_dpp v177, v65 quad_perm:[1,0,3,2] row_mask:0xf bank_mask:0xf
	v_cvt_pk_bf16_f32 v5, v5, v162
	v_cvt_pk_bf16_f32 v9, v9, v163
	v_cvt_pk_bf16_f32 v13, v13, v164
	v_cvt_pk_bf16_f32 v17, v17, v165
	v_cvt_pk_bf16_f32 v21, v21, v166
	v_cvt_pk_bf16_f32 v25, v25, v167
	v_cvt_pk_bf16_f32 v29, v29, v168
	v_cvt_pk_bf16_f32 v33, v33, v169
	v_cvt_pk_bf16_f32 v37, v37, v170
	v_cvt_pk_bf16_f32 v41, v41, v171
	v_cvt_pk_bf16_f32 v45, v45, v172
	v_cvt_pk_bf16_f32 v49, v49, v173
	v_cvt_pk_bf16_f32 v53, v53, v174
	v_cvt_pk_bf16_f32 v57, v57, v175
	v_cvt_pk_bf16_f32 v61, v61, v176
	v_cvt_pk_bf16_f32 v65, v65, v177
	s_mov_b64 exec, s[76:77]
	global_store_dword v205, v5, s[36:37] offset:0
	global_store_dword v205, v9, s[36:37] offset:32
	global_store_dword v205, v13, s[36:37] offset:64
	global_store_dword v205, v17, s[36:37] offset:96
	global_store_dword v205, v21, s[36:37] offset:128
	global_store_dword v205, v25, s[36:37] offset:160
	global_store_dword v205, v29, s[36:37] offset:192
	global_store_dword v205, v33, s[36:37] offset:224
	global_store_dword v205, v37, s[36:37] offset:256
	global_store_dword v205, v41, s[36:37] offset:288
	global_store_dword v205, v45, s[36:37] offset:320
	global_store_dword v205, v49, s[36:37] offset:352
	global_store_dword v205, v53, s[36:37] offset:384
	global_store_dword v205, v57, s[36:37] offset:416
	global_store_dword v205, v61, s[36:37] offset:448
	global_store_dword v205, v65, s[36:37] offset:480
	s_mov_b64 exec, -1
	v_add_u32_e32 v205, 0x10000, v204
	v_mul_f32_e32 v66, v66, v150
	v_mul_f32_e32 v70, v70, v150
	v_mul_f32_e32 v74, v74, v150
	v_mul_f32_e32 v78, v78, v150
	v_mul_f32_e32 v82, v82, v150
	v_mul_f32_e32 v86, v86, v150
	v_mul_f32_e32 v90, v90, v150
	v_mul_f32_e32 v94, v94, v150
	v_mul_f32_e32 v98, v98, v150
	v_mul_f32_e32 v102, v102, v150
	v_mul_f32_e32 v106, v106, v150
	v_mul_f32_e32 v110, v110, v150
	v_mul_f32_e32 v114, v114, v150
	v_mul_f32_e32 v118, v118, v150
	v_mul_f32_e32 v122, v122, v150
	v_mul_f32_e32 v126, v126, v150
	v_mov_b32_dpp v162, v66 quad_perm:[1,0,3,2] row_mask:0xf bank_mask:0xf
	v_mov_b32_dpp v163, v70 quad_perm:[1,0,3,2] row_mask:0xf bank_mask:0xf
	v_mov_b32_dpp v164, v74 quad_perm:[1,0,3,2] row_mask:0xf bank_mask:0xf
	v_mov_b32_dpp v165, v78 quad_perm:[1,0,3,2] row_mask:0xf bank_mask:0xf
	v_mov_b32_dpp v166, v82 quad_perm:[1,0,3,2] row_mask:0xf bank_mask:0xf
	v_mov_b32_dpp v167, v86 quad_perm:[1,0,3,2] row_mask:0xf bank_mask:0xf
	v_mov_b32_dpp v168, v90 quad_perm:[1,0,3,2] row_mask:0xf bank_mask:0xf
	v_mov_b32_dpp v169, v94 quad_perm:[1,0,3,2] row_mask:0xf bank_mask:0xf
	v_mov_b32_dpp v170, v98 quad_perm:[1,0,3,2] row_mask:0xf bank_mask:0xf
	v_mov_b32_dpp v171, v102 quad_perm:[1,0,3,2] row_mask:0xf bank_mask:0xf
	v_mov_b32_dpp v172, v106 quad_perm:[1,0,3,2] row_mask:0xf bank_mask:0xf
	v_mov_b32_dpp v173, v110 quad_perm:[1,0,3,2] row_mask:0xf bank_mask:0xf
	v_mov_b32_dpp v174, v114 quad_perm:[1,0,3,2] row_mask:0xf bank_mask:0xf
	v_mov_b32_dpp v175, v118 quad_perm:[1,0,3,2] row_mask:0xf bank_mask:0xf
	v_mov_b32_dpp v176, v122 quad_perm:[1,0,3,2] row_mask:0xf bank_mask:0xf
	v_mov_b32_dpp v177, v126 quad_perm:[1,0,3,2] row_mask:0xf bank_mask:0xf
	v_cvt_pk_bf16_f32 v66, v66, v162
	v_cvt_pk_bf16_f32 v70, v70, v163
	v_cvt_pk_bf16_f32 v74, v74, v164
	v_cvt_pk_bf16_f32 v78, v78, v165
	v_cvt_pk_bf16_f32 v82, v82, v166
	v_cvt_pk_bf16_f32 v86, v86, v167
	v_cvt_pk_bf16_f32 v90, v90, v168
	v_cvt_pk_bf16_f32 v94, v94, v169
	v_cvt_pk_bf16_f32 v98, v98, v170
	v_cvt_pk_bf16_f32 v102, v102, v171
	v_cvt_pk_bf16_f32 v106, v106, v172
	v_cvt_pk_bf16_f32 v110, v110, v173
	v_cvt_pk_bf16_f32 v114, v114, v174
	v_cvt_pk_bf16_f32 v118, v118, v175
	v_cvt_pk_bf16_f32 v122, v122, v176
	v_cvt_pk_bf16_f32 v126, v126, v177
	s_mov_b64 exec, s[76:77]
	global_store_dword v205, v66, s[36:37] offset:0
	global_store_dword v205, v70, s[36:37] offset:32
	global_store_dword v205, v74, s[36:37] offset:64
	global_store_dword v205, v78, s[36:37] offset:96
	global_store_dword v205, v82, s[36:37] offset:128
	global_store_dword v205, v86, s[36:37] offset:160
	global_store_dword v205, v90, s[36:37] offset:192
	global_store_dword v205, v94, s[36:37] offset:224
	global_store_dword v205, v98, s[36:37] offset:256
	global_store_dword v205, v102, s[36:37] offset:288
	global_store_dword v205, v106, s[36:37] offset:320
	global_store_dword v205, v110, s[36:37] offset:352
	global_store_dword v205, v114, s[36:37] offset:384
	global_store_dword v205, v118, s[36:37] offset:416
	global_store_dword v205, v122, s[36:37] offset:448
	global_store_dword v205, v126, s[36:37] offset:480
	s_mov_b64 exec, -1
	v_add_u32_e32 v205, 0x11000, v204
	v_mul_f32_e32 v67, v67, v151
	v_mul_f32_e32 v71, v71, v151
	v_mul_f32_e32 v75, v75, v151
	v_mul_f32_e32 v79, v79, v151
	v_mul_f32_e32 v83, v83, v151
	v_mul_f32_e32 v87, v87, v151
	v_mul_f32_e32 v91, v91, v151
	v_mul_f32_e32 v95, v95, v151
	v_mul_f32_e32 v99, v99, v151
	v_mul_f32_e32 v103, v103, v151
	v_mul_f32_e32 v107, v107, v151
	v_mul_f32_e32 v111, v111, v151
	v_mul_f32_e32 v115, v115, v151
	v_mul_f32_e32 v119, v119, v151
	v_mul_f32_e32 v123, v123, v151
	v_mul_f32_e32 v127, v127, v151
	v_mov_b32_dpp v162, v67 quad_perm:[1,0,3,2] row_mask:0xf bank_mask:0xf
	v_mov_b32_dpp v163, v71 quad_perm:[1,0,3,2] row_mask:0xf bank_mask:0xf
	v_mov_b32_dpp v164, v75 quad_perm:[1,0,3,2] row_mask:0xf bank_mask:0xf
	v_mov_b32_dpp v165, v79 quad_perm:[1,0,3,2] row_mask:0xf bank_mask:0xf
	v_mov_b32_dpp v166, v83 quad_perm:[1,0,3,2] row_mask:0xf bank_mask:0xf
	v_mov_b32_dpp v167, v87 quad_perm:[1,0,3,2] row_mask:0xf bank_mask:0xf
	v_mov_b32_dpp v168, v91 quad_perm:[1,0,3,2] row_mask:0xf bank_mask:0xf
	v_mov_b32_dpp v169, v95 quad_perm:[1,0,3,2] row_mask:0xf bank_mask:0xf
	v_mov_b32_dpp v170, v99 quad_perm:[1,0,3,2] row_mask:0xf bank_mask:0xf
	v_mov_b32_dpp v171, v103 quad_perm:[1,0,3,2] row_mask:0xf bank_mask:0xf
	v_mov_b32_dpp v172, v107 quad_perm:[1,0,3,2] row_mask:0xf bank_mask:0xf
	v_mov_b32_dpp v173, v111 quad_perm:[1,0,3,2] row_mask:0xf bank_mask:0xf
	v_mov_b32_dpp v174, v115 quad_perm:[1,0,3,2] row_mask:0xf bank_mask:0xf
	v_mov_b32_dpp v175, v119 quad_perm:[1,0,3,2] row_mask:0xf bank_mask:0xf
	v_mov_b32_dpp v176, v123 quad_perm:[1,0,3,2] row_mask:0xf bank_mask:0xf
	v_mov_b32_dpp v177, v127 quad_perm:[1,0,3,2] row_mask:0xf bank_mask:0xf
	v_cvt_pk_bf16_f32 v67, v67, v162
	v_cvt_pk_bf16_f32 v71, v71, v163
	v_cvt_pk_bf16_f32 v75, v75, v164
	v_cvt_pk_bf16_f32 v79, v79, v165
	v_cvt_pk_bf16_f32 v83, v83, v166
	v_cvt_pk_bf16_f32 v87, v87, v167
	v_cvt_pk_bf16_f32 v91, v91, v168
	v_cvt_pk_bf16_f32 v95, v95, v169
	v_cvt_pk_bf16_f32 v99, v99, v170
	v_cvt_pk_bf16_f32 v103, v103, v171
	v_cvt_pk_bf16_f32 v107, v107, v172
	v_cvt_pk_bf16_f32 v111, v111, v173
	v_cvt_pk_bf16_f32 v115, v115, v174
	v_cvt_pk_bf16_f32 v119, v119, v175
	v_cvt_pk_bf16_f32 v123, v123, v176
	v_cvt_pk_bf16_f32 v127, v127, v177
	s_mov_b64 exec, s[76:77]
	global_store_dword v205, v67, s[36:37] offset:0
	global_store_dword v205, v71, s[36:37] offset:32
	global_store_dword v205, v75, s[36:37] offset:64
	global_store_dword v205, v79, s[36:37] offset:96
	global_store_dword v205, v83, s[36:37] offset:128
	global_store_dword v205, v87, s[36:37] offset:160
	global_store_dword v205, v91, s[36:37] offset:192
	global_store_dword v205, v95, s[36:37] offset:224
	global_store_dword v205, v99, s[36:37] offset:256
	global_store_dword v205, v103, s[36:37] offset:288
	global_store_dword v205, v107, s[36:37] offset:320
	global_store_dword v205, v111, s[36:37] offset:352
	global_store_dword v205, v115, s[36:37] offset:384
	global_store_dword v205, v119, s[36:37] offset:416
	global_store_dword v205, v123, s[36:37] offset:448
	global_store_dword v205, v127, s[36:37] offset:480
	s_mov_b64 exec, -1
	v_add_u32_e32 v205, 0x12000, v204
	v_mul_f32_e32 v68, v68, v152
	v_mul_f32_e32 v72, v72, v152
	v_mul_f32_e32 v76, v76, v152
	v_mul_f32_e32 v80, v80, v152
	v_mul_f32_e32 v84, v84, v152
	v_mul_f32_e32 v88, v88, v152
	v_mul_f32_e32 v92, v92, v152
	v_mul_f32_e32 v96, v96, v152
	v_mul_f32_e32 v100, v100, v152
	v_mul_f32_e32 v104, v104, v152
	v_mul_f32_e32 v108, v108, v152
	v_mul_f32_e32 v112, v112, v152
	v_mul_f32_e32 v116, v116, v152
	v_mul_f32_e32 v120, v120, v152
	v_mul_f32_e32 v124, v124, v152
	v_mul_f32_e32 v128, v128, v152
	v_mov_b32_dpp v162, v68 quad_perm:[1,0,3,2] row_mask:0xf bank_mask:0xf
	v_mov_b32_dpp v163, v72 quad_perm:[1,0,3,2] row_mask:0xf bank_mask:0xf
	v_mov_b32_dpp v164, v76 quad_perm:[1,0,3,2] row_mask:0xf bank_mask:0xf
	v_mov_b32_dpp v165, v80 quad_perm:[1,0,3,2] row_mask:0xf bank_mask:0xf
	v_mov_b32_dpp v166, v84 quad_perm:[1,0,3,2] row_mask:0xf bank_mask:0xf
	v_mov_b32_dpp v167, v88 quad_perm:[1,0,3,2] row_mask:0xf bank_mask:0xf
	v_mov_b32_dpp v168, v92 quad_perm:[1,0,3,2] row_mask:0xf bank_mask:0xf
	v_mov_b32_dpp v169, v96 quad_perm:[1,0,3,2] row_mask:0xf bank_mask:0xf
	v_mov_b32_dpp v170, v100 quad_perm:[1,0,3,2] row_mask:0xf bank_mask:0xf
	v_mov_b32_dpp v171, v104 quad_perm:[1,0,3,2] row_mask:0xf bank_mask:0xf
	v_mov_b32_dpp v172, v108 quad_perm:[1,0,3,2] row_mask:0xf bank_mask:0xf
	v_mov_b32_dpp v173, v112 quad_perm:[1,0,3,2] row_mask:0xf bank_mask:0xf
	v_mov_b32_dpp v174, v116 quad_perm:[1,0,3,2] row_mask:0xf bank_mask:0xf
	v_mov_b32_dpp v175, v120 quad_perm:[1,0,3,2] row_mask:0xf bank_mask:0xf
	v_mov_b32_dpp v176, v124 quad_perm:[1,0,3,2] row_mask:0xf bank_mask:0xf
	v_mov_b32_dpp v177, v128 quad_perm:[1,0,3,2] row_mask:0xf bank_mask:0xf
	v_cvt_pk_bf16_f32 v68, v68, v162
	v_cvt_pk_bf16_f32 v72, v72, v163
	v_cvt_pk_bf16_f32 v76, v76, v164
	v_cvt_pk_bf16_f32 v80, v80, v165
	v_cvt_pk_bf16_f32 v84, v84, v166
	v_cvt_pk_bf16_f32 v88, v88, v167
	v_cvt_pk_bf16_f32 v92, v92, v168
	v_cvt_pk_bf16_f32 v96, v96, v169
	v_cvt_pk_bf16_f32 v100, v100, v170
	v_cvt_pk_bf16_f32 v104, v104, v171
	v_cvt_pk_bf16_f32 v108, v108, v172
	v_cvt_pk_bf16_f32 v112, v112, v173
	v_cvt_pk_bf16_f32 v116, v116, v174
	v_cvt_pk_bf16_f32 v120, v120, v175
	v_cvt_pk_bf16_f32 v124, v124, v176
	v_cvt_pk_bf16_f32 v128, v128, v177
	s_mov_b64 exec, s[76:77]
	global_store_dword v205, v68, s[36:37] offset:0
	global_store_dword v205, v72, s[36:37] offset:32
	global_store_dword v205, v76, s[36:37] offset:64
	global_store_dword v205, v80, s[36:37] offset:96
	global_store_dword v205, v84, s[36:37] offset:128
	global_store_dword v205, v88, s[36:37] offset:160
	global_store_dword v205, v92, s[36:37] offset:192
	global_store_dword v205, v96, s[36:37] offset:224
	global_store_dword v205, v100, s[36:37] offset:256
	global_store_dword v205, v104, s[36:37] offset:288
	global_store_dword v205, v108, s[36:37] offset:320
	global_store_dword v205, v112, s[36:37] offset:352
	global_store_dword v205, v116, s[36:37] offset:384
	global_store_dword v205, v120, s[36:37] offset:416
	global_store_dword v205, v124, s[36:37] offset:448
	global_store_dword v205, v128, s[36:37] offset:480
	s_mov_b64 exec, -1
	v_add_u32_e32 v205, 0x13000, v204
	v_mul_f32_e32 v69, v69, v153
	v_mul_f32_e32 v73, v73, v153
	v_mul_f32_e32 v77, v77, v153
	v_mul_f32_e32 v81, v81, v153
	v_mul_f32_e32 v85, v85, v153
	v_mul_f32_e32 v89, v89, v153
	v_mul_f32_e32 v93, v93, v153
	v_mul_f32_e32 v97, v97, v153
	v_mul_f32_e32 v101, v101, v153
	v_mul_f32_e32 v105, v105, v153
	v_mul_f32_e32 v109, v109, v153
	v_mul_f32_e32 v113, v113, v153
	v_mul_f32_e32 v117, v117, v153
	v_mul_f32_e32 v121, v121, v153
	v_mul_f32_e32 v125, v125, v153
	v_mul_f32_e32 v129, v129, v153
	v_mov_b32_dpp v162, v69 quad_perm:[1,0,3,2] row_mask:0xf bank_mask:0xf
	v_mov_b32_dpp v163, v73 quad_perm:[1,0,3,2] row_mask:0xf bank_mask:0xf
	v_mov_b32_dpp v164, v77 quad_perm:[1,0,3,2] row_mask:0xf bank_mask:0xf
	v_mov_b32_dpp v165, v81 quad_perm:[1,0,3,2] row_mask:0xf bank_mask:0xf
	v_mov_b32_dpp v166, v85 quad_perm:[1,0,3,2] row_mask:0xf bank_mask:0xf
	v_mov_b32_dpp v167, v89 quad_perm:[1,0,3,2] row_mask:0xf bank_mask:0xf
	v_mov_b32_dpp v168, v93 quad_perm:[1,0,3,2] row_mask:0xf bank_mask:0xf
	v_mov_b32_dpp v169, v97 quad_perm:[1,0,3,2] row_mask:0xf bank_mask:0xf
	v_mov_b32_dpp v170, v101 quad_perm:[1,0,3,2] row_mask:0xf bank_mask:0xf
	v_mov_b32_dpp v171, v105 quad_perm:[1,0,3,2] row_mask:0xf bank_mask:0xf
	v_mov_b32_dpp v172, v109 quad_perm:[1,0,3,2] row_mask:0xf bank_mask:0xf
	v_mov_b32_dpp v173, v113 quad_perm:[1,0,3,2] row_mask:0xf bank_mask:0xf
	v_mov_b32_dpp v174, v117 quad_perm:[1,0,3,2] row_mask:0xf bank_mask:0xf
	v_mov_b32_dpp v175, v121 quad_perm:[1,0,3,2] row_mask:0xf bank_mask:0xf
	v_mov_b32_dpp v176, v125 quad_perm:[1,0,3,2] row_mask:0xf bank_mask:0xf
	v_mov_b32_dpp v177, v129 quad_perm:[1,0,3,2] row_mask:0xf bank_mask:0xf
	v_cvt_pk_bf16_f32 v69, v69, v162
	v_cvt_pk_bf16_f32 v73, v73, v163
	v_cvt_pk_bf16_f32 v77, v77, v164
	v_cvt_pk_bf16_f32 v81, v81, v165
	v_cvt_pk_bf16_f32 v85, v85, v166
	v_cvt_pk_bf16_f32 v89, v89, v167
	v_cvt_pk_bf16_f32 v93, v93, v168
	v_cvt_pk_bf16_f32 v97, v97, v169
	v_cvt_pk_bf16_f32 v101, v101, v170
	v_cvt_pk_bf16_f32 v105, v105, v171
	v_cvt_pk_bf16_f32 v109, v109, v172
	v_cvt_pk_bf16_f32 v113, v113, v173
	v_cvt_pk_bf16_f32 v117, v117, v174
	v_cvt_pk_bf16_f32 v121, v121, v175
	v_cvt_pk_bf16_f32 v125, v125, v176
	v_cvt_pk_bf16_f32 v129, v129, v177
	s_mov_b64 exec, s[76:77]
	global_store_dword v205, v69, s[36:37] offset:0
	global_store_dword v205, v73, s[36:37] offset:32
	global_store_dword v205, v77, s[36:37] offset:64
	global_store_dword v205, v81, s[36:37] offset:96
	global_store_dword v205, v85, s[36:37] offset:128
	global_store_dword v205, v89, s[36:37] offset:160
	global_store_dword v205, v93, s[36:37] offset:192
	global_store_dword v205, v97, s[36:37] offset:224
	global_store_dword v205, v101, s[36:37] offset:256
	global_store_dword v205, v105, s[36:37] offset:288
	global_store_dword v205, v109, s[36:37] offset:320
	global_store_dword v205, v113, s[36:37] offset:352
	global_store_dword v205, v117, s[36:37] offset:384
	global_store_dword v205, v121, s[36:37] offset:416
	global_store_dword v205, v125, s[36:37] offset:448
	global_store_dword v205, v129, s[36:37] offset:480
	s_mov_b64 exec, -1
	s_mov_b64 s[36:37], -1
	s_branch .LBB0_2404
